# wave reductions in P0 row pass, prep, cross-attention softmax and final norm: ds_bpermute butterfly hops replaced by DPP moves / permlane swaps
# speedup vs baseline: 1.0050x; 1.0050x over previous
; #define GAS __attribute__((address_space(1)))
; __device__ __forceinline__ unsigned pk2(float lo, float hi) { f32x2_t v = {lo, hi}; bf16x2_t b = __builtin_convertvector(v, bf16x2_t); return __builtin_bit_cast(unsigned, b); }
; __device__ __forceinline__ float wave_sum(float v) {
; #pragma unroll
;     for (int o = 1; o < 64; o <<= 1) v += __shfl_xor(v, o);
;     return v;
; }
; __device__ __forceinline__ void p0_prologue(const Args& a, LAS unsigned char* lds, int vb, int G, int wave, int lane) {
;     ...
;     for (int m0 = 2 * gw; m0 < NT + MEMR; m0 += 2 * NGW) {
;         f32x4 v[2][4];
; #pragma unroll
;         for (int rr = 0; rr < 2; ++rr) { const int m = m0 + rr; const bool isx = m < NT; const int r = isx ? m : m - NT;
;             const GAS f32x4* xr = (const GAS f32x4*)((isx ? a.x : a.mem) + (size_t)r * DM) + lane;
; #pragma unroll
;             for (int j = 0; j < 4; ++j) v[rr][j] = __builtin_nontemporal_load(&xr[64 * j]); }
; #pragma unroll
;         for (int rr = 0; rr < 2; ++rr) { const int m = m0 + rr; const bool isx = m < NT; const int r = isx ? m : m - NT; float s = 0.f;
; #pragma unroll
;             for (int j = 0; j < 4; ++j) s += (v[rr][j][0] * v[rr][j][0] + v[rr][j][1] * v[rr][j][1]) + (v[rr][j][2] * v[rr][j][2] + v[rr][j][3] * v[rr][j][3]);
;             s = wave_sum(s);
;             GAS u32x2* o8 = (GAS u32x2*)((GAS bf16*)(ws + (isx ? WS_XB : WS_MEMB)) + (size_t)r * DM) + lane;
; #pragma unroll
;             for (int j = 0; j < 4; ++j) { u32x2 w; w.x = pk2(v[rr][j][0], v[rr][j][1]); w.y = pk2(v[rr][j][2], v[rr][j][3]); o8[64 * j] = w; }
;             if (isx) { if (lane < 16) ((GAS float*)(ws + WS_PARTX))[(size_t)r * 16 + lane] = lane == 0 ? s : 0.f; }
;             else if (lane == 0) ((GAS float*)(ws + WS_RSTDMEM))[r] = rsqrtf(s * (1.f / 1024.f) + EPS); }
.LBB0_606:
	s_add_i32 s0, s18, 0xffff8000
	s_cmp_lt_i32 s18, 0x8000
	s_cselect_b32 s14, s18, s0
	s_waitcnt lgkmcnt(0)
	s_cselect_b32 s2, s9, s11
	s_cselect_b32 s3, s8, s10
	s_cselect_b32 s24, s22, 0x1e000000
	s_ashr_i32 s15, s14, 31
	s_lshl_b64 s[0:1], s[14:15], 12
	s_add_u32 s0, s3, s0
	s_addc_u32 s1, s2, s1
	global_load_dwordx4 v[30:33], v18, s[0:1] nt
	global_load_dwordx4 v[34:37], v18, s[0:1] offset:1024 nt
	global_load_dwordx4 v[38:41], v18, s[0:1] offset:2048 nt
	global_load_dwordx4 v[42:45], v18, s[0:1] offset:3072 nt
	s_add_i32 s16, s18, 1
	s_cmpk_gt_i32 s16, 0x7fff
	s_cselect_b64 s[2:3], -1, 0
	s_add_i32 s17, s18, 0xffff8001
	s_cmp_lt_i32 s16, 0x8000
	s_cselect_b64 s[12:13], -1, 0
	s_and_b64 s[0:1], s[12:13], exec
	s_cselect_b32 s0, s16, s17
	s_cselect_b32 s25, s9, s11
	s_cselect_b32 s26, s8, s10
	s_ashr_i32 s1, s0, 31
	s_lshl_b64 s[16:17], s[0:1], 12
	s_add_u32 s16, s26, s16
	s_addc_u32 s17, s25, s17
	global_load_dwordx4 v[14:17], v18, s[16:17] nt
	global_load_dwordx4 v[10:13], v18, s[16:17] offset:1024 nt
	global_load_dwordx4 v[6:9], v18, s[16:17] offset:2048 nt
	global_load_dwordx4 v[2:5], v18, s[16:17] offset:3072 nt
	s_add_u32 s24, s80, s24
	s_addc_u32 s25, s81, 0
	s_lshl_b64 s[16:17], s[14:15], 11
	s_add_u32 s16, s24, s16
	s_addc_u32 s17, s25, s17
	s_cmpk_gt_i32 s18, 0x7fff
	s_waitcnt vmcnt(7)
	v_mul_f32_e32 v29, v31, v31
	v_mul_f32_e32 v46, v33, v33
	s_waitcnt vmcnt(6)
	v_mul_f32_e32 v47, v35, v35
	v_mul_f32_e32 v48, v37, v37
	s_waitcnt vmcnt(5)
	v_mul_f32_e32 v49, v39, v39
	v_mul_f32_e32 v50, v41, v41
	v_fmac_f32_e32 v29, v30, v30
	v_fmac_f32_e32 v46, v32, v32
	v_fmac_f32_e32 v47, v34, v34
	v_fmac_f32_e32 v48, v36, v36
	s_waitcnt vmcnt(4)
	v_mul_f32_e32 v51, v43, v43
	v_mul_f32_e32 v52, v45, v45
	v_fmac_f32_e32 v49, v38, v38
	v_fmac_f32_e32 v50, v40, v40
	v_add_f32_e32 v29, v29, v46
	v_add_f32_e32 v46, v47, v48
	v_fmac_f32_e32 v51, v42, v42
	v_fmac_f32_e32 v52, v44, v44
	v_add_f32_e32 v47, v49, v50
	v_add_f32_e32 v29, v29, v46
	v_add_f32_e32 v48, v51, v52
	v_add_f32_e32 v29, v29, v47
	v_add_f32_e32 v29, v29, v48
	s_nop 0
	v_cvt_pk_bf16_f32 v30, v30, v31
	v_cvt_pk_bf16_f32 v31, v32, v33
	v_cvt_pk_bf16_f32 v32, v34, v35
	v_cvt_pk_bf16_f32 v34, v38, v39
	s_waitcnt lgkmcnt(0)
	s_nop 1
	v_mov_b32_dpp v46, v29 quad_perm:[1,0,3,2] row_mask:0xf bank_mask:0xf
	v_add_f32_e32 v29, v29, v46
	s_nop 0
	v_cvt_pk_bf16_f32 v33, v36, v37
	v_cvt_pk_bf16_f32 v35, v40, v41
	v_cvt_pk_bf16_f32 v36, v42, v43
	v_cvt_pk_bf16_f32 v37, v44, v45
	s_waitcnt lgkmcnt(0)
	s_nop 1
	v_mov_b32_dpp v46, v29 quad_perm:[2,3,0,1] row_mask:0xf bank_mask:0xf
	v_add_f32_e32 v29, v29, v46
	s_nop 0
	global_store_dwordx2 v27, v[30:31], s[16:17]
	global_store_dwordx2 v27, v[32:33], s[16:17] offset:512
	global_store_dwordx2 v27, v[34:35], s[16:17] offset:1024
	global_store_dwordx2 v27, v[36:37], s[16:17] offset:1536
	s_mov_b64 s[16:17], -1
	s_waitcnt lgkmcnt(0)
	s_nop 1
	v_mov_b32_dpp v46, v29 row_half_mirror row_mask:0xf bank_mask:0xf
	v_add_f32_e32 v29, v29, v46
	s_nop 0
	s_waitcnt lgkmcnt(0)
	s_nop 1
	v_mov_b32_dpp v46, v29 row_ror:8 row_mask:0xf bank_mask:0xf
	v_add_f32_e32 v29, v29, v46
	s_nop 0
	s_waitcnt lgkmcnt(0)
	v_mov_b32_e32 v46, v29
	s_nop 1
	v_permlane16_swap_b32_e32 v29, v46
	v_add_f32_e32 v29, v29, v46
	s_nop 0
	s_waitcnt lgkmcnt(0)
	v_mov_b32_e32 v38, v29
	s_nop 1
	v_permlane32_swap_b32_e32 v29, v38
	v_add_f32_e32 v29, v29, v38
	s_cbranch_scc0 .LBB0_610
	s_and_saveexec_b64 s[16:17], s[4:5]
	s_cbranch_execz .LBB0_609
	v_fmamk_f32 v30, v29, 0x3a800000, v28
	v_mul_f32_e32 v31, 0x4b800000, v30
	v_cmp_gt_f32_e32 vcc, s23, v30
	s_lshl_b64 s[24:25], s[14:15], 2
	s_add_u32 s24, s19, s24
	v_cndmask_b32_e32 v30, v30, v31, vcc
	v_rsq_f32_e32 v30, v30
	s_addc_u32 s25, s20, s25
	v_mul_f32_e32 v31, 0x45800000, v30
	v_cndmask_b32_e32 v30, v30, v31, vcc
	global_store_dword v19, v30, s[24:25]

; #define GAS __attribute__((address_space(1)))
; __device__ __forceinline__ unsigned pk2(float lo, float hi) { f32x2_t v = {lo, hi}; bf16x2_t b = __builtin_convertvector(v, bf16x2_t); return __builtin_bit_cast(unsigned, b); }
; __device__ __forceinline__ float wave_sum(float v) {
; #pragma unroll
;     for (int o = 1; o < 64; o <<= 1) v += __shfl_xor(v, o);
;     return v;
; }
; __device__ __forceinline__ void p0_prologue(const Args& a, LAS unsigned char* lds, int vb, int G, int wave, int lane) {
;     ...
; #pragma unroll
;         for (int rr = 0; rr < 2; ++rr) { const int m = m0 + rr; const bool isx = m < NT; const int r = isx ? m : m - NT; float s = 0.f;
; #pragma unroll
;             for (int j = 0; j < 4; ++j) s += (v[rr][j][0] * v[rr][j][0] + v[rr][j][1] * v[rr][j][1]) + (v[rr][j][2] * v[rr][j][2] + v[rr][j][3] * v[rr][j][3]);
;             s = wave_sum(s);
;             GAS u32x2* o8 = (GAS u32x2*)((GAS bf16*)(ws + (isx ? WS_XB : WS_MEMB)) + (size_t)r * DM) + lane;
; #pragma unroll
;             for (int j = 0; j < 4; ++j) { u32x2 w; w.x = pk2(v[rr][j][0], v[rr][j][1]); w.y = pk2(v[rr][j][2], v[rr][j][3]); o8[64 * j] = w; }
;             if (isx) { if (lane < 16) ((GAS float*)(ws + WS_PARTX))[(size_t)r * 16 + lane] = lane == 0 ? s : 0.f; }
;             else if (lane == 0) ((GAS float*)(ws + WS_RSTDMEM))[r] = rsqrtf(s * (1.f / 1024.f) + EPS); }
.LBB0_614:
	s_waitcnt vmcnt(7)
	v_mul_f32_e32 v29, v15, v15
	v_mul_f32_e32 v30, v17, v17
	v_fmac_f32_e32 v29, v14, v14
	v_fmac_f32_e32 v30, v16, v16
	v_add_f32_e32 v29, v29, v30
	s_waitcnt vmcnt(6)
	v_mul_f32_e32 v30, v11, v11
	v_mul_f32_e32 v31, v13, v13
	v_fmac_f32_e32 v30, v10, v10
	v_fmac_f32_e32 v31, v12, v12
	v_add_f32_e32 v30, v30, v31
	v_add_f32_e32 v29, v29, v30
	s_waitcnt vmcnt(5)
	v_mul_f32_e32 v30, v7, v7
	v_mul_f32_e32 v31, v9, v9
	v_fmac_f32_e32 v30, v6, v6
	v_fmac_f32_e32 v31, v8, v8
	v_add_f32_e32 v30, v30, v31
	v_add_f32_e32 v29, v29, v30
	s_waitcnt vmcnt(4)
	v_mul_f32_e32 v30, v3, v3
	v_mul_f32_e32 v31, v5, v5
	v_fmac_f32_e32 v30, v2, v2
	v_fmac_f32_e32 v31, v4, v4
	v_add_f32_e32 v30, v30, v31
	v_add_f32_e32 v29, v29, v30
	s_nop 0
	s_and_b64 s[12:13], s[12:13], exec
	s_cselect_b32 s12, s22, 0x1e000000
	s_add_u32 s14, s80, s12
	s_addc_u32 s15, s81, 0
	s_waitcnt lgkmcnt(0)
	s_nop 1
	v_mov_b32_dpp v30, v29 quad_perm:[1,0,3,2] row_mask:0xf bank_mask:0xf
	v_add_f32_e32 v29, v29, v30
	s_nop 0
	s_lshl_b64 s[12:13], s[0:1], 11
	s_add_u32 s12, s14, s12
	s_addc_u32 s13, s15, s13
	v_cvt_pk_bf16_f32 v2, v2, v3
	s_waitcnt lgkmcnt(0)
	s_nop 1
	v_mov_b32_dpp v30, v29 quad_perm:[2,3,0,1] row_mask:0xf bank_mask:0xf
	v_add_f32_e32 v29, v29, v30
	s_nop 0
	v_cvt_pk_bf16_f32 v3, v4, v5
	v_cvt_pk_bf16_f32 v14, v14, v15
	v_cvt_pk_bf16_f32 v15, v16, v17
	v_cvt_pk_bf16_f32 v10, v10, v11
	s_waitcnt lgkmcnt(0)
	s_nop 1
	v_mov_b32_dpp v30, v29 row_half_mirror row_mask:0xf bank_mask:0xf
	v_add_f32_e32 v29, v29, v30
	s_nop 0
	v_cvt_pk_bf16_f32 v11, v12, v13
	v_cvt_pk_bf16_f32 v6, v6, v7
	v_cvt_pk_bf16_f32 v7, v8, v9
	global_store_dwordx2 v27, v[2:3], s[12:13] offset:1536
	s_waitcnt lgkmcnt(0)
	s_nop 1
	v_mov_b32_dpp v30, v29 row_ror:8 row_mask:0xf bank_mask:0xf
	v_add_f32_e32 v29, v29, v30
	s_nop 0
	s_andn2_b64 vcc, exec, s[2:3]
	s_mov_b64 s[2:3], -1
	global_store_dwordx2 v27, v[14:15], s[12:13]
	global_store_dwordx2 v27, v[10:11], s[12:13] offset:512
	s_waitcnt lgkmcnt(0)
	v_mov_b32_e32 v30, v29
	s_nop 1
	v_permlane16_swap_b32_e32 v29, v30
	v_add_f32_e32 v29, v29, v30
	ds_bpermute_b32 v30, v26, v29
	global_store_dwordx2 v27, v[6:7], s[12:13] offset:1024
	s_waitcnt lgkmcnt(0)
	v_add_f32_e32 v2, v29, v30
	s_cbranch_vccnz .LBB0_618
	s_and_saveexec_b64 s[2:3], s[4:5]
	s_cbranch_execz .LBB0_617
	v_fmamk_f32 v3, v2, 0x3a800000, v28
	v_mul_f32_e32 v4, 0x4b800000, v3
	v_cmp_gt_f32_e32 vcc, s23, v3
	s_lshl_b64 s[12:13], s[0:1], 2
	s_add_u32 s12, s19, s12
	v_cndmask_b32_e32 v3, v3, v4, vcc
	v_rsq_f32_e32 v3, v3
	s_addc_u32 s13, s20, s13
	v_mul_f32_e32 v4, 0x45800000, v3
	v_cndmask_b32_e32 v3, v3, v4, vcc
	global_store_dword v19, v3, s[12:13]

; #define LAS __attribute__((address_space(3)))
; #define GAS __attribute__((address_space(1)))
; __device__ __forceinline__ unsigned pk2(float lo, float hi) { f32x2_t v = {lo, hi}; bf16x2_t b = __builtin_convertvector(v, bf16x2_t); return __builtin_bit_cast(unsigned, b); }
; __device__ __forceinline__ void prep_unit(const Args& a, LAS unsigned char* lds, int b, int kt, int tid) {
;     const GAS bf16* z = (const GAS bf16*)(a.ws + WS_Z);
;     LAS bf16* tT = (LAS bf16*)lds;
;     const int key = tid >> 3, ch = tid & 7; const size_t row = (size_t)b * SEQ + kt * 64 + key;
;     const u32x4 d0 = *(const GAS u32x4*)(z + row * ZW + ZDC + 16 * ch), d1 = *(const GAS u32x4*)(z + row * ZW + ZDC + 16 * ch + 8);
;     const u32x4 k0 = *(const GAS u32x4*)(z + row * ZW + ZIK + 8 * ch);
;     float v[16]; float ss = 0.f;
; #pragma unroll
;     for (int i = 0; i < 4; ++i) { v[2 * i] = bflo(d0[i]); v[2 * i + 1] = bfhi(d0[i]); v[8 + 2 * i] = bflo(d1[i]); v[8 + 2 * i + 1] = bfhi(d1[i]); }
; #pragma unroll
;     for (int i = 0; i < 16; ++i) ss += v[i] * v[i];
;     ss += __shfl_xor(ss, 1); ss += __shfl_xor(ss, 2); ss += __shfl_xor(ss, 4);
;     const float r = rsqrtf(ss * (1.f / 128.f) + EPS);
;     unsigned short o[16];
;     u32x4 w0, w1;
; #pragma unroll
;     for (int i = 0; i < 4; ++i) { w0[i] = pk2(v[2 * i] * r, v[2 * i + 1] * r); w1[i] = pk2(v[8 + 2 * i] * r, v[8 + 2 * i + 1] * r);
;         o[2 * i] = (unsigned short)(w0[i] & 0xffffu); o[2 * i + 1] = (unsigned short)(w0[i] >> 16); o[8 + 2 * i] = (unsigned short)(w1[i] & 0xffffu); o[8 + 2 * i + 1] = (unsigned short)(w1[i] >> 16); }
;     GAS bf16* ckv = (GAS bf16*)(a.ws + WS_CKV);
;     *(GAS u32x4*)(ckv + row * 128 + 16 * ch) = w0; *(GAS u32x4*)(ckv + row * 128 + 16 * ch + 8) = w1;
; #pragma unroll
;     for (int i = 0; i < 16; ++i) tT[(16 * ch + i) * 72 + key] = o[i];
;     float kv[8]; float s2 = 0.f;
; #pragma unroll
;     for (int i = 0; i < 4; ++i) { kv[2 * i] = bflo(k0[i]); kv[2 * i + 1] = bfhi(k0[i]); }
; #pragma unroll
;     for (int i = 0; i < 8; ++i) s2 += kv[i] * kv[i];
;     s2 += __shfl_xor(s2, 1); s2 += __shfl_xor(s2, 2); s2 += __shfl_xor(s2, 4);
;     const float r2 = rsqrtf(s2 * (1.f / 64.f) + EPS);
.LBB0_929:
	s_bfe_u32 s0, s13, 0x40005
	s_and_b32 s6, s8, 0x7c0
	s_lshl_b32 s7, s0, 11
	s_lshl_b32 s0, s0, 19
	s_or_b32 s7, s7, s6
	v_lshl_add_u64 v[24:25], v[6:7], 0, s[0:1]
	s_lshl_b32 s0, s6, 1
	v_add_u32_e32 v23, s7, v15
	v_lshl_add_u64 v[24:25], v[24:25], 0, s[0:1]
	v_mad_u64_u32 v[26:27], s[6:7], v23, s10, v[8:9]
	v_lshl_add_u64 v[36:37], v[24:25], 0, v[16:17]
	v_lshl_add_u64 v[24:25], v[26:27], 0, v[10:11]
	v_add_co_u32_e32 v40, vcc, 0x1000, v24
	v_lshl_add_u64 v[32:33], v[26:27], 0, v[12:13]
	v_lshl_add_u64 v[34:35], v[24:25], 0, s[2:3]
	v_addc_co_u32_e32 v41, vcc, 0, v25, vcc
	v_add_co_u32_e32 v32, vcc, s11, v32
	global_load_dwordx4 v[24:27], v[34:35], off offset:16
	global_load_dwordx4 v[28:31], v[40:41], off offset:2048
	v_addc_co_u32_e32 v33, vcc, 0, v33, vcc
	global_load_dwordx4 v[32:35], v[32:33], off offset:3328
	v_lshlrev_b32_e32 v0, 8, v23
	v_lshl_add_u64 v[38:39], v[2:3], 0, v[0:1]
	v_lshlrev_b32_e32 v0, 7, v23
	v_lshl_add_u64 v[42:43], v[4:5], 0, v[0:1]
	s_add_i32 s13, s13, s84
	s_add_i32 s8, s8, s9
	s_cmpk_gt_i32 s13, 0x1ff
	s_waitcnt vmcnt(0)
	v_lshlrev_b32_e32 v40, 16, v27
	v_and_b32_e32 v53, 0xffff0000, v28
	v_lshlrev_b32_e32 v52, 16, v28
	v_mul_f32_e32 v0, v53, v53
	v_lshlrev_b32_e32 v48, 16, v29
	v_and_b32_e32 v49, 0xffff0000, v29
	v_lshlrev_b32_e32 v64, 16, v35
	v_and_b32_e32 v65, 0xffff0000, v35
	v_lshlrev_b32_e32 v66, 16, v34
	v_and_b32_e32 v67, 0xffff0000, v34
	v_lshlrev_b32_e32 v34, 16, v33
	v_and_b32_e32 v35, 0xffff0000, v33
	v_lshlrev_b32_e32 v68, 16, v32
	v_and_b32_e32 v69, 0xffff0000, v32
	v_pk_fma_f32 v[32:33], v[52:53], v[52:53], v[0:1] op_sel_hi:[1,1,0]
	v_mul_f32_e32 v58, v49, v49
	v_pk_fma_f32 v[32:33], v[48:49], v[48:49], v[32:33]
	v_and_b32_e32 v41, 0xffff0000, v27
	v_lshlrev_b32_e32 v46, 16, v26
	v_and_b32_e32 v47, 0xffff0000, v26
	v_lshlrev_b32_e32 v26, 16, v30
	v_and_b32_e32 v27, 0xffff0000, v30
	v_pk_add_f32 v[32:33], v[58:59], v[32:33] op_sel_hi:[0,1]
	v_mul_f32_e32 v60, v27, v27
	v_pk_fma_f32 v[32:33], v[26:27], v[26:27], v[32:33]
	v_lshlrev_b32_e32 v44, 16, v31
	v_and_b32_e32 v45, 0xffff0000, v31
	v_pk_add_f32 v[32:33], v[60:61], v[32:33] op_sel_hi:[0,1]
	v_lshlrev_b32_e32 v30, 16, v25
	v_and_b32_e32 v31, 0xffff0000, v25
	v_and_b32_e32 v25, 0xffff0000, v24
	v_mul_f32_e32 v62, v45, v45
	v_pk_fma_f32 v[32:33], v[44:45], v[44:45], v[32:33]
	v_lshlrev_b32_e32 v50, 16, v24
	v_and_b32_e32 v24, s0, v24
	v_mov_b32_e32 v51, v25
	v_pk_add_f32 v[32:33], v[62:63], v[32:33] op_sel_hi:[0,1]
	v_pk_mul_f32 v[24:25], v[24:25], v[24:25]
	v_pk_mul_f32 v[76:77], v[68:69], v[68:69]
	v_pk_fma_f32 v[32:33], v[50:51], v[50:51], v[32:33]
	v_pk_mul_f32 v[56:57], v[30:31], v[30:31]
	v_pk_mul_f32 v[74:75], v[34:35], v[34:35]
	v_mov_b32_e32 v24, v76
	v_pk_mov_b32 v[32:33], v[76:77], v[32:33] op_sel:[1,0]
	v_mov_b32_e32 v79, v56
	v_mov_b32_e32 v78, v74
	v_pk_add_f32 v[24:25], v[24:25], v[32:33]
	v_pk_mul_f32 v[54:55], v[46:47], v[46:47]
	v_pk_mul_f32 v[72:73], v[66:67], v[66:67]
	v_mov_b32_e32 v56, v75
	v_pk_add_f32 v[24:25], v[78:79], v[24:25]
	v_mov_b32_e32 v81, v54
	v_mov_b32_e32 v80, v72
	v_pk_add_f32 v[24:25], v[56:57], v[24:25]
	v_pk_mul_f32 v[28:29], v[40:41], v[40:41]
	v_pk_mul_f32 v[70:71], v[64:65], v[64:65]
	v_mov_b32_e32 v54, v73
	v_pk_add_f32 v[24:25], v[80:81], v[24:25]
	v_mov_b32_e32 v83, v28
	v_mov_b32_e32 v82, v70
	v_pk_add_f32 v[24:25], v[54:55], v[24:25]
	v_mov_b32_e32 v28, v71
	v_pk_add_f32 v[24:25], v[82:83], v[24:25]
	s_nop 0
	v_pk_add_f32 v[24:25], v[28:29], v[24:25]
	s_nop 0
	s_nop 0
	s_waitcnt lgkmcnt(0)
	s_nop 1
	v_mov_b32_dpp v29, v25 quad_perm:[1,0,3,2] row_mask:0xf bank_mask:0xf
	v_mov_b32_dpp v28, v24 quad_perm:[1,0,3,2] row_mask:0xf bank_mask:0xf
	v_pk_add_f32 v[24:25], v[24:25], v[28:29]
	s_nop 0
	s_nop 0
	s_waitcnt lgkmcnt(0)
	s_nop 1
	v_mov_b32_dpp v29, v25 quad_perm:[2,3,0,1] row_mask:0xf bank_mask:0xf
	v_mov_b32_dpp v28, v24 quad_perm:[2,3,0,1] row_mask:0xf bank_mask:0xf
	v_pk_add_f32 v[24:25], v[24:25], v[28:29]
	s_nop 0
	s_nop 0
	s_waitcnt lgkmcnt(0)
	s_nop 1
	v_mov_b32_dpp v29, v25 row_half_mirror row_mask:0xf bank_mask:0xf
	v_mov_b32_dpp v28, v24 row_half_mirror row_mask:0xf bank_mask:0xf
	v_pk_add_f32 v[24:25], v[24:25], v[28:29]
	s_nop 0
	v_pk_fma_f32 v[24:25], v[24:25], s[4:5], v[14:15] op_sel_hi:[1,1,0]
	s_nop 0
	v_mul_f32_e32 v0, 0x4b800000, v25
	v_mul_f32_e32 v23, 0x4b800000, v24
	v_cmp_gt_f32_e32 vcc, s12, v24
	v_cmp_gt_f32_e64 s[6:7], s12, v25
	s_nop 0
	v_cndmask_b32_e32 v23, v24, v23, vcc
	v_cndmask_b32_e64 v0, v25, v0, s[6:7]
	v_rsq_f32_e32 v0, v0
	v_rsq_f32_e32 v23, v23
	v_mul_f32_e32 v24, 0x45800000, v0
	v_mul_f32_e32 v25, 0x45800000, v23
	v_cndmask_b32_e64 v0, v0, v24, s[6:7]
	v_cndmask_b32_e32 v24, v23, v25, vcc
	v_pk_mul_f32 v[28:29], v[0:1], v[52:53] op_sel_hi:[0,1]
	v_pk_mul_f32 v[32:33], v[0:1], v[50:51] op_sel_hi:[0,1]
	v_pk_mul_f32 v[48:49], v[0:1], v[48:49] op_sel_hi:[0,1]
	v_pk_mul_f32 v[30:31], v[0:1], v[30:31] op_sel_hi:[0,1]
	v_pk_mul_f32 v[26:27], v[0:1], v[26:27] op_sel_hi:[0,1]
	v_pk_mul_f32 v[46:47], v[0:1], v[46:47] op_sel_hi:[0,1]
	v_pk_mul_f32 v[44:45], v[0:1], v[44:45] op_sel_hi:[0,1]
	v_pk_mul_f32 v[40:41], v[0:1], v[40:41] op_sel_hi:[0,1]
	v_pk_mul_f32 v[50:51], v[24:25], v[68:69] op_sel_hi:[0,1]
	v_pk_mul_f32 v[34:35], v[24:25], v[34:35] op_sel_hi:[0,1]
	v_pk_mul_f32 v[52:53], v[24:25], v[66:67] op_sel_hi:[0,1]
	v_pk_mul_f32 v[54:55], v[24:25], v[64:65] op_sel_hi:[0,1]
	v_cvt_pk_bf16_f32 v24, v28, v29
	v_cvt_pk_bf16_f32 v28, v32, v33
	v_cvt_pk_bf16_f32 v25, v48, v49
	v_cvt_pk_bf16_f32 v29, v30, v31
	v_cvt_pk_bf16_f32 v26, v26, v27
	v_cvt_pk_bf16_f32 v30, v46, v47
	v_cvt_pk_bf16_f32 v27, v44, v45
	v_cvt_pk_bf16_f32 v31, v40, v41
	v_cvt_pk_bf16_f32 v32, v50, v51
	v_cvt_pk_bf16_f32 v33, v34, v35
	v_cvt_pk_bf16_f32 v34, v52, v53
	v_cvt_pk_bf16_f32 v35, v54, v55
	global_store_dwordx4 v[38:39], v[24:27], off
	global_store_dwordx4 v[38:39], v[28:31], off offset:16
	ds_write_b16 v22, v24
	ds_write_b16_d16_hi v22, v24 offset:144
	ds_write_b16 v22, v25 offset:288
	ds_write_b16_d16_hi v22, v25 offset:432
	ds_write_b16 v22, v26 offset:576
	ds_write_b16_d16_hi v22, v26 offset:720
	ds_write_b16 v22, v27 offset:864
	ds_write_b16_d16_hi v22, v27 offset:1008
	ds_write_b16 v22, v28 offset:1152
	ds_write_b16_d16_hi v22, v28 offset:1296
	ds_write_b16 v22, v29 offset:1440
	ds_write_b16_d16_hi v22, v29 offset:1584
	ds_write_b16 v22, v30 offset:1728
	ds_write_b16_d16_hi v22, v30 offset:1872
	ds_write_b16 v22, v31 offset:2016
	ds_write_b16_d16_hi v22, v31 offset:2160
	global_store_dwordx4 v[42:43], v[32:35], off
	s_waitcnt lgkmcnt(0)
	s_barrier
	ds_read_b128 v[24:27], v21
	ds_read_b128 v[28:31], v21 offset:16
	s_waitcnt lgkmcnt(1)
	global_store_dwordx4 v[36:37], v[24:27], off
	s_waitcnt lgkmcnt(0)
	global_store_dwordx4 v[36:37], v[28:31], off offset:16
	s_barrier
	s_cbranch_scc0 .LBB0_929

; __device__ __forceinline__ void xattn_unit(const Args& a, LAS unsigned char* lds, int b, int h, int qb, int tid, int wave, int lane) {
;     constexpr int KS = 264, VS = 72, STG = 36864;
;     const GAS bf16* QX = (const GAS bf16*)(a.ws + WS_QX); const GAS bf16* KX = (const GAS bf16*)(a.ws + WS_KX); const GAS bf16* VTX = (const GAS bf16*)(a.ws + WS_VTX); GAS bf16* XO = (GAS bf16*)(a.ws + WS_XO);
;     const int fr = lane & 15, fq = lane >> 4; const size_t qrow = (size_t)b * SEQ + qb * 128 + 16 * wave + fr;
;     bf16x8 qf[8];
; #pragma unroll
;     for (int kk = 0; kk < 8; ++kk) qf[kk] = *(const GAS bf16x8*)(QX + qrow * DM + h * 256 + 32 * kk + 8 * fq);
;     u32x4 rr[2][4];
;     const unsigned vok = (unsigned)((tid >> 5) * DM + 8 * (tid & 31)) * 2u, vov = (unsigned)((tid >> 3) * MEMR + 8 * (tid & 7)) * 2u;
;     const GAS char* kxb = (const GAS char*)KX + ((size_t)b * 256 * DM + h * 256) * 2; const GAS char* vxb = (const GAS char*)VTX + ((size_t)h * 256 * MEMR + b * 256) * 2;
;     auto gload = [&](int j) {
;         if (j < 4) { const GAS char* p_ = kxb + (size_t)j * (64 * DM * 2);
; #pragma unroll
;             for (int i = 0; i < 4; ++i) rr[j & 1][i] = *(const GAS u32x4*)(p_ + (size_t)(vok + (unsigned)(i * 16 * DM * 2)));
;         } else { const GAS char* p_ = vxb + (size_t)(j - 4) * 128;
; #pragma unroll
;             for (int i = 0; i < 4; ++i) rr[j & 1][i] = *(const GAS u32x4*)(p_ + (size_t)(vov + (unsigned)(i * 64 * MEMR * 2)));
;         }
;     };
;     auto lstore = [&](int j) {
;         LAS bf16* base = (LAS bf16*)(lds + (j & 1) * STG);
;         if (j < 4) {
; #pragma unroll
;             for (int i = 0; i < 4; ++i) { const int id = tid + 512 * i; *(LAS u32x4*)(base + (id >> 5) * KS + 8 * (id & 31)) = rr[j & 1][i]; }
;         } else {
; #pragma unroll
;             for (int i = 0; i < 4; ++i) { const int id = tid + 512 * i; *(LAS u32x4*)(base + (id >> 3) * VS + 8 * (id & 7)) = rr[j & 1][i]; }
;         }
;     };
;     f32x4 S[16]; bf16x8 pf[8]; f32x4 O[16]; float l = 0.f;
; #pragma unroll
;     for (int i = 0; i < 16; ++i) { S[i] = (f32x4){0.f, 0.f, 0.f, 0.f}; O[i] = (f32x4){0.f, 0.f, 0.f, 0.f}; }
;     gload(0); gload(1); lstore(0); __syncthreads();
; #pragma unroll
;     for (int j = 0; j < 8; ++j) {
;         if (j < 6) gload(j + 2);
;         const LAS bf16* base = (const LAS bf16*)(lds + (j & 1) * STG);
;         if (j < 4) {
.LBB0_1513:
	s_bfe_u32 s6, s21, 0x40006
	s_and_b32 s4, s14, 0x780
	v_mov_b32_e32 v216, v252
	s_bfe_u32 s7, s21, 0x20004
	s_lshl_b32 s8, s6, 11
	s_add_i32 s9, s4, s70
	s_lshl_b32 s4, s7, 9
	s_lshl_b32 s22, s6, 19
	v_and_b32_e32 v213, 15, v216
	s_add_i32 s8, s8, s9
	v_or_b32_e32 v200, s8, v213
	s_add_u32 s8, s10, s22
	s_addc_u32 s9, s11, 0
	s_lshl_b32 s7, s7, 21
	s_lshl_b32 s6, s6, 9
	s_or_b32 s6, s7, s6
	s_add_u32 s8, s8, s4
	v_lshlrev_b32_e32 v192, 4, v216
	v_ashrrev_i32_e32 v3, 5, v216
	s_addc_u32 s9, s9, 0
	v_lshlrev_b32_e32 v2, 6, v216
	v_and_b32_e32 v4, 0x1f0, v192
	v_mul_lo_u32 v3, v3, s18
	v_lshlrev_b64 v[202:203], 11, v[200:201]
	s_add_u32 s6, s12, s6
	v_add_u32_e32 v217, 0x200, v216
	v_add_u32_e32 v218, 0x400, v216
	v_add_u32_e32 v219, 0x600, v216
	v_and_or_b32 v193, v2, s16, v4
	v_add3_u32 v200, 0, v3, v4
	v_lshl_add_u64 v[2:3], s[0:1], 0, v[202:203]
	s_addc_u32 s7, s13, 0
	v_mov_b32_e32 v1, v201
	v_and_b32_e32 v215, 63, v216
	v_and_b32_e32 v0, 48, v216
	v_ashrrev_i32_e32 v5, 5, v217
	v_ashrrev_i32_e32 v6, 5, v218
	v_ashrrev_i32_e32 v7, 5, v219
	v_lshl_add_u64 v[2:3], v[2:3], 0, s[4:5]
	s_add_u32 s22, s8, 0x20000
	v_add_u32_e32 v8, 0, v0
	v_or_b32_e32 v214, 48, v215
	v_mul_lo_u32 v5, v5, s18
	v_mul_lo_u32 v6, v6, s18
	v_mul_lo_u32 v7, v7, s18
	v_lshl_add_u64 v[32:33], v[2:3], 0, v[0:1]
	s_addc_u32 s23, s9, 0
	v_mad_u32_u24 v210, v213, s18, v8
	v_mad_u32_u24 v209, v214, s18, v8
	v_add_u32_e32 v194, 0x8000, v193
	v_add_u32_e32 v195, 0x10000, v193
	v_add_u32_e32 v196, 0x18000, v193
	v_add3_u32 v211, 0, v5, v4
	v_add3_u32 v212, 0, v6, v4
	v_add3_u32 v221, 0, v7, v4
	global_load_dwordx4 v[12:15], v193, s[8:9]
	global_load_dwordx4 v[16:19], v194, s[8:9]
	global_load_dwordx4 v[20:23], v195, s[8:9]
	global_load_dwordx4 v[24:27], v196, s[8:9]
	global_load_dwordx4 v[140:143], v[32:33], off
	global_load_dwordx4 v[156:159], v[32:33], off offset:64
	global_load_dwordx4 v[68:71], v[32:33], off offset:128
	global_load_dwordx4 v[64:67], v[32:33], off offset:192
	global_load_dwordx4 v[28:31], v[32:33], off offset:256
	global_load_dwordx4 v[8:11], v[32:33], off offset:320
	global_load_dwordx4 v[4:7], v[32:33], off offset:384
	global_load_dwordx4 v[0:3], v[32:33], off offset:448
	s_nop 0
	global_load_dwordx4 v[32:35], v193, s[22:23]
	global_load_dwordx4 v[36:39], v194, s[22:23]
	global_load_dwordx4 v[40:43], v195, s[22:23]
	global_load_dwordx4 v[44:47], v196, s[22:23]
	s_add_u32 s22, s8, 0x40000
	s_addc_u32 s23, s9, 0
	s_add_u32 s8, s8, 0x60000
	s_addc_u32 s9, s9, 0
	v_and_b32_e32 v220, 0x70, v192
	v_cmp_lt_i32_e32 vcc, v227, v226
	v_lshrrev_b32_e32 v217, 3, v217
	v_lshrrev_b32_e32 v218, 3, v218
	s_add_i32 s21, s21, s76
	s_add_i32 s14, s14, s15
	s_cmpk_lt_i32 s21, 0x400
	s_waitcnt vmcnt(0)
	ds_write_b128 v200, v[12:15]
	ds_write_b128 v211, v[16:19]
	ds_write_b128 v212, v[20:23]
	ds_write_b128 v221, v[24:27]
	s_waitcnt lgkmcnt(0)
	s_barrier
	global_load_dwordx4 v[12:15], v193, s[22:23]
	global_load_dwordx4 v[16:19], v194, s[22:23]
	global_load_dwordx4 v[20:23], v195, s[22:23]
	global_load_dwordx4 v[24:27], v196, s[22:23]
	ds_read_b128 v[48:51], v210
	ds_read_b128 v[52:55], v210 offset:64
	ds_read_b128 v[56:59], v210 offset:128
	ds_read_b128 v[60:63], v210 offset:192
	ds_read_b128 v[72:75], v210 offset:256
	ds_read_b128 v[76:79], v210 offset:320
	ds_read_b128 v[80:83], v210 offset:384
	ds_read_b128 v[84:87], v210 offset:448
	ds_read_b128 v[88:91], v210 offset:8448
	ds_read_b128 v[92:95], v210 offset:8512
	ds_read_b128 v[96:99], v210 offset:8576
	ds_read_b128 v[100:103], v210 offset:8640
	ds_read_b128 v[104:107], v210 offset:8704
	ds_read_b128 v[108:111], v210 offset:8768
	ds_read_b128 v[112:115], v210 offset:8832
	ds_read_b128 v[116:119], v210 offset:8896
	ds_read_b128 v[120:123], v210 offset:16896
	ds_read_b128 v[124:127], v210 offset:16960
	s_waitcnt lgkmcnt(14)
	v_mfma_f32_16x16x32_bf16 v[48:51], v[48:51], v[140:143], 0
	ds_read_b128 v[128:131], v210 offset:17024
	ds_read_b128 v[132:135], v210 offset:17088
	ds_read_b128 v[136:139], v209
	ds_read_b128 v[144:147], v210 offset:17152
	ds_read_b128 v[148:151], v210 offset:17216
	ds_read_b128 v[152:155], v210 offset:17280
	ds_read_b128 v[160:163], v210 offset:17344
	ds_read_b128 v[164:167], v209 offset:64
	ds_read_b128 v[168:171], v209 offset:128
	s_waitcnt lgkmcnt(14)
	v_mfma_f32_16x16x32_bf16 v[88:91], v[88:91], v[140:143], 0
	ds_read_b128 v[172:175], v209 offset:192
	ds_read_b128 v[176:179], v209 offset:256
	ds_read_b128 v[180:183], v209 offset:320
	s_waitcnt lgkmcnt(13)
	v_mfma_f32_16x16x32_bf16 v[120:123], v[120:123], v[140:143], 0
	v_mfma_f32_16x16x32_bf16 v[48:51], v[52:55], v[156:159], v[48:51]
	ds_read_b128 v[52:55], v209 offset:384
	ds_read_b128 v[184:187], v209 offset:448
	ds_write_b128 v200, v[32:35] offset:36864
	ds_write_b128 v211, v[36:39] offset:36864
	ds_write_b128 v212, v[40:43] offset:36864
	ds_write_b128 v221, v[44:47] offset:36864
	v_mfma_f32_16x16x32_bf16 v[32:35], v[92:95], v[156:159], v[88:91]
	s_waitcnt lgkmcnt(0)
	s_barrier
; #define LAS __attribute__((address_space(3)))
; #define GAS __attribute__((address_space(1)))
; __device__ __forceinline__ f32x4 mfma16(bf16x8 a, bf16x8 b, f32x4 c) { return __builtin_amdgcn_mfma_f32_16x16x32_bf16(a, b, c, 0, 0, 0); }
; __device__ __forceinline__ void xattn_unit(const Args& a, LAS unsigned char* lds, int b, int h, int qb, int tid, int wave, int lane) {
;     ...
;     auto gload = [&](int j) {
;         if (j < 4) { const GAS char* p_ = kxb + (size_t)j * (64 * DM * 2);
; #pragma unroll
;             for (int i = 0; i < 4; ++i) rr[j & 1][i] = *(const GAS u32x4*)(p_ + (size_t)(vok + (unsigned)(i * 16 * DM * 2)));
;         } else { const GAS char* p_ = vxb + (size_t)(j - 4) * 128;
; #pragma unroll
;             for (int i = 0; i < 4; ++i) rr[j & 1][i] = *(const GAS u32x4*)(p_ + (size_t)(vov + (unsigned)(i * 64 * MEMR * 2)));
;         }
;     };
;     auto lstore = [&](int j) {
;         LAS bf16* base = (LAS bf16*)(lds + (j & 1) * STG);
;         if (j < 4) {
; #pragma unroll
;             for (int i = 0; i < 4; ++i) { const int id = tid + 512 * i; *(LAS u32x4*)(base + (id >> 5) * KS + 8 * (id & 31)) = rr[j & 1][i]; }
;         } else {
; #pragma unroll
;             for (int i = 0; i < 4; ++i) { const int id = tid + 512 * i; *(LAS u32x4*)(base + (id >> 3) * VS + 8 * (id & 7)) = rr[j & 1][i]; }
;         }
;     };
;     f32x4 S[16]; bf16x8 pf[8]; f32x4 O[16]; float l = 0.f;
; #pragma unroll
;     for (int i = 0; i < 16; ++i) { S[i] = (f32x4){0.f, 0.f, 0.f, 0.f}; O[i] = (f32x4){0.f, 0.f, 0.f, 0.f}; }
;     gload(0); gload(1); lstore(0); __syncthreads();
; #pragma unroll
;     for (int j = 0; j < 8; ++j) {
;         if (j < 6) gload(j + 2);
;         const LAS bf16* base = (const LAS bf16*)(lds + (j & 1) * STG);
;         if (j < 4) {
; #pragma unroll
;             for (int rt = 0; rt < 4; ++rt)
; #pragma unroll
;                 for (int kk = 0; kk < 8; ++kk) S[4 * j + rt] = mfma16(*(const LAS bf16x8*)(base + (16 * rt + fr) * KS + 32 * kk + 8 * fq), qf[kk], S[4 * j + rt]);
	ds_read_b128 v[44:47], v210 offset:36864
	ds_read_b128 v[88:91], v210 offset:36928
	v_mfma_f32_16x16x32_bf16 v[136:139], v[136:139], v[140:143], 0
	v_mfma_f32_16x16x32_bf16 v[36:39], v[124:127], v[156:159], v[120:123]
	ds_read_b128 v[92:95], v210 offset:45312
	s_nop 1
	ds_read_b128 v[120:123], v210 offset:45376
	s_waitcnt lgkmcnt(3)
	v_mfma_f32_16x16x32_bf16 v[44:47], v[44:47], v[140:143], 0
	v_mfma_f32_16x16x32_bf16 v[48:51], v[56:59], v[68:71], v[48:51]
	v_mfma_f32_16x16x32_bf16 v[40:43], v[164:167], v[156:159], v[136:139]
	ds_read_b128 v[124:127], v210 offset:53760
	s_nop 1
	ds_read_b128 v[136:139], v210 offset:53824
	ds_read_b128 v[164:167], v209 offset:36864
	ds_read_b128 v[188:191], v209 offset:36928
	s_waitcnt lgkmcnt(5)
	v_mfma_f32_16x16x32_bf16 v[92:95], v[92:95], v[140:143], 0
	v_mfma_f32_16x16x32_bf16 v[32:35], v[96:99], v[68:71], v[32:35]
	v_mfma_f32_16x16x32_bf16 v[44:47], v[88:91], v[156:159], v[44:47]
	v_mfma_f32_16x16x32_bf16 v[48:51], v[60:63], v[64:67], v[48:51]
	ds_read_b128 v[60:63], v210 offset:36992
	ds_read_b128 v[96:99], v210 offset:37056
	s_waitcnt lgkmcnt(5)
	v_mfma_f32_16x16x32_bf16 v[124:127], v[124:127], v[140:143], 0
	v_mfma_f32_16x16x32_bf16 v[56:59], v[120:123], v[156:159], v[92:95]
	v_mfma_f32_16x16x32_bf16 v[32:35], v[100:103], v[64:67], v[32:35]
	s_waitcnt lgkmcnt(1)
	v_mfma_f32_16x16x32_bf16 v[44:47], v[60:63], v[68:71], v[44:47]
	ds_read_b128 v[60:63], v210 offset:45440
	ds_read_b128 v[100:103], v210 offset:45504
	v_mfma_f32_16x16x32_bf16 v[164:167], v[164:167], v[140:143], 0
	v_mfma_f32_16x16x32_bf16 v[88:91], v[136:139], v[156:159], v[124:127]
	s_waitcnt lgkmcnt(1)
	v_mfma_f32_16x16x32_bf16 v[56:59], v[60:63], v[68:71], v[56:59]
	ds_read_b128 v[60:63], v210 offset:53888
	ds_read_b128 v[120:123], v210 offset:53952
	v_mfma_f32_16x16x32_bf16 v[92:95], v[188:191], v[156:159], v[164:167]
	s_waitcnt lgkmcnt(1)
	v_mfma_f32_16x16x32_bf16 v[60:63], v[60:63], v[68:71], v[88:91]
	s_nop 2
	ds_read_b128 v[88:91], v209 offset:36992
	ds_read_b128 v[124:127], v209 offset:37056
	v_mfma_f32_16x16x32_bf16 v[40:43], v[168:171], v[68:71], v[40:43]
	s_waitcnt lgkmcnt(1)
	v_mfma_f32_16x16x32_bf16 v[88:91], v[88:91], v[68:71], v[92:95]
	v_mfma_f32_16x16x32_bf16 v[48:51], v[72:75], v[28:31], v[48:51]
	v_mfma_f32_16x16x32_bf16 v[40:43], v[172:175], v[64:67], v[40:43]
	v_mfma_f32_16x16x32_bf16 v[44:47], v[96:99], v[64:67], v[44:47]
	s_waitcnt lgkmcnt(0)
	v_mfma_f32_16x16x32_bf16 v[72:75], v[124:127], v[64:67], v[88:91]
	v_mfma_f32_16x16x32_bf16 v[48:51], v[76:79], v[8:11], v[48:51]
	ds_read_b128 v[76:79], v210 offset:37120
	s_nop 0
	ds_read_b128 v[88:91], v210 offset:37184
	v_mfma_f32_16x16x32_bf16 v[32:35], v[104:107], v[28:31], v[32:35]
	v_mfma_f32_16x16x32_bf16 v[40:43], v[176:179], v[28:31], v[40:43]
	v_mfma_f32_16x16x32_bf16 v[56:59], v[100:103], v[64:67], v[56:59]
	s_waitcnt lgkmcnt(1)
	v_mfma_f32_16x16x32_bf16 v[44:47], v[76:79], v[28:31], v[44:47]
	ds_read_b128 v[76:79], v210 offset:45568
	ds_read_b128 v[92:95], v210 offset:45632
	v_mfma_f32_16x16x32_bf16 v[60:63], v[120:123], v[64:67], v[60:63]
	v_mfma_f32_16x16x32_bf16 v[32:35], v[108:111], v[8:11], v[32:35]
	v_mfma_f32_16x16x32_bf16 v[40:43], v[180:183], v[8:11], v[40:43]
	s_waitcnt lgkmcnt(1)
	v_mfma_f32_16x16x32_bf16 v[56:59], v[76:79], v[28:31], v[56:59]
	ds_read_b128 v[76:79], v210 offset:54016
	ds_read_b128 v[96:99], v210 offset:54080
	v_mfma_f32_16x16x32_bf16 v[36:39], v[128:131], v[68:71], v[36:39]
	s_waitcnt lgkmcnt(1)
	v_mfma_f32_16x16x32_bf16 v[60:63], v[76:79], v[28:31], v[60:63]
	ds_read_b128 v[76:79], v209 offset:37120
	ds_read_b128 v[100:103], v209 offset:37184
	v_mfma_f32_16x16x32_bf16 v[48:51], v[80:83], v[4:7], v[48:51]
	v_mfma_f32_16x16x32_bf16 v[32:35], v[112:115], v[4:7], v[32:35]
	v_mfma_f32_16x16x32_bf16 v[52:55], v[52:55], v[4:7], v[40:43]
	v_mfma_f32_16x16x32_bf16 v[36:39], v[132:135], v[64:67], v[36:39]
	s_waitcnt lgkmcnt(1)
	v_mfma_f32_16x16x32_bf16 v[72:75], v[76:79], v[28:31], v[72:75]
	v_mfma_f32_16x16x32_bf16 v[76:79], v[88:91], v[8:11], v[44:47]
	v_mfma_f32_16x16x32_bf16 v[44:47], v[84:87], v[0:3], v[48:51]
	v_mfma_f32_16x16x32_bf16 v[40:43], v[116:119], v[0:3], v[32:35]
	v_mfma_f32_16x16x32_bf16 v[32:35], v[184:187], v[0:3], v[52:55]
	s_nop 0
	ds_read_b128 v[48:51], v210 offset:37248
	s_nop 0
	ds_read_b128 v[52:55], v210 offset:37312
	v_mfma_f32_16x16x32_bf16 v[36:39], v[144:147], v[28:31], v[36:39]
	v_mfma_f32_16x16x32_bf16 v[56:59], v[92:95], v[8:11], v[56:59]
	v_lshlrev_b32_e32 v92, 10, v216
	v_and_or_b32 v205, v92, s17, v220
	v_add_u32_e32 v206, 0x80000, v205
	s_waitcnt lgkmcnt(1)
	v_mfma_f32_16x16x32_bf16 v[48:51], v[48:51], v[4:7], v[76:79]
	s_nop 2
	ds_read_b128 v[76:79], v210 offset:45696
	ds_read_b128 v[80:83], v210 offset:45760
	v_add_u32_e32 v207, 0x100000, v205
	v_add_u32_e32 v208, 0x180000, v205
	v_mfma_f32_16x16x32_bf16 v[36:39], v[148:151], v[8:11], v[36:39]
	v_mfma_f32_16x16x32_bf16 v[60:63], v[96:99], v[8:11], v[60:63]
	s_waitcnt lgkmcnt(1)
	v_mfma_f32_16x16x32_bf16 v[56:59], v[76:79], v[4:7], v[56:59]
	ds_read_b128 v[76:79], v210 offset:54144
	ds_read_b128 v[84:87], v210 offset:54208
	v_mfma_f32_16x16x32_bf16 v[36:39], v[152:155], v[4:7], v[36:39]
	s_waitcnt lgkmcnt(1)
	v_mfma_f32_16x16x32_bf16 v[60:63], v[76:79], v[4:7], v[60:63]
	ds_read_b128 v[76:79], v209 offset:37248
	ds_read_b128 v[88:91], v209 offset:37312
	global_load_dwordx4 v[144:147], v193, s[8:9]
	global_load_dwordx4 v[148:151], v194, s[8:9]
	global_load_dwordx4 v[152:155], v195, s[8:9]
	global_load_dwordx4 v[172:175], v196, s[8:9]
	v_mfma_f32_16x16x32_bf16 v[72:75], v[100:103], v[8:11], v[72:75]
	s_waitcnt vmcnt(7)
	ds_write_b128 v200, v[12:15]
	s_waitcnt vmcnt(6)
	ds_write_b128 v211, v[16:19]
	s_waitcnt vmcnt(5)
	ds_write_b128 v212, v[20:23]
	s_waitcnt vmcnt(4)
	ds_write_b128 v221, v[24:27]
	s_waitcnt lgkmcnt(0)
	s_barrier
; #define LAS __attribute__((address_space(3)))
; #define GAS __attribute__((address_space(1)))
; __device__ __forceinline__ f32x4 mfma16(bf16x8 a, bf16x8 b, f32x4 c) { return __builtin_amdgcn_mfma_f32_16x16x32_bf16(a, b, c, 0, 0, 0); }
; __device__ __forceinline__ void xattn_unit(const Args& a, LAS unsigned char* lds, int b, int h, int qb, int tid, int wave, int lane) {
;     ...
;     auto gload = [&](int j) {
;         if (j < 4) { const GAS char* p_ = kxb + (size_t)j * (64 * DM * 2);
; #pragma unroll
;             for (int i = 0; i < 4; ++i) rr[j & 1][i] = *(const GAS u32x4*)(p_ + (size_t)(vok + (unsigned)(i * 16 * DM * 2)));
;         } else { const GAS char* p_ = vxb + (size_t)(j - 4) * 128;
; #pragma unroll
;             for (int i = 0; i < 4; ++i) rr[j & 1][i] = *(const GAS u32x4*)(p_ + (size_t)(vov + (unsigned)(i * 64 * MEMR * 2)));
;         }
;     };
;     auto lstore = [&](int j) {
;         LAS bf16* base = (LAS bf16*)(lds + (j & 1) * STG);
;         if (j < 4) {
; #pragma unroll
;             for (int i = 0; i < 4; ++i) { const int id = tid + 512 * i; *(LAS u32x4*)(base + (id >> 5) * KS + 8 * (id & 31)) = rr[j & 1][i]; }
;         } else {
; #pragma unroll
;             for (int i = 0; i < 4; ++i) { const int id = tid + 512 * i; *(LAS u32x4*)(base + (id >> 3) * VS + 8 * (id & 7)) = rr[j & 1][i]; }
;         }
;     };
;     f32x4 S[16]; bf16x8 pf[8]; f32x4 O[16]; float l = 0.f;
; #pragma unroll
;     for (int i = 0; i < 16; ++i) { S[i] = (f32x4){0.f, 0.f, 0.f, 0.f}; O[i] = (f32x4){0.f, 0.f, 0.f, 0.f}; }
;     gload(0); gload(1); lstore(0); __syncthreads();
; #pragma unroll
;     for (int j = 0; j < 8; ++j) {
;         if (j < 6) gload(j + 2);
;         const LAS bf16* base = (const LAS bf16*)(lds + (j & 1) * STG);
;         if (j < 4) {
; #pragma unroll
;             for (int rt = 0; rt < 4; ++rt)
; #pragma unroll
;                 for (int kk = 0; kk < 8; ++kk) S[4 * j + rt] = mfma16(*(const LAS bf16x8*)(base + (16 * rt + fr) * KS + 32 * kk + 8 * fq), qf[kk], S[4 * j + rt]);
	v_mfma_f32_16x16x32_bf16 v[72:75], v[76:79], v[4:7], v[72:75]
	global_load_dwordx4 v[12:15], v205, s[6:7]
	global_load_dwordx4 v[16:19], v206, s[6:7]
	global_load_dwordx4 v[20:23], v207, s[6:7]
	global_load_dwordx4 v[24:27], v208, s[6:7]
	v_mfma_f32_16x16x32_bf16 v[36:39], v[160:163], v[0:3], v[36:39]
	v_mfma_f32_16x16x32_bf16 v[52:55], v[52:55], v[0:3], v[48:51]
	v_mfma_f32_16x16x32_bf16 v[56:59], v[80:83], v[0:3], v[56:59]
	v_mfma_f32_16x16x32_bf16 v[60:63], v[84:87], v[0:3], v[60:63]
	v_mfma_f32_16x16x32_bf16 v[48:51], v[88:91], v[0:3], v[72:75]
	ds_read_b128 v[84:87], v210
	ds_read_b128 v[92:95], v210 offset:64
	ds_read_b128 v[176:179], v210 offset:128
	ds_read_b128 v[160:163], v210 offset:192
	ds_read_b128 v[116:119], v210 offset:256
	ds_read_b128 v[108:111], v210 offset:320
	ds_read_b128 v[80:83], v210 offset:384
	ds_read_b128 v[72:75], v210 offset:448
	ds_read_b128 v[96:99], v210 offset:8448
	ds_read_b128 v[180:183], v210 offset:8512
	ds_read_b128 v[228:231], v210 offset:8576
	ds_read_b128 v[164:167], v210 offset:8640
	ds_read_b128 v[124:127], v210 offset:8704
	ds_read_b128 v[112:115], v210 offset:8768
	ds_read_b128 v[88:91], v210 offset:8832
	ds_read_b128 v[76:79], v210 offset:8896
	ds_read_b128 v[100:103], v210 offset:16896
	ds_read_b128 v[184:187], v210 offset:16960
	ds_read_b128 v[232:235], v210 offset:17024
	ds_read_b128 v[168:171], v210 offset:17088
	ds_read_b128 v[104:107], v209
	s_waitcnt lgkmcnt(14)
	v_mfma_f32_16x16x32_bf16 v[188:191], v[84:87], v[140:143], 0
	s_waitcnt lgkmcnt(12)
	v_mfma_f32_16x16x32_bf16 v[192:195], v[96:99], v[140:143], 0
	ds_read_b128 v[128:131], v210 offset:17152
	ds_read_b128 v[120:123], v210 offset:17216
	ds_read_b128 v[96:99], v210 offset:17280
	ds_read_b128 v[84:87], v210 offset:17344
	ds_read_b128 v[236:239], v209 offset:64
	ds_read_b128 v[240:243], v209 offset:128
	s_waitcnt lgkmcnt(6)
	v_mfma_f32_16x16x32_bf16 v[244:247], v[104:107], v[140:143], 0
	ds_read_b128 v[136:139], v209 offset:192
	ds_read_b128 v[132:135], v209 offset:256
	ds_read_b128 v[104:107], v209 offset:320
	v_mfma_f32_16x16x32_bf16 v[196:199], v[100:103], v[140:143], 0
	v_mfma_f32_16x16x32_bf16 v[248:251], v[92:95], v[156:159], v[188:191]
	ds_read_b128 v[100:103], v209 offset:384
	ds_read_b128 v[92:95], v209 offset:448
	s_waitcnt vmcnt(7)
	ds_write_b128 v200, v[144:147] offset:36864
	s_waitcnt vmcnt(6)
	ds_write_b128 v211, v[148:151] offset:36864
	s_waitcnt vmcnt(5)
	ds_write_b128 v212, v[152:155] offset:36864
	s_waitcnt vmcnt(4)
	ds_write_b128 v221, v[172:175] offset:36864
	s_waitcnt lgkmcnt(0)
	s_barrier
	v_mfma_f32_16x16x32_bf16 v[236:239], v[236:239], v[156:159], v[244:247]
	ds_read_b128 v[148:151], v210 offset:36864
	s_nop 1
	ds_read_b128 v[244:247], v210 offset:36928
	v_mfma_f32_16x16x32_bf16 v[144:147], v[180:183], v[156:159], v[192:195]
	s_waitcnt lgkmcnt(1)
	v_mfma_f32_16x16x32_bf16 v[222:225], v[148:151], v[140:143], 0
	ds_read_b128 v[152:155], v210 offset:45312
	ds_read_b128 v[148:151], v210 offset:45376
	ds_read_b128 v[180:183], v210 offset:53760
	ds_read_b128 v[192:195], v210 offset:53824
	v_mfma_f32_16x16x32_bf16 v[172:175], v[184:187], v[156:159], v[196:199]
	s_waitcnt lgkmcnt(1)
	v_mfma_f32_16x16x32_bf16 v[196:199], v[180:183], v[140:143], 0
	ds_read_b128 v[180:183], v209 offset:36864
	ds_read_b128 v[184:187], v209 offset:36928
	v_mfma_f32_16x16x32_bf16 v[152:155], v[152:155], v[140:143], 0
	s_waitcnt lgkmcnt(1)
	v_mfma_f32_16x16x32_bf16 v[188:191], v[180:183], v[140:143], 0
	v_mfma_f32_16x16x32_bf16 v[180:183], v[176:179], v[68:71], v[248:251]
	v_mfma_f32_16x16x32_bf16 v[176:179], v[228:231], v[68:71], v[144:147]
	v_mfma_f32_16x16x32_bf16 v[140:143], v[240:243], v[68:71], v[236:239]
	s_nop 1
	v_cndmask_b32_e32 v144, v253, v227, vcc
	v_cmp_lt_i32_e32 vcc, v204, v226
	v_lshlrev_b32_e32 v211, 2, v144
	v_mfma_f32_16x16x32_bf16 v[148:151], v[148:151], v[156:159], v[152:155]
	v_cndmask_b32_e32 v200, v253, v204, vcc
	v_lshlrev_b32_e32 v212, 2, v200
	v_lshrrev_b32_e32 v200, 1, v216
	v_mfma_f32_16x16x32_bf16 v[152:155], v[192:195], v[156:159], v[196:199]
	v_lshrrev_b32_e32 v194, 3, v219
	v_lshrrev_b32_e32 v216, 3, v216
	v_mul_lo_u32 v216, v216, s20
	v_mfma_f32_16x16x32_bf16 v[160:163], v[160:163], v[64:67], v[180:183]
	v_and_b32_e32 v200, 24, v200
	v_or_b32_e32 v192, 0x70, v215
	v_or_b32_e32 v193, 0xb0, v215
	v_mul_lo_u32 v180, v217, s20
	v_mul_lo_u32 v181, v218, s20
	v_mul_lo_u32 v182, v194, s20
	v_mfma_f32_16x16x32_bf16 v[144:147], v[244:247], v[156:159], v[222:225]
	s_waitcnt lgkmcnt(0)
	v_mfma_f32_16x16x32_bf16 v[156:159], v[184:187], v[156:159], v[188:191]
	v_add3_u32 v184, 0, v216, v220
	v_or_b32_e32 v185, 0xf0, v215
	v_mfma_f32_16x16x32_bf16 v[164:167], v[164:167], v[64:67], v[176:179]
	s_nop 2
	v_add3_u32 v176, 0, v180, v220
	v_add3_u32 v177, 0, v181, v220
	v_add3_u32 v178, 0, v182, v220
	v_mfma_f32_16x16x32_bf16 v[180:183], v[136:139], v[64:67], v[140:143]
	ds_read_b128 v[136:139], v210 offset:36992
	ds_read_b128 v[186:189], v210 offset:37056
	s_waitcnt lgkmcnt(1)
	v_mfma_f32_16x16x32_bf16 v[194:197], v[136:139], v[68:71], v[144:147]
	ds_read_b128 v[136:139], v210 offset:45440
	ds_read_b128 v[216:219], v210 offset:45504
	s_nop 0
	v_max_f32_e32 v147, v43, v43
	v_mfma_f32_16x16x32_bf16 v[172:175], v[232:235], v[68:71], v[172:175]
	s_waitcnt lgkmcnt(1)
	v_mfma_f32_16x16x32_bf16 v[148:151], v[136:139], v[68:71], v[148:151]
	ds_read_b128 v[136:139], v210 offset:53888
	ds_read_b128 v[220:223], v210 offset:53952
	v_mfma_f32_16x16x32_bf16 v[168:171], v[168:171], v[64:67], v[172:175]
	s_waitcnt lgkmcnt(1)
; #define LAS __attribute__((address_space(3)))
; __device__ __forceinline__ f32x4 mfma16(bf16x8 a, bf16x8 b, f32x4 c) { return __builtin_amdgcn_mfma_f32_16x16x32_bf16(a, b, c, 0, 0, 0); }
; __device__ __forceinline__ bf16x8 pack8(f32x4 a, f32x4 b) { u32x4 w; w.x = pk2(a[0], a[1]); w.y = pk2(a[2], a[3]); w.z = pk2(b[0], b[1]); w.w = pk2(b[2], b[3]); return __builtin_bit_cast(bf16x8, w); }
; __device__ __forceinline__ void xattn_unit(const Args& a, LAS unsigned char* lds, int b, int h, int qb, int tid, int wave, int lane) {
;     ...
;         if (j < 6) gload(j + 2);
;         const LAS bf16* base = (const LAS bf16*)(lds + (j & 1) * STG);
;         if (j < 4) {
; #pragma unroll
;             for (int rt = 0; rt < 4; ++rt)
; #pragma unroll
;                 for (int kk = 0; kk < 8; ++kk) S[4 * j + rt] = mfma16(*(const LAS bf16x8*)(base + (16 * rt + fr) * KS + 32 * kk + 8 * fq), qf[kk], S[4 * j + rt]);
;             if (j == 3) {
;                 float mx = -3.0e38f;
; #pragma unroll
;                 for (int i = 0; i < 16; ++i) mx = fmaxf(mx, fmaxf(fmaxf(S[i][0], S[i][1]), fmaxf(S[i][2], S[i][3])));
;                 mx = fmaxf(mx, __shfl_xor(mx, 16)); mx = fmaxf(mx, __shfl_xor(mx, 32));
; #pragma unroll
;                 for (int i = 0; i < 16; ++i)
; #pragma unroll
;                     for (int k = 0; k < 4; ++k) { S[i][k] = __builtin_amdgcn_exp2f(S[i][k] - mx); l += S[i][k]; }
;                 l += __shfl_xor(l, 16); l += __shfl_xor(l, 32);
; #pragma unroll
;                 for (int c2 = 0; c2 < 8; ++c2) pf[c2] = pack8(S[2 * c2], S[2 * c2 + 1]);
	v_mfma_f32_16x16x32_bf16 v[152:155], v[136:139], v[68:71], v[152:155]
	ds_read_b128 v[136:139], v209 offset:36992
	ds_read_b128 v[228:231], v209 offset:37056
	v_add_u32_e32 v172, 0, v200
	v_mad_u32_u24 v173, v213, s20, v172
	s_waitcnt lgkmcnt(1)
	v_mfma_f32_16x16x32_bf16 v[68:71], v[136:139], v[68:71], v[156:159]
	v_mad_u32_u24 v138, v192, s20, v172
	v_mad_u32_u24 v137, v193, s20, v172
	v_mad_u32_u24 v139, v214, s20, v172
	v_mfma_f32_16x16x32_bf16 v[156:159], v[116:119], v[28:31], v[160:163]
	v_mad_u32_u24 v136, v185, s20, v172
	v_add_u32_e32 v146, 0x1000, v173
	v_add_u32_e32 v144, 0x2000, v173
	v_mfma_f32_16x16x32_bf16 v[160:163], v[124:127], v[28:31], v[164:167]
	v_add_u32_e32 v142, 0x2800, v173
	v_add_u32_e32 v143, 0x3000, v173
	v_add_u32_e32 v141, 0x4800, v173
	v_mfma_f32_16x16x32_bf16 v[164:167], v[128:131], v[28:31], v[168:171]
	v_add_u32_e32 v140, 0x5000, v173
	v_add_u32_e32 v145, 0x800, v173
	v_lshl_add_u64 v[174:175], s[2:3], 0, v[202:203]
	v_mfma_f32_16x16x32_bf16 v[168:171], v[132:135], v[28:31], v[180:183]
	v_add_u32_e32 v135, 0x5800, v173
	v_add_u32_e32 v132, 0x6800, v173
	v_add_u32_e32 v133, 0x7000, v173
	v_mfma_f32_16x16x32_bf16 v[180:183], v[186:189], v[64:67], v[194:197]
	v_add_u32_e32 v134, 0x7800, v173
	v_lshl_add_u64 v[174:175], v[174:175], 0, s[4:5]
	v_add_u32_e32 v131, 0x9000, v173
	v_mfma_f32_16x16x32_bf16 v[148:151], v[216:219], v[64:67], v[148:151]
	v_add_u32_e32 v129, 0x9800, v173
	v_add_u32_e32 v130, 0xa000, v173
	v_add_u32_e32 v128, 0x9000, v139
	v_mfma_f32_16x16x32_bf16 v[152:155], v[220:223], v[64:67], v[152:155]
	v_add_u32_e32 v126, 0xb000, v173
	v_add_u32_e32 v127, 0xb800, v173
	v_add_u32_e32 v125, 0xc000, v173
	s_waitcnt lgkmcnt(0)
	v_mfma_f32_16x16x32_bf16 v[64:67], v[228:231], v[64:67], v[68:71]
	v_add_u32_e32 v124, 0x9000, v138
	v_add_u32_e32 v119, 0xd800, v173
	v_add_u32_e32 v118, 0xe000, v173
	v_mfma_f32_16x16x32_bf16 v[68:71], v[108:111], v[8:11], v[156:159]
	v_lshl_add_u64 v[108:109], v[174:175], 0, v[200:201]
	v_add_u32_e32 v116, 0xe800, v173
	v_add_u32_e32 v117, 0x9000, v137
	v_mfma_f32_16x16x32_bf16 v[156:159], v[112:115], v[8:11], v[160:163]
	v_max_f32_e32 v114, v47, v47
	v_max_f32_e32 v115, v46, v46
	v_max_f32_e32 v114, v115, v114
	v_mfma_f32_16x16x32_bf16 v[120:123], v[120:123], v[8:11], v[164:167]
	ds_read_b128 v[160:163], v210 offset:37120
	s_nop 1
	ds_read_b128 v[164:167], v210 offset:37184
	v_add_u32_e32 v111, 0xf800, v173
	v_add_u32_e32 v113, 0x7000, v131
	v_mfma_f32_16x16x32_bf16 v[104:107], v[104:107], v[8:11], v[168:171]
	v_add_u32_e32 v112, 0x7800, v131
	v_add_u32_e32 v110, 0x9000, v136
	s_waitcnt lgkmcnt(1)
	v_mfma_f32_16x16x32_bf16 v[160:163], v[160:163], v[28:31], v[180:183]
	ds_read_b128 v[168:171], v210 offset:45568
	s_nop 1
	ds_read_b128 v[180:183], v210 offset:45632
	s_waitcnt lgkmcnt(1)
	v_mfma_f32_16x16x32_bf16 v[148:151], v[168:171], v[28:31], v[148:151]
	ds_read_b128 v[168:171], v210 offset:54016
	ds_read_b128 v[186:189], v210 offset:54080
	s_waitcnt lgkmcnt(1)
	v_mfma_f32_16x16x32_bf16 v[152:155], v[168:171], v[28:31], v[152:155]
	ds_read_b128 v[168:171], v209 offset:37120
	ds_read_b128 v[190:193], v209 offset:37184
	s_waitcnt lgkmcnt(1)
	v_mfma_f32_16x16x32_bf16 v[28:31], v[168:171], v[28:31], v[64:67]
	v_max_f32_e32 v168, v42, v42
	v_max_f32_e32 v169, v39, v39
	v_max_f32_e32 v170, v38, v38
	v_mfma_f32_16x16x32_bf16 v[64:67], v[80:83], v[4:7], v[68:71]
	v_mfma_f32_16x16x32_bf16 v[68:71], v[88:91], v[4:7], v[156:159]
	v_max_f32_e32 v88, v35, v35
	v_max_f32_e32 v89, v34, v34
	v_max_f32_e32 v115, v89, v88
	v_mfma_f32_16x16x32_bf16 v[80:83], v[96:99], v[4:7], v[120:123]
	v_max_f32_e32 v96, v168, v147
	v_max_f32_e32 v97, v170, v169
	v_max_f32_e32 v147, v59, v59
	v_mfma_f32_16x16x32_bf16 v[88:91], v[100:103], v[4:7], v[104:107]
	v_max3_f32 v100, v44, v45, v114
	v_max3_f32 v101, v40, v41, v96
	v_max3_f32 v102, v36, v37, v97
	v_max3_f32 v103, v32, v33, v115
	v_max3_f32 v100, v100, s19, v101
	v_max3_f32 v114, v100, v102, v103
	v_mfma_f32_16x16x32_bf16 v[100:103], v[180:183], v[8:11], v[148:151]
	v_max_f32_e32 v115, v55, v55
	v_max_f32_e32 v120, v54, v54
	s_nop 0
	v_max_f32_e32 v148, v58, v58
	v_mfma_f32_16x16x32_bf16 v[96:99], v[164:167], v[8:11], v[160:163]
	v_max_f32_e32 v149, v63, v63
	v_max_f32_e32 v150, v62, v62
	v_mfma_f32_16x16x32_bf16 v[104:107], v[186:189], v[8:11], v[152:155]
	s_waitcnt lgkmcnt(0)
	v_mfma_f32_16x16x32_bf16 v[8:11], v[190:193], v[8:11], v[28:31]
	s_nop 2
	v_max_f32_e32 v28, v51, v51
	v_max_f32_e32 v29, v50, v50
	v_max_f32_e32 v30, v120, v115
	v_max_f32_e32 v31, v148, v147
	v_mfma_f32_16x16x32_bf16 v[120:123], v[72:75], v[0:3], v[64:67]
	v_max_f32_e32 v28, v29, v28
	v_max3_f32 v29, v52, v53, v30
	v_max3_f32 v30, v56, v57, v31
	v_max_f32_e32 v64, v150, v149
	v_max3_f32 v31, v60, v61, v64
	v_max3_f32 v28, v48, v49, v28
	v_max3_f32 v29, v114, v29, v30
	v_max3_f32 v114, v29, v31, v28
	ds_read_b128 v[28:31], v210 offset:37248
	ds_read_b128 v[72:75], v210 offset:37312
	v_mfma_f32_16x16x32_bf16 v[80:83], v[84:87], v[0:3], v[80:83]
	v_max_f32_e32 v115, v123, v123
	v_max_f32_e32 v147, v122, v122
	v_mfma_f32_16x16x32_bf16 v[84:87], v[92:95], v[0:3], v[88:91]
	s_waitcnt lgkmcnt(1)
	v_mfma_f32_16x16x32_bf16 v[88:91], v[28:31], v[4:7], v[96:99]
	ds_read_b128 v[28:31], v210 offset:45696
	ds_read_b128 v[92:95], v210 offset:45760
	s_waitcnt lgkmcnt(1)
	v_mfma_f32_16x16x32_bf16 v[96:99], v[28:31], v[4:7], v[100:103]
	ds_read_b128 v[28:31], v210 offset:54144
	s_nop 1
	ds_read_b128 v[100:103], v210 offset:54208
	s_waitcnt lgkmcnt(1)
	v_mfma_f32_16x16x32_bf16 v[104:107], v[28:31], v[4:7], v[104:107]
	ds_read_b128 v[28:31], v209 offset:37248
	ds_read_b128 v[148:151], v209 offset:37312
	v_mfma_f32_16x16x32_bf16 v[76:79], v[76:79], v[0:3], v[68:71]
	s_waitcnt lgkmcnt(1)
	v_mfma_f32_16x16x32_bf16 v[4:7], v[28:31], v[4:7], v[8:11]
	s_nop 0
	global_load_dwordx4 v[68:71], v205, s[6:7] offset:128
	global_load_dwordx4 v[28:31], v206, s[6:7] offset:128
	global_load_dwordx4 v[64:67], v207, s[6:7] offset:128
	v_mfma_f32_16x16x32_bf16 v[8:11], v[72:75], v[0:3], v[88:91]
	global_load_dwordx4 v[72:75], v208, s[6:7] offset:128
	s_waitcnt vmcnt(7)
	ds_write_b128 v184, v[12:15]
	s_waitcnt vmcnt(6)
	ds_write_b128 v176, v[16:19]
	s_waitcnt vmcnt(5)
	ds_write_b128 v177, v[20:23]
	s_waitcnt vmcnt(4)
	ds_write_b128 v178, v[24:27]
	s_waitcnt lgkmcnt(0)
	v_mfma_f32_16x16x32_bf16 v[88:91], v[92:95], v[0:3], v[96:99]
	s_barrier
; #define LAS __attribute__((address_space(3)))
; __device__ __forceinline__ f32x4 mfma16(bf16x8 a, bf16x8 b, f32x4 c) { return __builtin_amdgcn_mfma_f32_16x16x32_bf16(a, b, c, 0, 0, 0); }
; __device__ __forceinline__ bf16x8 pack8(f32x4 a, f32x4 b) { u32x4 w; w.x = pk2(a[0], a[1]); w.y = pk2(a[2], a[3]); w.z = pk2(b[0], b[1]); w.w = pk2(b[2], b[3]); return __builtin_bit_cast(bf16x8, w); }
; __device__ __forceinline__ void xattn_unit(const Args& a, LAS unsigned char* lds, int b, int h, int qb, int tid, int wave, int lane) {
;     ...
;             if (j == 3) {
;                 float mx = -3.0e38f;
; #pragma unroll
;                 for (int i = 0; i < 16; ++i) mx = fmaxf(mx, fmaxf(fmaxf(S[i][0], S[i][1]), fmaxf(S[i][2], S[i][3])));
;                 mx = fmaxf(mx, __shfl_xor(mx, 16)); mx = fmaxf(mx, __shfl_xor(mx, 32));
; #pragma unroll
;                 for (int i = 0; i < 16; ++i)
; #pragma unroll
;                     for (int k = 0; k < 4; ++k) { S[i][k] = __builtin_amdgcn_exp2f(S[i][k] - mx); l += S[i][k]; }
;                 l += __shfl_xor(l, 16); l += __shfl_xor(l, 32);
; #pragma unroll
;                 for (int c2 = 0; c2 < 8; ++c2) pf[c2] = pack8(S[2 * c2], S[2 * c2 + 1]);
;             }
;         } else {
;             const int mt = j - 4;
; #pragma unroll
;             for (int dt = 0; dt < 16; ++dt) {
;                 const LAS bf16* vr = base + (16 * dt + fr) * VS + 4 * fq;
;                 O[dt] = mfma16(cat8(*(const LAS u32x2*)vr, *(const LAS u32x2*)(vr + 16)), pf[2 * mt], O[dt]);
	ds_read2_b64 v[12:15], v173 offset1:4
	ds_read2_b64 v[16:19], v145 offset0:32 offset1:36
	v_max_f32_e32 v96, v79, v79
	v_max_f32_e32 v97, v78, v78
	v_max_f32_e32 v98, v83, v83
	v_mfma_f32_16x16x32_bf16 v[92:95], v[100:103], v[0:3], v[104:107]
	v_max_f32_e32 v99, v82, v82
	v_max_f32_e32 v100, v87, v87
	v_max_f32_e32 v101, v86, v86
	v_mfma_f32_16x16x32_bf16 v[0:3], v[148:151], v[0:3], v[4:7]
	ds_read2_b64 v[20:23], v146 offset0:64 offset1:68
	ds_read2_b64 v[24:27], v139 offset1:4
	ds_read2_b64 v[148:151], v173 offset0:8 offset1:12
	v_max_f32_e32 v4, v147, v115
	v_max_f32_e32 v5, v97, v96
	v_max_f32_e32 v6, v99, v98
	v_max_f32_e32 v7, v101, v100
	v_max3_f32 v4, v120, v121, v4
	v_max3_f32 v5, v76, v77, v5
	v_max3_f32 v6, v80, v81, v6
	v_max3_f32 v7, v84, v85, v7
	v_max3_f32 v4, v114, v4, v5
	v_max3_f32 v4, v4, v6, v7
	v_max_f32_e32 v5, v11, v11
	v_max_f32_e32 v6, v10, v10
	v_max_f32_e32 v7, v91, v91
	v_max_f32_e32 v96, v90, v90
	v_max_f32_e32 v97, v95, v95
	v_max_f32_e32 v98, v94, v94
	v_max_f32_e32 v99, v3, v3
	v_max_f32_e32 v100, v2, v2
	v_max_f32_e32 v5, v6, v5
	v_max_f32_e32 v6, v96, v7
	v_max_f32_e32 v7, v98, v97
	v_max_f32_e32 v96, v100, v99
	v_max3_f32 v5, v8, v9, v5
	v_max3_f32 v6, v88, v89, v6
	v_max3_f32 v7, v92, v93, v7
	v_max3_f32 v96, v0, v1, v96
	v_max3_f32 v4, v4, v5, v6
	v_max3_f32 v4, v4, v7, v96
	ds_bpermute_b32 v5, v211, v4
	s_waitcnt lgkmcnt(0)
	v_max_f32_e32 v5, v5, v5
	v_max_f32_e32 v4, v4, v5
	ds_bpermute_b32 v5, v212, v4
	s_waitcnt lgkmcnt(0)
	v_max_f32_e32 v5, v5, v5
	v_max_f32_e32 v4, v4, v5
	v_sub_f32_e32 v5, v44, v4
	v_sub_f32_e32 v6, v45, v4
	v_sub_f32_e32 v7, v46, v4
	v_sub_f32_e32 v44, v47, v4
	v_sub_f32_e32 v40, v40, v4
	v_sub_f32_e32 v41, v41, v4
	v_sub_f32_e32 v42, v42, v4
	v_sub_f32_e32 v43, v43, v4
	v_sub_f32_e32 v36, v36, v4
	v_sub_f32_e32 v37, v37, v4
	v_sub_f32_e32 v38, v38, v4
	v_sub_f32_e32 v39, v39, v4
	v_sub_f32_e32 v32, v32, v4
	v_sub_f32_e32 v33, v33, v4
	v_sub_f32_e32 v34, v34, v4
	v_sub_f32_e32 v35, v35, v4
	v_sub_f32_e32 v45, v52, v4
	v_sub_f32_e32 v46, v53, v4
	v_sub_f32_e32 v47, v54, v4
	v_sub_f32_e32 v52, v55, v4
	v_sub_f32_e32 v53, v56, v4
	v_sub_f32_e32 v54, v57, v4
	v_sub_f32_e32 v55, v58, v4
	v_sub_f32_e32 v56, v59, v4
	v_sub_f32_e32 v57, v60, v4
	v_sub_f32_e32 v58, v61, v4
	v_sub_f32_e32 v59, v62, v4
	v_sub_f32_e32 v60, v63, v4
	v_sub_f32_e32 v48, v48, v4
	v_sub_f32_e32 v49, v49, v4
	v_sub_f32_e32 v50, v50, v4
	v_sub_f32_e32 v51, v51, v4
	v_sub_f32_e32 v61, v120, v4
	v_sub_f32_e32 v62, v121, v4
	v_sub_f32_e32 v63, v122, v4
	v_sub_f32_e32 v96, v123, v4
	v_sub_f32_e32 v76, v76, v4
	v_sub_f32_e32 v77, v77, v4
	v_sub_f32_e32 v78, v78, v4
	v_sub_f32_e32 v79, v79, v4
	v_sub_f32_e32 v80, v80, v4
	v_sub_f32_e32 v81, v81, v4
	v_sub_f32_e32 v82, v82, v4
	v_sub_f32_e32 v83, v83, v4
	v_sub_f32_e32 v84, v84, v4
	v_sub_f32_e32 v85, v85, v4
	v_sub_f32_e32 v86, v86, v4
	v_sub_f32_e32 v87, v87, v4
	v_sub_f32_e32 v8, v8, v4
	v_sub_f32_e32 v9, v9, v4
	v_sub_f32_e32 v10, v10, v4
	v_sub_f32_e32 v11, v11, v4
	v_sub_f32_e32 v88, v88, v4
	v_sub_f32_e32 v89, v89, v4
	v_sub_f32_e32 v90, v90, v4
	v_sub_f32_e32 v91, v91, v4
	v_sub_f32_e32 v92, v92, v4
	v_sub_f32_e32 v93, v93, v4
	v_sub_f32_e32 v94, v94, v4
	v_sub_f32_e32 v95, v95, v4
	v_sub_f32_e32 v0, v0, v4
	v_sub_f32_e32 v1, v1, v4
	v_sub_f32_e32 v2, v2, v4
	v_sub_f32_e32 v3, v3, v4
	v_exp_f32_e32 v4, v5
	v_exp_f32_e32 v97, v6
	v_exp_f32_e32 v98, v7
	v_exp_f32_e32 v99, v44
	v_exp_f32_e32 v100, v40
	v_exp_f32_e32 v190, v52
	v_add_f32_e32 v52, 0, v4
	v_exp_f32_e32 v101, v41
	v_add_f32_e32 v52, v97, v52
	v_exp_f32_e32 v102, v42
	v_add_f32_e32 v52, v98, v52
	v_exp_f32_e32 v103, v43
	v_add_f32_e32 v52, v99, v52
	v_exp_f32_e32 v104, v36
	v_add_f32_e32 v52, v100, v52
	v_exp_f32_e32 v105, v37
	v_add_f32_e32 v52, v101, v52
	v_exp_f32_e32 v106, v38
	v_exp_f32_e32 v114, v39
	v_add_f32_e32 v52, v102, v52
	v_add_f32_e32 v52, v103, v52
	v_add_f32_e32 v52, v104, v52
	v_add_f32_e32 v52, v105, v52
	v_exp_f32_e32 v191, v53
	v_exp_f32_e32 v192, v54
	v_exp_f32_e32 v193, v55
	v_exp_f32_e32 v194, v56
	v_exp_f32_e32 v195, v57
	v_exp_f32_e32 v196, v58
	v_exp_f32_e32 v197, v59
	v_exp_f32_e32 v198, v60
	v_exp_f32_e32 v209, v61
	v_exp_f32_e32 v210, v62
	v_exp_f32_e32 v213, v63
	v_exp_f32_e32 v214, v96
	v_exp_f32_e32 v215, v76
	v_exp_f32_e32 v216, v77
	v_exp_f32_e32 v217, v78
	v_exp_f32_e32 v218, v79
	v_exp_f32_e32 v219, v80
	v_exp_f32_e32 v220, v81
	v_exp_f32_e32 v221, v82
	v_exp_f32_e32 v222, v83
	v_exp_f32_e32 v223, v84
	v_exp_f32_e32 v224, v85
	v_exp_f32_e32 v225, v86
	v_exp_f32_e32 v228, v87
	v_exp_f32_e32 v233, v88
	v_exp_f32_e32 v234, v89
	v_exp_f32_e32 v235, v90
	v_exp_f32_e32 v236, v91
	v_exp_f32_e32 v237, v92
	v_exp_f32_e32 v238, v93
	v_exp_f32_e32 v239, v94
	v_exp_f32_e32 v240, v95
	v_cvt_pk_bf16_f32 v36, v4, v97
	v_cvt_pk_bf16_f32 v37, v98, v99
	v_cvt_pk_bf16_f32 v38, v100, v101
	v_cvt_pk_bf16_f32 v39, v102, v103
	v_cvt_pk_bf16_f32 v40, v104, v105
	v_cvt_pk_bf16_f32 v41, v106, v114
	v_add_f32_e32 v156, v106, v52
	ds_read2_b64 v[52:55], v144 offset0:128 offset1:132
	ds_read2_b64 v[56:59], v142 offset0:160 offset1:164
	ds_read2_b64 v[60:63], v143 offset0:192 offset1:196
	ds_read2_b64 v[76:79], v138 offset1:4
	ds_read2_b64 v[80:83], v141 offset1:4
	ds_read2_b64 v[84:87], v140 offset0:32 offset1:36
	ds_read2_b64 v[88:91], v135 offset0:64 offset1:68
	ds_read2_b64 v[92:95], v137 offset1:4
	ds_read2_b64 v[96:99], v132 offset0:128 offset1:132
	ds_read2_b64 v[100:103], v133 offset0:160 offset1:164
	ds_read2_b64 v[104:107], v134 offset0:192 offset1:196
	ds_read2_b64 v[120:123], v136 offset1:4
	v_exp_f32_e32 v115, v32
	v_exp_f32_e32 v147, v33
	v_exp_f32_e32 v172, v34
	v_exp_f32_e32 v174, v35
	v_mfma_f32_16x16x32_bf16 v[12:15], v[12:15], v[36:39], 0
	v_cvt_pk_bf16_f32 v42, v115, v147
	v_add_f32_e32 v114, v114, v156
	v_cvt_pk_bf16_f32 v43, v172, v174
	v_mfma_f32_16x16x32_bf16 v[16:19], v[16:19], v[36:39], 0
	v_exp_f32_e32 v175, v45
	v_exp_f32_e32 v179, v46
	v_exp_f32_e32 v185, v47
	v_mfma_f32_16x16x32_bf16 v[20:23], v[20:23], v[36:39], 0
	v_cvt_pk_bf16_f32 v46, v191, v192
	v_cvt_pk_bf16_f32 v44, v175, v179
	v_cvt_pk_bf16_f32 v45, v185, v190
	v_mfma_f32_16x16x32_bf16 v[24:27], v[24:27], v[36:39], 0
	v_cvt_pk_bf16_f32 v47, v193, v194
	v_exp_f32_e32 v199, v48
	v_exp_f32_e32 v200, v49
	s_waitcnt lgkmcnt(11)
; #define LAS __attribute__((address_space(3)))
; __device__ __forceinline__ f32x4 mfma16(bf16x8 a, bf16x8 b, f32x4 c) { return __builtin_amdgcn_mfma_f32_16x16x32_bf16(a, b, c, 0, 0, 0); }
; __device__ __forceinline__ bf16x8 pack8(f32x4 a, f32x4 b) { u32x4 w; w.x = pk2(a[0], a[1]); w.y = pk2(a[2], a[3]); w.z = pk2(b[0], b[1]); w.w = pk2(b[2], b[3]); return __builtin_bit_cast(bf16x8, w); }
; __device__ __forceinline__ void xattn_unit(const Args& a, LAS unsigned char* lds, int b, int h, int qb, int tid, int wave, int lane) {
;     ...
;                 for (int i = 0; i < 16; ++i)
; #pragma unroll
;                     for (int k = 0; k < 4; ++k) { S[i][k] = __builtin_amdgcn_exp2f(S[i][k] - mx); l += S[i][k]; }
;                 l += __shfl_xor(l, 16); l += __shfl_xor(l, 32);
; #pragma unroll
;                 for (int c2 = 0; c2 < 8; ++c2) pf[c2] = pack8(S[2 * c2], S[2 * c2 + 1]);
;             }
;         } else {
;             const int mt = j - 4;
; #pragma unroll
;             for (int dt = 0; dt < 16; ++dt) {
;                 const LAS bf16* vr = base + (16 * dt + fr) * VS + 4 * fq;
;                 O[dt] = mfma16(cat8(*(const LAS u32x2*)vr, *(const LAS u32x2*)(vr + 16)), pf[2 * mt], O[dt]);
;                 O[dt] = mfma16(cat8(*(const LAS u32x2*)(vr + 32), *(const LAS u32x2*)(vr + 48)), pf[2 * mt + 1], O[dt]);
;             }
;         }
;         if (j < 7) lstore(j + 1);
;         __syncthreads();
	v_mfma_f32_16x16x32_bf16 v[52:55], v[52:55], v[36:39], 0
	v_exp_f32_e32 v202, v50
	v_exp_f32_e32 v203, v51
	v_cvt_pk_bf16_f32 v48, v195, v196
	s_waitcnt lgkmcnt(10)
	v_mfma_f32_16x16x32_bf16 v[56:59], v[56:59], v[36:39], 0
	v_cvt_pk_bf16_f32 v49, v197, v198
	v_cvt_pk_bf16_f32 v50, v199, v200
	v_cvt_pk_bf16_f32 v51, v202, v203
	s_waitcnt lgkmcnt(9)
	v_mfma_f32_16x16x32_bf16 v[60:63], v[60:63], v[36:39], 0
	v_add_f32_e32 v114, v115, v114
	v_add_f32_e32 v114, v147, v114
	v_add_f32_e32 v114, v172, v114
	s_waitcnt lgkmcnt(8)
	v_mfma_f32_16x16x32_bf16 v[76:79], v[76:79], v[36:39], 0
	v_add_f32_e32 v114, v174, v114
	v_add_f32_e32 v114, v175, v114
	v_add_f32_e32 v114, v179, v114
	s_waitcnt lgkmcnt(7)
	v_mfma_f32_16x16x32_bf16 v[80:83], v[80:83], v[36:39], 0
	v_add_f32_e32 v114, v185, v114
	v_add_f32_e32 v114, v190, v114
	v_add_f32_e32 v114, v191, v114
	s_waitcnt lgkmcnt(6)
	v_mfma_f32_16x16x32_bf16 v[84:87], v[84:87], v[36:39], 0
	v_add_f32_e32 v114, v192, v114
	v_add_f32_e32 v114, v193, v114
	v_add_f32_e32 v114, v194, v114
	s_waitcnt lgkmcnt(5)
	v_mfma_f32_16x16x32_bf16 v[88:91], v[88:91], v[36:39], 0
	v_exp_f32_e32 v229, v8
	v_exp_f32_e32 v230, v9
	v_exp_f32_e32 v231, v10
	s_waitcnt lgkmcnt(4)
	v_mfma_f32_16x16x32_bf16 v[92:95], v[92:95], v[36:39], 0
	v_exp_f32_e32 v232, v11
	v_exp_f32_e32 v241, v0
	v_exp_f32_e32 v242, v1
	s_waitcnt lgkmcnt(3)
	v_mfma_f32_16x16x32_bf16 v[96:99], v[96:99], v[36:39], 0
	v_exp_f32_e32 v243, v2
	v_exp_f32_e32 v244, v3
	v_cvt_pk_bf16_f32 v32, v209, v210
	s_waitcnt lgkmcnt(2)
	v_mfma_f32_16x16x32_bf16 v[100:103], v[100:103], v[36:39], 0
	v_cvt_pk_bf16_f32 v33, v213, v214
	v_cvt_pk_bf16_f32 v34, v215, v216
	v_cvt_pk_bf16_f32 v35, v217, v218
	s_waitcnt lgkmcnt(1)
	v_mfma_f32_16x16x32_bf16 v[104:107], v[104:107], v[36:39], 0
	v_cvt_pk_bf16_f32 v8, v219, v220
	v_cvt_pk_bf16_f32 v9, v221, v222
	v_cvt_pk_bf16_f32 v10, v223, v224
	s_waitcnt lgkmcnt(0)
	v_mfma_f32_16x16x32_bf16 v[36:39], v[120:123], v[36:39], 0
	ds_read2_b64 v[120:123], v145 offset0:40 offset1:44
	v_cvt_pk_bf16_f32 v11, v225, v228
	v_cvt_pk_bf16_f32 v4, v229, v230
	v_mfma_f32_16x16x32_bf16 v[12:15], v[148:151], v[40:43], v[12:15]
	ds_read2_b64 v[148:151], v146 offset0:72 offset1:76
	v_cvt_pk_bf16_f32 v5, v231, v232
	v_cvt_pk_bf16_f32 v6, v233, v234
	s_waitcnt lgkmcnt(1)
	v_mfma_f32_16x16x32_bf16 v[16:19], v[120:123], v[40:43], v[16:19]
	ds_read2_b64 v[120:123], v139 offset0:8 offset1:12
	v_cvt_pk_bf16_f32 v7, v235, v236
	v_cvt_pk_bf16_f32 v0, v237, v238
	s_waitcnt lgkmcnt(1)
	v_mfma_f32_16x16x32_bf16 v[20:23], v[148:151], v[40:43], v[20:23]
	ds_read2_b64 v[148:151], v144 offset0:136 offset1:140
	v_cvt_pk_bf16_f32 v1, v239, v240
	v_cvt_pk_bf16_f32 v2, v241, v242
	s_waitcnt lgkmcnt(1)
	v_mfma_f32_16x16x32_bf16 v[24:27], v[120:123], v[40:43], v[24:27]
	ds_read2_b64 v[120:123], v142 offset0:168 offset1:172
	v_cvt_pk_bf16_f32 v3, v243, v244
	s_waitcnt lgkmcnt(1)
	v_mfma_f32_16x16x32_bf16 v[52:55], v[148:151], v[40:43], v[52:55]
	ds_read2_b64 v[148:151], v143 offset0:200 offset1:204
	s_waitcnt lgkmcnt(1)
	v_mfma_f32_16x16x32_bf16 v[56:59], v[120:123], v[40:43], v[56:59]
	ds_read2_b64 v[120:123], v138 offset0:8 offset1:12
	s_waitcnt lgkmcnt(1)
	v_mfma_f32_16x16x32_bf16 v[60:63], v[148:151], v[40:43], v[60:63]
	ds_read2_b64 v[148:151], v141 offset0:8 offset1:12
	ds_read2_b64 v[152:155], v140 offset0:40 offset1:44
	ds_read2_b64 v[156:159], v135 offset0:72 offset1:76
	s_waitcnt lgkmcnt(3)
	v_mfma_f32_16x16x32_bf16 v[76:79], v[120:123], v[40:43], v[76:79]
	global_load_dwordx4 v[120:123], v205, s[6:7] offset:256
	s_waitcnt lgkmcnt(2)
	v_mfma_f32_16x16x32_bf16 v[80:83], v[148:151], v[40:43], v[80:83]
	global_load_dwordx4 v[148:151], v206, s[6:7] offset:256
	global_load_dwordx4 v[160:163], v207, s[6:7] offset:256
	ds_read2_b64 v[164:167], v137 offset0:8 offset1:12
	s_waitcnt lgkmcnt(2)
	v_mfma_f32_16x16x32_bf16 v[84:87], v[152:155], v[40:43], v[84:87]
	global_load_dwordx4 v[152:155], v208, s[6:7] offset:256
	ds_read2_b64 v[168:171], v132 offset0:136 offset1:140
	ds_read2_b64 v[180:183], v133 offset0:168 offset1:172
	s_waitcnt lgkmcnt(3)
	v_mfma_f32_16x16x32_bf16 v[88:91], v[156:159], v[40:43], v[88:91]
	ds_read2_b64 v[156:159], v134 offset0:200 offset1:204
	ds_read2_b64 v[186:189], v136 offset0:8 offset1:12
	s_waitcnt vmcnt(7)
	ds_write_b128 v184, v[68:71] offset:36864
	s_waitcnt vmcnt(6)
	ds_write_b128 v176, v[28:31] offset:36864
	s_waitcnt vmcnt(5)
	ds_write_b128 v177, v[64:67] offset:36864
	s_waitcnt vmcnt(4)
	ds_write_b128 v178, v[72:75] offset:36864
	s_waitcnt lgkmcnt(0)
	s_barrier
; #define LAS __attribute__((address_space(3)))
; __device__ __forceinline__ f32x4 mfma16(bf16x8 a, bf16x8 b, f32x4 c) { return __builtin_amdgcn_mfma_f32_16x16x32_bf16(a, b, c, 0, 0, 0); }
; __device__ __forceinline__ void xattn_unit(const Args& a, LAS unsigned char* lds, int b, int h, int qb, int tid, int wave, int lane) {
;     ...
;         } else {
;             const int mt = j - 4;
; #pragma unroll
;             for (int dt = 0; dt < 16; ++dt) {
;                 const LAS bf16* vr = base + (16 * dt + fr) * VS + 4 * fq;
;                 O[dt] = mfma16(cat8(*(const LAS u32x2*)vr, *(const LAS u32x2*)(vr + 16)), pf[2 * mt], O[dt]);
;                 O[dt] = mfma16(cat8(*(const LAS u32x2*)(vr + 32), *(const LAS u32x2*)(vr + 48)), pf[2 * mt + 1], O[dt]);
;             }
;         }
;         if (j < 7) lstore(j + 1);
;         __syncthreads();
	ds_read2_b64 v[72:75], v131 offset1:4
	v_mfma_f32_16x16x32_bf16 v[92:95], v[164:167], v[40:43], v[92:95]
	v_mfma_f32_16x16x32_bf16 v[68:71], v[168:171], v[40:43], v[96:99]
	v_mfma_f32_16x16x32_bf16 v[28:31], v[180:183], v[40:43], v[100:103]
	v_mfma_f32_16x16x32_bf16 v[64:67], v[156:159], v[40:43], v[104:107]
	v_mfma_f32_16x16x32_bf16 v[36:39], v[186:189], v[40:43], v[36:39]
	ds_read2_b64 v[40:43], v129 offset0:32 offset1:36
	s_waitcnt lgkmcnt(1)
	v_mfma_f32_16x16x32_bf16 v[12:15], v[72:75], v[44:47], v[12:15]
	ds_read2_b64 v[72:75], v130 offset0:64 offset1:68
	s_waitcnt lgkmcnt(1)
	v_mfma_f32_16x16x32_bf16 v[16:19], v[40:43], v[44:47], v[16:19]
	ds_read2_b64 v[40:43], v128 offset1:4
	s_waitcnt lgkmcnt(1)
	v_mfma_f32_16x16x32_bf16 v[20:23], v[72:75], v[44:47], v[20:23]
	ds_read2_b64 v[72:75], v126 offset0:128 offset1:132
	s_waitcnt lgkmcnt(1)
	v_mfma_f32_16x16x32_bf16 v[24:27], v[40:43], v[44:47], v[24:27]
	ds_read2_b64 v[40:43], v127 offset0:160 offset1:164
	s_waitcnt lgkmcnt(1)
	v_mfma_f32_16x16x32_bf16 v[52:55], v[72:75], v[44:47], v[52:55]
	ds_read2_b64 v[72:75], v125 offset0:192 offset1:196
	s_waitcnt lgkmcnt(1)
	v_mfma_f32_16x16x32_bf16 v[40:43], v[40:43], v[44:47], v[56:59]
	s_nop 2
	ds_read2_b64 v[56:59], v124 offset1:4
	s_waitcnt lgkmcnt(1)
	v_mfma_f32_16x16x32_bf16 v[60:63], v[72:75], v[44:47], v[60:63]
	ds_read2_b64 v[72:75], v119 offset1:4
	s_waitcnt lgkmcnt(1)
	v_mfma_f32_16x16x32_bf16 v[56:59], v[56:59], v[44:47], v[76:79]
	s_nop 2
	ds_read2_b64 v[76:79], v118 offset0:32 offset1:36
	s_waitcnt lgkmcnt(1)
	v_mfma_f32_16x16x32_bf16 v[72:75], v[72:75], v[44:47], v[80:83]
	s_nop 2
	ds_read2_b64 v[80:83], v116 offset0:64 offset1:68
	s_waitcnt lgkmcnt(1)
	v_mfma_f32_16x16x32_bf16 v[76:79], v[76:79], v[44:47], v[84:87]
	s_nop 2
	ds_read2_b64 v[84:87], v117 offset1:4
	s_waitcnt lgkmcnt(1)
	v_mfma_f32_16x16x32_bf16 v[80:83], v[80:83], v[44:47], v[88:91]
	s_nop 2
	ds_read2_b64 v[88:91], v111 offset0:128 offset1:132
	s_waitcnt lgkmcnt(1)
	v_mfma_f32_16x16x32_bf16 v[84:87], v[84:87], v[44:47], v[92:95]
	s_nop 2
	ds_read2_b64 v[92:95], v113 offset0:160 offset1:164
	s_waitcnt lgkmcnt(1)
	v_mfma_f32_16x16x32_bf16 v[68:71], v[88:91], v[44:47], v[68:71]
	ds_read2_b64 v[88:91], v112 offset0:192 offset1:196
	s_waitcnt lgkmcnt(1)
	v_mfma_f32_16x16x32_bf16 v[28:31], v[92:95], v[44:47], v[28:31]
	ds_read2_b64 v[92:95], v110 offset1:4
	s_waitcnt lgkmcnt(1)
	v_mfma_f32_16x16x32_bf16 v[64:67], v[88:91], v[44:47], v[64:67]
	ds_read2_b64 v[88:91], v131 offset0:8 offset1:12
	s_waitcnt lgkmcnt(1)
	v_mfma_f32_16x16x32_bf16 v[36:39], v[92:95], v[44:47], v[36:39]
	ds_read2_b64 v[44:47], v129 offset0:40 offset1:44
	s_waitcnt lgkmcnt(1)
	v_mfma_f32_16x16x32_bf16 v[12:15], v[88:91], v[48:51], v[12:15]
	ds_read2_b64 v[88:91], v130 offset0:72 offset1:76
	s_waitcnt lgkmcnt(1)
	v_mfma_f32_16x16x32_bf16 v[16:19], v[44:47], v[48:51], v[16:19]
	ds_read2_b64 v[44:47], v128 offset0:8 offset1:12
	s_waitcnt lgkmcnt(1)
	v_mfma_f32_16x16x32_bf16 v[20:23], v[88:91], v[48:51], v[20:23]
	ds_read2_b64 v[88:91], v126 offset0:136 offset1:140
	s_waitcnt lgkmcnt(1)
	v_mfma_f32_16x16x32_bf16 v[24:27], v[44:47], v[48:51], v[24:27]
	ds_read2_b64 v[44:47], v127 offset0:168 offset1:172
	s_waitcnt lgkmcnt(1)
	v_mfma_f32_16x16x32_bf16 v[52:55], v[88:91], v[48:51], v[52:55]
	ds_read2_b64 v[88:91], v125 offset0:200 offset1:204
	ds_read2_b64 v[92:95], v124 offset0:8 offset1:12
	ds_read2_b64 v[96:99], v119 offset0:8 offset1:12
	s_waitcnt lgkmcnt(3)
	v_mfma_f32_16x16x32_bf16 v[40:43], v[44:47], v[48:51], v[40:43]
	global_load_dwordx4 v[44:47], v205, s[6:7] offset:384
	s_waitcnt lgkmcnt(2)
	v_mfma_f32_16x16x32_bf16 v[60:63], v[88:91], v[48:51], v[60:63]
	global_load_dwordx4 v[88:91], v206, s[6:7] offset:384
	global_load_dwordx4 v[100:103], v207, s[6:7] offset:384
	ds_read2_b64 v[104:107], v118 offset0:40 offset1:44
	s_waitcnt lgkmcnt(2)
	v_mfma_f32_16x16x32_bf16 v[56:59], v[92:95], v[48:51], v[56:59]
	global_load_dwordx4 v[92:95], v208, s[6:7] offset:384
	ds_read2_b64 v[156:159], v116 offset0:72 offset1:76
	ds_read2_b64 v[164:167], v117 offset0:8 offset1:12
	s_waitcnt lgkmcnt(3)
	v_mfma_f32_16x16x32_bf16 v[72:75], v[96:99], v[48:51], v[72:75]
	ds_read2_b64 v[96:99], v111 offset0:136 offset1:140
	ds_read2_b64 v[168:171], v113 offset0:168 offset1:172
	ds_read2_b64 v[180:183], v112 offset0:200 offset1:204
	s_waitcnt lgkmcnt(5)
	v_mfma_f32_16x16x32_bf16 v[76:79], v[104:107], v[48:51], v[76:79]
	ds_read2_b64 v[104:107], v110 offset0:8 offset1:12
	s_waitcnt vmcnt(7)
	ds_write_b128 v184, v[120:123]
	s_waitcnt vmcnt(6)
	ds_write_b128 v176, v[148:151]
	s_waitcnt vmcnt(5)
	ds_write_b128 v177, v[160:163]
	s_waitcnt vmcnt(4)
	ds_write_b128 v178, v[152:155]
	s_waitcnt lgkmcnt(0)
	v_mfma_f32_16x16x32_bf16 v[68:71], v[96:99], v[48:51], v[68:71]
	v_add_f32_e32 v96, v195, v114
	v_add_f32_e32 v96, v196, v96
	v_add_f32_e32 v96, v197, v96
	v_add_f32_e32 v96, v198, v96
	v_add_f32_e32 v96, v199, v96
	v_add_f32_e32 v96, v200, v96
	v_add_f32_e32 v96, v202, v96
	v_add_f32_e32 v96, v203, v96
	v_add_f32_e32 v96, v209, v96
	v_mfma_f32_16x16x32_bf16 v[80:83], v[156:159], v[48:51], v[80:83]
	s_barrier
; #define LAS __attribute__((address_space(3)))
; __device__ __forceinline__ f32x4 mfma16(bf16x8 a, bf16x8 b, f32x4 c) { return __builtin_amdgcn_mfma_f32_16x16x32_bf16(a, b, c, 0, 0, 0); }
; __device__ __forceinline__ void xattn_unit(const Args& a, LAS unsigned char* lds, int b, int h, int qb, int tid, int wave, int lane) {
;     ...
;                 l += __shfl_xor(l, 16); l += __shfl_xor(l, 32);
;     ...
;             const int mt = j - 4;
; #pragma unroll
;             for (int dt = 0; dt < 16; ++dt) {
;                 const LAS bf16* vr = base + (16 * dt + fr) * VS + 4 * fq;
;                 O[dt] = mfma16(cat8(*(const LAS u32x2*)vr, *(const LAS u32x2*)(vr + 16)), pf[2 * mt], O[dt]);
;                 O[dt] = mfma16(cat8(*(const LAS u32x2*)(vr + 32), *(const LAS u32x2*)(vr + 48)), pf[2 * mt + 1], O[dt]);
;             }
;         }
;         if (j < 7) lstore(j + 1);
;         __syncthreads();
;     }
;     const float il = 1.f / l;
	v_mfma_f32_16x16x32_bf16 v[84:87], v[164:167], v[48:51], v[84:87]
	v_mfma_f32_16x16x32_bf16 v[28:31], v[168:171], v[48:51], v[28:31]
	v_mfma_f32_16x16x32_bf16 v[64:67], v[180:183], v[48:51], v[64:67]
	v_mfma_f32_16x16x32_bf16 v[36:39], v[104:107], v[48:51], v[36:39]
	v_add_f32_e32 v48, v210, v96
	v_add_f32_e32 v48, v213, v48
	v_add_f32_e32 v48, v214, v48
	v_add_f32_e32 v48, v215, v48
	v_add_f32_e32 v48, v216, v48
	v_add_f32_e32 v48, v217, v48
	v_add_f32_e32 v48, v218, v48
	v_add_f32_e32 v48, v219, v48
	v_add_f32_e32 v48, v220, v48
	v_add_f32_e32 v48, v221, v48
	v_add_f32_e32 v48, v222, v48
	v_add_f32_e32 v48, v223, v48
	v_add_f32_e32 v48, v224, v48
	v_add_f32_e32 v48, v225, v48
	v_add_f32_e32 v48, v228, v48
	v_add_f32_e32 v48, v229, v48
	v_add_f32_e32 v48, v230, v48
	v_add_f32_e32 v48, v231, v48
	v_add_f32_e32 v48, v232, v48
	v_add_f32_e32 v48, v233, v48
	v_add_f32_e32 v48, v234, v48
	v_add_f32_e32 v48, v235, v48
	v_add_f32_e32 v48, v236, v48
	v_add_f32_e32 v48, v237, v48
	v_add_f32_e32 v48, v238, v48
	v_add_f32_e32 v48, v239, v48
	v_add_f32_e32 v48, v240, v48
	v_add_f32_e32 v48, v241, v48
	v_add_f32_e32 v48, v242, v48
	v_add_f32_e32 v48, v243, v48
	v_add_f32_e32 v48, v244, v48
	s_nop 0
	s_waitcnt lgkmcnt(0)
	v_mov_b32_e32 v49, v48
	s_nop 1
	v_permlane16_swap_b32_e32 v48, v49
	v_add_f32_e32 v48, v48, v49
	s_nop 0
	s_waitcnt lgkmcnt(0)
	v_mov_b32_e32 v49, v48
	s_nop 1
	v_permlane32_swap_b32_e32 v48, v49
	v_add_f32_e32 v48, v48, v49
	v_div_scale_f32 v49, s[6:7], v48, v48, 1.0
	v_rcp_f32_e32 v51, v49
	v_div_scale_f32 v50, vcc, 1.0, v48, 1.0
	v_fma_f32 v96, -v49, v51, 1.0
	v_fmac_f32_e32 v51, v96, v51
	v_mul_f32_e32 v96, v50, v51
	v_fma_f32 v97, -v49, v96, v50
	v_fmac_f32_e32 v96, v97, v51
	v_fma_f32 v49, -v49, v96, v50
	v_div_fmas_f32 v49, v49, v51, v96
	v_div_fixup_f32 v114, v49, v48, 1.0
	ds_read2_b64 v[48:51], v173 offset1:4
	ds_read2_b64 v[96:99], v145 offset0:32 offset1:36
	s_waitcnt lgkmcnt(1)
	v_mfma_f32_16x16x32_bf16 v[12:15], v[48:51], v[32:35], v[12:15]
	ds_read2_b64 v[48:51], v146 offset0:64 offset1:68
	s_waitcnt lgkmcnt(1)
	v_mfma_f32_16x16x32_bf16 v[16:19], v[96:99], v[32:35], v[16:19]
	ds_read2_b64 v[96:99], v139 offset1:4
	s_waitcnt lgkmcnt(1)
	v_mfma_f32_16x16x32_bf16 v[20:23], v[48:51], v[32:35], v[20:23]
	ds_read2_b64 v[48:51], v144 offset0:128 offset1:132
	s_waitcnt lgkmcnt(1)
	v_mfma_f32_16x16x32_bf16 v[24:27], v[96:99], v[32:35], v[24:27]
	ds_read2_b64 v[96:99], v142 offset0:160 offset1:164
	s_waitcnt lgkmcnt(1)
	v_mfma_f32_16x16x32_bf16 v[48:51], v[48:51], v[32:35], v[52:55]
	s_nop 2
	ds_read2_b64 v[52:55], v143 offset0:192 offset1:196
	s_waitcnt lgkmcnt(1)
	v_mfma_f32_16x16x32_bf16 v[40:43], v[96:99], v[32:35], v[40:43]
	ds_read2_b64 v[96:99], v138 offset1:4
	s_waitcnt lgkmcnt(1)
	v_mfma_f32_16x16x32_bf16 v[52:55], v[52:55], v[32:35], v[60:63]
	s_nop 2
	ds_read2_b64 v[60:63], v141 offset1:4
	s_waitcnt lgkmcnt(1)
	v_mfma_f32_16x16x32_bf16 v[56:59], v[96:99], v[32:35], v[56:59]
	ds_read2_b64 v[96:99], v140 offset0:32 offset1:36
	s_waitcnt lgkmcnt(1)
	v_mfma_f32_16x16x32_bf16 v[60:63], v[60:63], v[32:35], v[72:75]
	s_nop 2
	ds_read2_b64 v[72:75], v135 offset0:64 offset1:68
	s_waitcnt lgkmcnt(1)
	v_mfma_f32_16x16x32_bf16 v[76:79], v[96:99], v[32:35], v[76:79]
	ds_read2_b64 v[96:99], v137 offset1:4
	s_waitcnt lgkmcnt(1)
	v_mfma_f32_16x16x32_bf16 v[72:75], v[72:75], v[32:35], v[80:83]
	s_nop 2
	ds_read2_b64 v[80:83], v132 offset0:128 offset1:132
	s_waitcnt lgkmcnt(1)
	v_mfma_f32_16x16x32_bf16 v[84:87], v[96:99], v[32:35], v[84:87]
	ds_read2_b64 v[96:99], v133 offset0:160 offset1:164
	s_waitcnt lgkmcnt(1)
	v_mfma_f32_16x16x32_bf16 v[68:71], v[80:83], v[32:35], v[68:71]
	ds_read2_b64 v[80:83], v134 offset0:192 offset1:196
	s_waitcnt lgkmcnt(1)
	v_mfma_f32_16x16x32_bf16 v[28:31], v[96:99], v[32:35], v[28:31]
	ds_read2_b64 v[96:99], v136 offset1:4
	s_waitcnt lgkmcnt(1)
	v_mfma_f32_16x16x32_bf16 v[64:67], v[80:83], v[32:35], v[64:67]
	ds_read2_b64 v[80:83], v173 offset0:8 offset1:12
	s_waitcnt lgkmcnt(1)
	v_mfma_f32_16x16x32_bf16 v[32:35], v[96:99], v[32:35], v[36:39]
	s_nop 2
	ds_read2_b64 v[36:39], v145 offset0:40 offset1:44
	s_waitcnt lgkmcnt(1)
	v_mfma_f32_16x16x32_bf16 v[12:15], v[80:83], v[8:11], v[12:15]
	ds_read2_b64 v[80:83], v146 offset0:72 offset1:76
	s_waitcnt lgkmcnt(1)
	v_mfma_f32_16x16x32_bf16 v[16:19], v[36:39], v[8:11], v[16:19]
	ds_read2_b64 v[36:39], v139 offset0:8 offset1:12
	s_waitcnt lgkmcnt(1)
	v_mfma_f32_16x16x32_bf16 v[20:23], v[80:83], v[8:11], v[20:23]
	ds_read2_b64 v[80:83], v144 offset0:136 offset1:140
	s_waitcnt lgkmcnt(1)
	v_mfma_f32_16x16x32_bf16 v[24:27], v[36:39], v[8:11], v[24:27]
	ds_read2_b64 v[36:39], v142 offset0:168 offset1:172
	s_waitcnt lgkmcnt(1)
	v_mfma_f32_16x16x32_bf16 v[48:51], v[80:83], v[8:11], v[48:51]
	ds_read2_b64 v[80:83], v143 offset0:200 offset1:204
	s_waitcnt lgkmcnt(1)
	v_mfma_f32_16x16x32_bf16 v[36:39], v[36:39], v[8:11], v[40:43]
	s_nop 2
	ds_read2_b64 v[40:43], v138 offset0:8 offset1:12
	s_waitcnt lgkmcnt(1)
	v_mfma_f32_16x16x32_bf16 v[52:55], v[80:83], v[8:11], v[52:55]
	ds_read2_b64 v[80:83], v141 offset0:8 offset1:12
	s_waitcnt lgkmcnt(1)
	v_mfma_f32_16x16x32_bf16 v[40:43], v[40:43], v[8:11], v[56:59]
	s_nop 2
	ds_read2_b64 v[56:59], v140 offset0:40 offset1:44
	s_waitcnt lgkmcnt(1)
	v_mfma_f32_16x16x32_bf16 v[60:63], v[80:83], v[8:11], v[60:63]
	ds_read2_b64 v[80:83], v135 offset0:72 offset1:76
	s_waitcnt lgkmcnt(1)
	v_mfma_f32_16x16x32_bf16 v[56:59], v[56:59], v[8:11], v[76:79]
	s_nop 2
	ds_read2_b64 v[76:79], v137 offset0:8 offset1:12
	s_waitcnt lgkmcnt(1)
	v_mfma_f32_16x16x32_bf16 v[72:75], v[80:83], v[8:11], v[72:75]
	ds_read2_b64 v[80:83], v132 offset0:136 offset1:140
	ds_read2_b64 v[96:99], v133 offset0:168 offset1:172
	s_waitcnt lgkmcnt(2)
	v_mfma_f32_16x16x32_bf16 v[76:79], v[76:79], v[8:11], v[84:87]
	s_nop 2
	ds_read2_b64 v[84:87], v134 offset0:200 offset1:204
	ds_read2_b64 v[104:107], v136 offset0:8 offset1:12
	s_waitcnt vmcnt(3)
	ds_write_b128 v184, v[44:47] offset:36864
	s_waitcnt vmcnt(2)
	ds_write_b128 v176, v[88:91] offset:36864
	s_waitcnt vmcnt(1)
	ds_write_b128 v177, v[100:103] offset:36864
	s_waitcnt vmcnt(0)
	ds_write_b128 v178, v[92:95] offset:36864
	s_waitcnt lgkmcnt(7)
	v_mfma_f32_16x16x32_bf16 v[44:47], v[80:83], v[8:11], v[68:71]
	s_waitcnt lgkmcnt(0)
	s_barrier
; #define LAS __attribute__((address_space(3)))
; __device__ __forceinline__ unsigned pk2(float lo, float hi) { f32x2_t v = {lo, hi}; bf16x2_t b = __builtin_convertvector(v, bf16x2_t); return __builtin_bit_cast(unsigned, b); }
; __device__ __forceinline__ f32x4 mfma16(bf16x8 a, bf16x8 b, f32x4 c) { return __builtin_amdgcn_mfma_f32_16x16x32_bf16(a, b, c, 0, 0, 0); }
; __device__ __forceinline__ void xattn_unit(const Args& a, LAS unsigned char* lds, int b, int h, int qb, int tid, int wave, int lane) {
;     ...
;             const int mt = j - 4;
; #pragma unroll
;             for (int dt = 0; dt < 16; ++dt) {
;                 const LAS bf16* vr = base + (16 * dt + fr) * VS + 4 * fq;
;                 O[dt] = mfma16(cat8(*(const LAS u32x2*)vr, *(const LAS u32x2*)(vr + 16)), pf[2 * mt], O[dt]);
;                 O[dt] = mfma16(cat8(*(const LAS u32x2*)(vr + 32), *(const LAS u32x2*)(vr + 48)), pf[2 * mt + 1], O[dt]);
;             }
;         }
;         if (j < 7) lstore(j + 1);
;         __syncthreads();
;     }
;     const float il = 1.f / l;
; #pragma unroll
;     for (int dt = 0; dt < 16; ++dt) { u32x2 w; w.x = pk2(O[dt][0] * il, O[dt][1] * il); w.y = pk2(O[dt][2] * il, O[dt][3] * il);
	v_mfma_f32_16x16x32_bf16 v[28:31], v[96:99], v[8:11], v[28:31]
	ds_read2_b64 v[68:71], v131 offset1:4
	v_mfma_f32_16x16x32_bf16 v[64:67], v[84:87], v[8:11], v[64:67]
	v_mfma_f32_16x16x32_bf16 v[8:11], v[104:107], v[8:11], v[32:35]
	s_nop 2
	ds_read2_b64 v[32:35], v129 offset0:32 offset1:36
	s_waitcnt lgkmcnt(1)
	v_mfma_f32_16x16x32_bf16 v[12:15], v[68:71], v[4:7], v[12:15]
	ds_read2_b64 v[68:71], v130 offset0:64 offset1:68
	s_waitcnt lgkmcnt(1)
	v_mfma_f32_16x16x32_bf16 v[16:19], v[32:35], v[4:7], v[16:19]
	ds_read2_b64 v[32:35], v128 offset1:4
	s_waitcnt lgkmcnt(1)
	v_mfma_f32_16x16x32_bf16 v[20:23], v[68:71], v[4:7], v[20:23]
	ds_read2_b64 v[68:71], v126 offset0:128 offset1:132
	s_waitcnt lgkmcnt(1)
	v_mfma_f32_16x16x32_bf16 v[24:27], v[32:35], v[4:7], v[24:27]
	ds_read2_b64 v[32:35], v127 offset0:160 offset1:164
	s_waitcnt lgkmcnt(1)
	v_mfma_f32_16x16x32_bf16 v[48:51], v[68:71], v[4:7], v[48:51]
	ds_read2_b64 v[68:71], v125 offset0:192 offset1:196
	s_waitcnt lgkmcnt(1)
	v_mfma_f32_16x16x32_bf16 v[32:35], v[32:35], v[4:7], v[36:39]
	s_nop 2
	ds_read2_b64 v[36:39], v124 offset1:4
	s_waitcnt lgkmcnt(1)
	v_mfma_f32_16x16x32_bf16 v[52:55], v[68:71], v[4:7], v[52:55]
	ds_read2_b64 v[68:71], v119 offset1:4
	s_waitcnt lgkmcnt(1)
	v_mfma_f32_16x16x32_bf16 v[36:39], v[36:39], v[4:7], v[40:43]
	s_nop 2
	ds_read2_b64 v[40:43], v118 offset0:32 offset1:36
	s_waitcnt lgkmcnt(1)
	v_mfma_f32_16x16x32_bf16 v[60:63], v[68:71], v[4:7], v[60:63]
	ds_read2_b64 v[68:71], v116 offset0:64 offset1:68
	s_waitcnt lgkmcnt(1)
	v_mfma_f32_16x16x32_bf16 v[40:43], v[40:43], v[4:7], v[56:59]
	s_nop 2
	ds_read2_b64 v[56:59], v117 offset1:4
	s_waitcnt lgkmcnt(1)
	v_mfma_f32_16x16x32_bf16 v[68:71], v[68:71], v[4:7], v[72:75]
	s_nop 2
	ds_read2_b64 v[72:75], v111 offset0:128 offset1:132
	s_waitcnt lgkmcnt(1)
	v_mfma_f32_16x16x32_bf16 v[56:59], v[56:59], v[4:7], v[76:79]
	s_nop 2
	ds_read2_b64 v[76:79], v113 offset0:160 offset1:164
	s_waitcnt lgkmcnt(1)
	v_mfma_f32_16x16x32_bf16 v[44:47], v[72:75], v[4:7], v[44:47]
	ds_read2_b64 v[72:75], v112 offset0:192 offset1:196
	s_waitcnt lgkmcnt(1)
	v_mfma_f32_16x16x32_bf16 v[28:31], v[76:79], v[4:7], v[28:31]
	ds_read2_b64 v[76:79], v110 offset1:4
	s_waitcnt lgkmcnt(1)
	v_mfma_f32_16x16x32_bf16 v[64:67], v[72:75], v[4:7], v[64:67]
	ds_read2_b64 v[72:75], v131 offset0:8 offset1:12
	s_waitcnt lgkmcnt(1)
	v_mfma_f32_16x16x32_bf16 v[4:7], v[76:79], v[4:7], v[8:11]
	s_nop 2
	ds_read2_b64 v[8:11], v129 offset0:40 offset1:44
	s_waitcnt lgkmcnt(1)
	v_mfma_f32_16x16x32_bf16 v[12:15], v[72:75], v[0:3], v[12:15]
	ds_read2_b64 v[72:75], v130 offset0:72 offset1:76
	s_waitcnt lgkmcnt(1)
	v_mfma_f32_16x16x32_bf16 v[8:11], v[8:11], v[0:3], v[16:19]
	s_nop 2
	ds_read2_b64 v[16:19], v128 offset0:8 offset1:12
	s_waitcnt lgkmcnt(1)
	v_mfma_f32_16x16x32_bf16 v[20:23], v[72:75], v[0:3], v[20:23]
	ds_read2_b64 v[72:75], v126 offset0:136 offset1:140
	s_nop 0
	v_pk_mul_f32 v[8:9], v[114:115], v[8:9] op_sel_hi:[0,1]
	v_pk_mul_f32 v[10:11], v[114:115], v[10:11] op_sel_hi:[0,1]
	s_waitcnt lgkmcnt(1)
	v_mfma_f32_16x16x32_bf16 v[16:19], v[16:19], v[0:3], v[24:27]
	s_nop 2
	ds_read2_b64 v[24:27], v127 offset0:168 offset1:172
	s_waitcnt lgkmcnt(1)
	v_mfma_f32_16x16x32_bf16 v[48:51], v[72:75], v[0:3], v[48:51]
	ds_read2_b64 v[72:75], v125 offset0:200 offset1:204
	s_nop 0
	v_pk_mul_f32 v[16:17], v[114:115], v[16:17] op_sel_hi:[0,1]
	v_pk_mul_f32 v[18:19], v[114:115], v[18:19] op_sel_hi:[0,1]
	s_waitcnt lgkmcnt(1)
	v_mfma_f32_16x16x32_bf16 v[24:27], v[24:27], v[0:3], v[32:35]
	s_nop 2
	ds_read2_b64 v[32:35], v124 offset0:8 offset1:12
	s_waitcnt lgkmcnt(1)
	v_mfma_f32_16x16x32_bf16 v[52:55], v[72:75], v[0:3], v[52:55]
	ds_read2_b64 v[72:75], v119 offset0:8 offset1:12
	s_nop 0
	v_pk_mul_f32 v[24:25], v[114:115], v[24:25] op_sel_hi:[0,1]
	v_pk_mul_f32 v[26:27], v[114:115], v[26:27] op_sel_hi:[0,1]
	s_waitcnt lgkmcnt(1)
	v_mfma_f32_16x16x32_bf16 v[32:35], v[32:35], v[0:3], v[36:39]
	s_nop 2
	ds_read2_b64 v[36:39], v118 offset0:40 offset1:44
	s_waitcnt lgkmcnt(1)
	v_mfma_f32_16x16x32_bf16 v[60:63], v[72:75], v[0:3], v[60:63]
	ds_read2_b64 v[72:75], v116 offset0:72 offset1:76
	s_nop 0
	v_pk_mul_f32 v[32:33], v[114:115], v[32:33] op_sel_hi:[0,1]
	v_pk_mul_f32 v[34:35], v[114:115], v[34:35] op_sel_hi:[0,1]
	s_waitcnt lgkmcnt(1)
	v_mfma_f32_16x16x32_bf16 v[36:39], v[36:39], v[0:3], v[40:43]
	s_nop 2
	ds_read2_b64 v[40:43], v117 offset0:8 offset1:12
	s_waitcnt lgkmcnt(1)
	v_mfma_f32_16x16x32_bf16 v[68:71], v[72:75], v[0:3], v[68:71]
	ds_read2_b64 v[72:75], v111 offset0:136 offset1:140
	s_nop 0
	v_pk_mul_f32 v[36:37], v[114:115], v[36:37] op_sel_hi:[0,1]
	v_pk_mul_f32 v[38:39], v[114:115], v[38:39] op_sel_hi:[0,1]
	s_waitcnt lgkmcnt(1)
	v_mfma_f32_16x16x32_bf16 v[40:43], v[40:43], v[0:3], v[56:59]
	s_nop 2
	ds_read2_b64 v[56:59], v113 offset0:168 offset1:172
	s_waitcnt lgkmcnt(1)
	v_mfma_f32_16x16x32_bf16 v[44:47], v[72:75], v[0:3], v[44:47]
	ds_read2_b64 v[72:75], v112 offset0:200 offset1:204
	s_nop 0
	v_pk_mul_f32 v[40:41], v[114:115], v[40:41] op_sel_hi:[0,1]
	v_pk_mul_f32 v[42:43], v[114:115], v[42:43] op_sel_hi:[0,1]
	s_waitcnt lgkmcnt(1)
	v_mfma_f32_16x16x32_bf16 v[28:31], v[56:59], v[0:3], v[28:31]
	ds_read2_b64 v[56:59], v110 offset0:8 offset1:12
	s_nop 0
	v_pk_mul_f32 v[44:45], v[114:115], v[44:45] op_sel_hi:[0,1]
	v_pk_mul_f32 v[46:47], v[114:115], v[46:47] op_sel_hi:[0,1]
	s_waitcnt lgkmcnt(1)
	v_mfma_f32_16x16x32_bf16 v[64:67], v[72:75], v[0:3], v[64:67]
	s_nop 1
	v_mul_f32_e64 v28, v114, v28
	v_mul_f32_e64 v29, v114, v29
	v_pk_mul_f32 v[30:31], v[114:115], v[30:31] op_sel_hi:[0,1]
	s_waitcnt lgkmcnt(0)
	v_mfma_f32_16x16x32_bf16 v[0:3], v[56:59], v[0:3], v[4:7]
	v_mul_f32_e64 v56, v114, v68
	v_mul_f32_e64 v57, v114, v69
	s_nop 0
	v_pk_mul_f32 v[4:5], v[114:115], v[12:13] op_sel_hi:[0,1]
	v_pk_mul_f32 v[6:7], v[114:115], v[14:15] op_sel_hi:[0,1]
	v_pk_mul_f32 v[12:13], v[114:115], v[20:21] op_sel_hi:[0,1]
	v_pk_mul_f32 v[14:15], v[114:115], v[22:23] op_sel_hi:[0,1]
	v_pk_mul_f32 v[20:21], v[114:115], v[48:49] op_sel_hi:[0,1]
	v_pk_mul_f32 v[22:23], v[114:115], v[50:51] op_sel_hi:[0,1]
	v_pk_mul_f32 v[48:49], v[114:115], v[52:53] op_sel_hi:[0,1]
	v_pk_mul_f32 v[50:51], v[114:115], v[54:55] op_sel_hi:[0,1]
	v_pk_mul_f32 v[52:53], v[114:115], v[60:61] op_sel_hi:[0,1]
	v_pk_mul_f32 v[54:55], v[114:115], v[62:63] op_sel_hi:[0,1]
	v_pk_mul_f32 v[58:59], v[114:115], v[70:71] op_sel_hi:[0,1]
	v_pk_mul_f32 v[60:61], v[114:115], v[64:65] op_sel_hi:[0,1]
	v_pk_mul_f32 v[62:63], v[114:115], v[66:67] op_sel_hi:[0,1]
	v_pk_mul_f32 v[0:1], v[114:115], v[0:1] op_sel_hi:[0,1]
	v_pk_mul_f32 v[2:3], v[114:115], v[2:3] op_sel_hi:[0,1]
	v_cvt_pk_bf16_f32 v4, v4, v5
	v_cvt_pk_bf16_f32 v5, v6, v7
	s_barrier
; #define GAS __attribute__((address_space(1)))
; __device__ __forceinline__ unsigned pk2(float lo, float hi) { f32x2_t v = {lo, hi}; bf16x2_t b = __builtin_convertvector(v, bf16x2_t); return __builtin_bit_cast(unsigned, b); }
; __device__ __forceinline__ void xattn_unit(const Args& a, LAS unsigned char* lds, int b, int h, int qb, int tid, int wave, int lane) {
;     ...
;     const float il = 1.f / l;
; #pragma unroll
;     for (int dt = 0; dt < 16; ++dt) { u32x2 w; w.x = pk2(O[dt][0] * il, O[dt][1] * il); w.y = pk2(O[dt][2] * il, O[dt][3] * il);
;         *(GAS u32x2*)(XO + qrow * DM + h * 256 + 16 * dt + 4 * fq) = w; }
	v_cvt_pk_bf16_f32 v6, v8, v9
	v_cvt_pk_bf16_f32 v7, v10, v11
	v_cvt_pk_bf16_f32 v8, v12, v13
	v_cvt_pk_bf16_f32 v9, v14, v15
	v_cvt_pk_bf16_f32 v10, v16, v17
	v_cvt_pk_bf16_f32 v11, v18, v19
	v_cvt_pk_bf16_f32 v12, v20, v21
	v_cvt_pk_bf16_f32 v13, v22, v23
	v_cvt_pk_bf16_f32 v14, v24, v25
	v_cvt_pk_bf16_f32 v15, v26, v27
	v_cvt_pk_bf16_f32 v16, v48, v49
	v_cvt_pk_bf16_f32 v17, v50, v51
	v_cvt_pk_bf16_f32 v18, v32, v33
	v_cvt_pk_bf16_f32 v19, v34, v35
	v_cvt_pk_bf16_f32 v20, v52, v53
	v_cvt_pk_bf16_f32 v21, v54, v55
	v_cvt_pk_bf16_f32 v22, v36, v37
	v_cvt_pk_bf16_f32 v23, v38, v39
	v_cvt_pk_bf16_f32 v24, v56, v57
	v_cvt_pk_bf16_f32 v25, v58, v59
	v_cvt_pk_bf16_f32 v26, v40, v41
	v_cvt_pk_bf16_f32 v27, v42, v43
	v_cvt_pk_bf16_f32 v36, v44, v45
	v_cvt_pk_bf16_f32 v37, v46, v47
	v_cvt_pk_bf16_f32 v38, v28, v29
	v_cvt_pk_bf16_f32 v39, v30, v31
	v_cvt_pk_bf16_f32 v40, v60, v61
	v_cvt_pk_bf16_f32 v41, v62, v63
	v_cvt_pk_bf16_f32 v42, v0, v1
	v_cvt_pk_bf16_f32 v43, v2, v3
	v_bfe_u32 v44, v252, 4, 1
	v_mul_u32_u24_e32 v44, 24, v44
	v_mov_b32_e32 v45, 0
	v_lshl_add_u64 v[44:45], v[108:109], 0, v[44:45]
	v_permlane16_swap_b32_e32 v4, v6
	v_permlane16_swap_b32_e32 v5, v7
	v_permlane16_swap_b32_e32 v8, v10
	v_permlane16_swap_b32_e32 v9, v11
	v_permlane16_swap_b32_e32 v12, v14
	v_permlane16_swap_b32_e32 v13, v15
	v_permlane16_swap_b32_e32 v16, v18
	v_permlane16_swap_b32_e32 v17, v19
	v_permlane16_swap_b32_e32 v20, v22
	v_permlane16_swap_b32_e32 v21, v23
	v_permlane16_swap_b32_e32 v24, v26
	v_permlane16_swap_b32_e32 v25, v27
	v_permlane16_swap_b32_e32 v36, v38
	v_permlane16_swap_b32_e32 v37, v39
	v_permlane16_swap_b32_e32 v40, v42
	v_permlane16_swap_b32_e32 v41, v43
	global_store_dwordx4 v[44:45], v[4:7], off
	global_store_dwordx4 v[44:45], v[8:11], off offset:64
	global_store_dwordx4 v[44:45], v[12:15], off offset:128
	global_store_dwordx4 v[44:45], v[16:19], off offset:192
	global_store_dwordx4 v[44:45], v[20:23], off offset:256
	global_store_dwordx4 v[44:45], v[24:27], off offset:320
	global_store_dwordx4 v[44:45], v[36:39], off offset:384
	global_store_dwordx4 v[44:45], v[40:43], off offset:448
	s_cbranch_scc1 .LBB0_1513

; __device__ __forceinline__ void xattn_unit(const Args& a, LAS unsigned char* lds, int b, int h, int qb, int tid, int wave, int lane) {
;     ...
;     const int fr = lane & 15, fq = lane >> 4; const size_t qrow = (size_t)b * SEQ + qb * 128 + 16 * wave + fr;
;     bf16x8 qf[8];
; #pragma unroll
;     for (int kk = 0; kk < 8; ++kk) qf[kk] = *(const GAS bf16x8*)(QX + qrow * DM + h * 256 + 32 * kk + 8 * fq);
;     u32x4 rr[2][4];
;     const unsigned vok = (unsigned)((tid >> 5) * DM + 8 * (tid & 31)) * 2u, vov = (unsigned)((tid >> 3) * MEMR + 8 * (tid & 7)) * 2u;
;     const GAS char* kxb = (const GAS char*)KX + ((size_t)b * 256 * DM + h * 256) * 2; const GAS char* vxb = (const GAS char*)VTX + ((size_t)h * 256 * MEMR + b * 256) * 2;
;     auto gload = [&](int j) {
;         if (j < 4) { const GAS char* p_ = kxb + (size_t)j * (64 * DM * 2);
; #pragma unroll
;             for (int i = 0; i < 4; ++i) rr[j & 1][i] = *(const GAS u32x4*)(p_ + (size_t)(vok + (unsigned)(i * 16 * DM * 2)));
;         } else { const GAS char* p_ = vxb + (size_t)(j - 4) * 128;
; #pragma unroll
;             for (int i = 0; i < 4; ++i) rr[j & 1][i] = *(const GAS u32x4*)(p_ + (size_t)(vov + (unsigned)(i * 64 * MEMR * 2)));
;         }
;     };
;     auto lstore = [&](int j) {
;         LAS bf16* base = (LAS bf16*)(lds + (j & 1) * STG);
;         if (j < 4) {
; #pragma unroll
;             for (int i = 0; i < 4; ++i) { const int id = tid + 512 * i; *(LAS u32x4*)(base + (id >> 5) * KS + 8 * (id & 31)) = rr[j & 1][i]; }
;         } else {
; #pragma unroll
;             for (int i = 0; i < 4; ++i) { const int id = tid + 512 * i; *(LAS u32x4*)(base + (id >> 3) * VS + 8 * (id & 7)) = rr[j & 1][i]; }
;         }
;     };
;     f32x4 S[16]; bf16x8 pf[8]; f32x4 O[16]; float l = 0.f;
; #pragma unroll
;     for (int i = 0; i < 16; ++i) { S[i] = (f32x4){0.f, 0.f, 0.f, 0.f}; O[i] = (f32x4){0.f, 0.f, 0.f, 0.f}; }
;     gload(0); gload(1); lstore(0); __syncthreads();
; #pragma unroll
;     for (int j = 0; j < 8; ++j) {
;         if (j < 6) gload(j + 2);
;         const LAS bf16* base = (const LAS bf16*)(lds + (j & 1) * STG);
;         if (j < 4) {
; #pragma unroll
;             for (int rt = 0; rt < 4; ++rt)
; #pragma unroll
;                 for (int kk = 0; kk < 8; ++kk) S[4 * j + rt] = mfma16(*(const LAS bf16x8*)(base + (16 * rt + fr) * KS + 32 * kk + 8 * fq), qf[kk], S[4 * j + rt]);
.LBB0_1518:
	s_ashr_i32 s0, s10, 4
	s_and_b32 s6, s17, 0x780
	s_add_i32 s7, s0, s12
	v_mov_b32_e32 v200, v252
	s_and_b32 s23, s0, 3
	s_add_i32 s0, s6, s70
	s_ashr_i32 s6, s7, 2
	s_ashr_i32 s7, s6, 31
	v_lshlrev_b32_e32 v192, 4, v200
	v_add_u32_e32 v216, 0x200, v200
	v_lshlrev_b32_e32 v2, 6, v200
	v_and_b32_e32 v4, 0x1f0, v192
	v_ashrrev_i32_e32 v5, 5, v216
	s_lshl_b64 s[8:9], s[6:7], 11
	v_and_b32_e32 v213, 15, v200
	v_and_or_b32 v193, v2, s18, v4
	v_mul_lo_u32 v2, v5, s20
	s_add_u32 s0, s8, s0
	v_add3_u32 v212, 0, v2, v4
	s_addc_u32 s24, s9, 0
	v_or_b32_e32 v2, s0, v213
	s_lshl_b32 s0, s23, 9
	s_lshl_b64 s[8:9], s[6:7], 19
	v_ashrrev_i32_e32 v3, 5, v200
	v_add_u32_e32 v217, 0x400, v200
	s_add_u32 s8, s13, s8
	v_mul_lo_u32 v3, v3, s20
	v_ashrrev_i32_e32 v6, 5, v217
	s_addc_u32 s9, s14, s9
	s_lshl_b32 s6, s6, 8
	v_add3_u32 v211, 0, v3, v4
	v_mul_lo_u32 v3, v6, s20
	s_lshl_b32 s7, s23, 20
	s_ashr_i32 s23, s6, 31
	v_add3_u32 v224, 0, v3, v4
	v_mov_b32_e32 v3, s24
	s_add_u32 s6, s6, s7
	v_lshlrev_b64 v[202:203], 11, v[2:3]
	s_addc_u32 s7, s23, 0
	v_add_u32_e32 v218, 0x600, v200
	v_lshl_add_u64 v[2:3], s[2:3], 0, v[202:203]
	s_lshl_b64 s[6:7], s[6:7], 1
	v_mov_b32_e32 v1, v201
	v_and_b32_e32 v214, 63, v200
	v_and_b32_e32 v0, 48, v200
	v_ashrrev_i32_e32 v7, 5, v218
	v_lshl_add_u64 v[2:3], v[2:3], 0, s[0:1]
	s_add_u32 s8, s8, s0
	v_add_u32_e32 v8, 0, v0
	v_or_b32_e32 v215, 48, v214
	v_mul_lo_u32 v5, v7, s20
	v_lshl_add_u64 v[12:13], v[2:3], 0, v[0:1]
	s_addc_u32 s9, s9, 0
	v_mad_u32_u24 v210, v213, s20, v8
	v_mad_u32_u24 v209, v215, s20, v8
	v_add_u32_e32 v194, 0x8000, v193
	v_add_u32_e32 v195, 0x10000, v193
	v_add_u32_e32 v196, 0x18000, v193
	v_add3_u32 v225, 0, v5, v4
	global_load_dwordx4 v[156:159], v[12:13], off
	global_load_dwordx4 v[120:123], v[12:13], off offset:64
	global_load_dwordx4 v[112:115], v[12:13], off offset:128
	global_load_dwordx4 v[104:107], v[12:13], off offset:192
	global_load_dwordx4 v[28:31], v[12:13], off offset:256
	global_load_dwordx4 v[8:11], v[12:13], off offset:320
	global_load_dwordx4 v[4:7], v[12:13], off offset:384
	global_load_dwordx4 v[0:3], v[12:13], off offset:448
	s_nop 0
	global_load_dwordx4 v[12:15], v193, s[8:9]
	global_load_dwordx4 v[16:19], v194, s[8:9]
	global_load_dwordx4 v[20:23], v195, s[8:9]
	global_load_dwordx4 v[24:27], v196, s[8:9]
	s_add_u32 s6, s15, s6
	s_addc_u32 s7, s16, s7
	s_add_u32 s24, s8, 0x20000
	s_addc_u32 s25, s9, 0
	global_load_dwordx4 v[32:35], v193, s[24:25]
	global_load_dwordx4 v[36:39], v194, s[24:25]
	global_load_dwordx4 v[40:43], v195, s[24:25]
	global_load_dwordx4 v[44:47], v196, s[24:25]
	s_add_u32 s24, s8, 0x40000
	s_addc_u32 s25, s9, 0
	s_add_u32 s8, s8, 0x60000
	s_addc_u32 s9, s9, 0
	v_and_b32_e32 v219, 0x70, v192
	v_lshrrev_b32_e32 v216, 3, v216
	v_cmp_lt_i32_e32 vcc, v227, v226
	s_add_i32 s10, s10, 1
	s_addk_i32 s17, 0x80
	s_cmp_ge_i32 s10, s11
	s_waitcnt vmcnt(0)
	ds_write_b128 v211, v[12:15]
	ds_write_b128 v212, v[16:19]
	ds_write_b128 v224, v[20:23]
	ds_write_b128 v225, v[24:27]
	s_waitcnt lgkmcnt(0)
	s_barrier
	global_load_dwordx4 v[12:15], v193, s[24:25]
	global_load_dwordx4 v[16:19], v194, s[24:25]
	global_load_dwordx4 v[20:23], v195, s[24:25]
	global_load_dwordx4 v[24:27], v196, s[24:25]
	ds_read_b128 v[48:51], v210
	ds_read_b128 v[52:55], v210 offset:64
	ds_read_b128 v[56:59], v210 offset:128
	ds_read_b128 v[60:63], v210 offset:192
	ds_read_b128 v[64:67], v210 offset:256
	ds_read_b128 v[68:71], v210 offset:320
	ds_read_b128 v[72:75], v210 offset:384
	ds_read_b128 v[76:79], v210 offset:448
	ds_read_b128 v[80:83], v210 offset:8448
	ds_read_b128 v[84:87], v210 offset:8512
	ds_read_b128 v[88:91], v210 offset:8576
	ds_read_b128 v[92:95], v210 offset:8640
	ds_read_b128 v[96:99], v210 offset:8704
	ds_read_b128 v[100:103], v210 offset:8768
	ds_read_b128 v[108:111], v210 offset:8832
	ds_read_b128 v[116:119], v210 offset:8896
	ds_read_b128 v[124:127], v210 offset:16896
	ds_read_b128 v[128:131], v210 offset:16960
	s_waitcnt lgkmcnt(14)
	v_mfma_f32_16x16x32_bf16 v[48:51], v[48:51], v[156:159], 0
	ds_read_b128 v[132:135], v210 offset:17024
	ds_read_b128 v[136:139], v210 offset:17088
	ds_read_b128 v[140:143], v209
	ds_read_b128 v[144:147], v210 offset:17152
	ds_read_b128 v[148:151], v210 offset:17216
	ds_read_b128 v[152:155], v210 offset:17280
	ds_read_b128 v[160:163], v210 offset:17344
	ds_read_b128 v[164:167], v209 offset:64
	ds_read_b128 v[168:171], v209 offset:128
	s_waitcnt lgkmcnt(14)
	v_mfma_f32_16x16x32_bf16 v[80:83], v[80:83], v[156:159], 0
	ds_read_b128 v[172:175], v209 offset:192
	ds_read_b128 v[176:179], v209 offset:256
	ds_read_b128 v[180:183], v209 offset:320
	s_waitcnt lgkmcnt(13)
	v_mfma_f32_16x16x32_bf16 v[124:127], v[124:127], v[156:159], 0
	v_mfma_f32_16x16x32_bf16 v[48:51], v[52:55], v[120:123], v[48:51]
	ds_read_b128 v[52:55], v209 offset:384
	ds_read_b128 v[184:187], v209 offset:448
	ds_write_b128 v211, v[32:35] offset:36864
	ds_write_b128 v212, v[36:39] offset:36864
	ds_write_b128 v224, v[40:43] offset:36864
	ds_write_b128 v225, v[44:47] offset:36864
	v_mfma_f32_16x16x32_bf16 v[32:35], v[84:87], v[120:123], v[80:83]
	s_waitcnt lgkmcnt(0)
	s_barrier
; #define LAS __attribute__((address_space(3)))
; __device__ __forceinline__ f32x4 mfma16(bf16x8 a, bf16x8 b, f32x4 c) { return __builtin_amdgcn_mfma_f32_16x16x32_bf16(a, b, c, 0, 0, 0); }
; __device__ __forceinline__ void xattn_unit(const Args& a, LAS unsigned char* lds, int b, int h, int qb, int tid, int wave, int lane) {
;     ...
;     for (int j = 0; j < 8; ++j) {
;         if (j < 6) gload(j + 2);
;         const LAS bf16* base = (const LAS bf16*)(lds + (j & 1) * STG);
;         if (j < 4) {
; #pragma unroll
;             for (int rt = 0; rt < 4; ++rt)
; #pragma unroll
;                 for (int kk = 0; kk < 8; ++kk) S[4 * j + rt] = mfma16(*(const LAS bf16x8*)(base + (16 * rt + fr) * KS + 32 * kk + 8 * fq), qf[kk], S[4 * j + rt]);
	ds_read_b128 v[44:47], v210 offset:36864
	ds_read_b128 v[80:83], v210 offset:36928
	v_mfma_f32_16x16x32_bf16 v[140:143], v[140:143], v[156:159], 0
	v_mfma_f32_16x16x32_bf16 v[36:39], v[128:131], v[120:123], v[124:127]
	ds_read_b128 v[84:87], v210 offset:45312
	s_nop 1
	ds_read_b128 v[124:127], v210 offset:45376
	s_waitcnt lgkmcnt(3)
	v_mfma_f32_16x16x32_bf16 v[44:47], v[44:47], v[156:159], 0
	v_mfma_f32_16x16x32_bf16 v[48:51], v[56:59], v[112:115], v[48:51]
	v_mfma_f32_16x16x32_bf16 v[40:43], v[164:167], v[120:123], v[140:143]
	ds_read_b128 v[128:131], v210 offset:53760
	s_nop 1
	ds_read_b128 v[140:143], v210 offset:53824
	ds_read_b128 v[164:167], v209 offset:36864
	ds_read_b128 v[188:191], v209 offset:36928
	s_waitcnt lgkmcnt(5)
	v_mfma_f32_16x16x32_bf16 v[84:87], v[84:87], v[156:159], 0
	v_mfma_f32_16x16x32_bf16 v[32:35], v[88:91], v[112:115], v[32:35]
	v_mfma_f32_16x16x32_bf16 v[44:47], v[80:83], v[120:123], v[44:47]
	v_mfma_f32_16x16x32_bf16 v[48:51], v[60:63], v[104:107], v[48:51]
	ds_read_b128 v[60:63], v210 offset:36992
	ds_read_b128 v[88:91], v210 offset:37056
	s_waitcnt lgkmcnt(5)
	v_mfma_f32_16x16x32_bf16 v[128:131], v[128:131], v[156:159], 0
	v_mfma_f32_16x16x32_bf16 v[56:59], v[124:127], v[120:123], v[84:87]
	v_mfma_f32_16x16x32_bf16 v[32:35], v[92:95], v[104:107], v[32:35]
	s_waitcnt lgkmcnt(1)
	v_mfma_f32_16x16x32_bf16 v[44:47], v[60:63], v[112:115], v[44:47]
	ds_read_b128 v[60:63], v210 offset:45440
	ds_read_b128 v[92:95], v210 offset:45504
	v_mfma_f32_16x16x32_bf16 v[164:167], v[164:167], v[156:159], 0
	v_mfma_f32_16x16x32_bf16 v[80:83], v[140:143], v[120:123], v[128:131]
	s_waitcnt lgkmcnt(1)
	v_mfma_f32_16x16x32_bf16 v[56:59], v[60:63], v[112:115], v[56:59]
	ds_read_b128 v[60:63], v210 offset:53888
	ds_read_b128 v[124:127], v210 offset:53952
	v_mfma_f32_16x16x32_bf16 v[84:87], v[188:191], v[120:123], v[164:167]
	s_waitcnt lgkmcnt(1)
	v_mfma_f32_16x16x32_bf16 v[60:63], v[60:63], v[112:115], v[80:83]
	s_nop 2
	ds_read_b128 v[80:83], v209 offset:36992
	ds_read_b128 v[128:131], v209 offset:37056
	v_mfma_f32_16x16x32_bf16 v[40:43], v[168:171], v[112:115], v[40:43]
	s_waitcnt lgkmcnt(1)
	v_mfma_f32_16x16x32_bf16 v[80:83], v[80:83], v[112:115], v[84:87]
	v_mfma_f32_16x16x32_bf16 v[48:51], v[64:67], v[28:31], v[48:51]
	v_mfma_f32_16x16x32_bf16 v[40:43], v[172:175], v[104:107], v[40:43]
	v_mfma_f32_16x16x32_bf16 v[44:47], v[88:91], v[104:107], v[44:47]
	s_waitcnt lgkmcnt(0)
	v_mfma_f32_16x16x32_bf16 v[64:67], v[128:131], v[104:107], v[80:83]
	v_mfma_f32_16x16x32_bf16 v[48:51], v[68:71], v[8:11], v[48:51]
	ds_read_b128 v[68:71], v210 offset:37120
	s_nop 0
	ds_read_b128 v[80:83], v210 offset:37184
	v_mfma_f32_16x16x32_bf16 v[32:35], v[96:99], v[28:31], v[32:35]
	v_mfma_f32_16x16x32_bf16 v[40:43], v[176:179], v[28:31], v[40:43]
	v_mfma_f32_16x16x32_bf16 v[56:59], v[92:95], v[104:107], v[56:59]
	s_waitcnt lgkmcnt(1)
	v_mfma_f32_16x16x32_bf16 v[44:47], v[68:71], v[28:31], v[44:47]
	ds_read_b128 v[68:71], v210 offset:45568
	ds_read_b128 v[84:87], v210 offset:45632
	v_mfma_f32_16x16x32_bf16 v[36:39], v[132:135], v[112:115], v[36:39]
	v_mfma_f32_16x16x32_bf16 v[60:63], v[124:127], v[104:107], v[60:63]
	v_mfma_f32_16x16x32_bf16 v[32:35], v[100:103], v[8:11], v[32:35]
	v_mfma_f32_16x16x32_bf16 v[40:43], v[180:183], v[8:11], v[40:43]
	s_waitcnt lgkmcnt(1)
	v_mfma_f32_16x16x32_bf16 v[56:59], v[68:71], v[28:31], v[56:59]
	ds_read_b128 v[68:71], v210 offset:54016
	ds_read_b128 v[88:91], v210 offset:54080
	v_mfma_f32_16x16x32_bf16 v[36:39], v[136:139], v[104:107], v[36:39]
	s_waitcnt lgkmcnt(1)
	v_mfma_f32_16x16x32_bf16 v[60:63], v[68:71], v[28:31], v[60:63]
	ds_read_b128 v[68:71], v209 offset:37120
	ds_read_b128 v[92:95], v209 offset:37184
	v_mfma_f32_16x16x32_bf16 v[48:51], v[72:75], v[4:7], v[48:51]
	v_mfma_f32_16x16x32_bf16 v[32:35], v[108:111], v[4:7], v[32:35]
	v_mfma_f32_16x16x32_bf16 v[52:55], v[52:55], v[4:7], v[40:43]
	v_mfma_f32_16x16x32_bf16 v[36:39], v[144:147], v[28:31], v[36:39]
	s_waitcnt lgkmcnt(1)
	v_mfma_f32_16x16x32_bf16 v[64:67], v[68:71], v[28:31], v[64:67]
	v_mfma_f32_16x16x32_bf16 v[68:71], v[80:83], v[8:11], v[44:47]
	v_mfma_f32_16x16x32_bf16 v[44:47], v[76:79], v[0:3], v[48:51]
	v_mfma_f32_16x16x32_bf16 v[40:43], v[116:119], v[0:3], v[32:35]
	v_mfma_f32_16x16x32_bf16 v[32:35], v[184:187], v[0:3], v[52:55]
	s_nop 0
	ds_read_b128 v[48:51], v210 offset:37248
	s_nop 0
	ds_read_b128 v[52:55], v210 offset:37312
	v_mfma_f32_16x16x32_bf16 v[36:39], v[148:151], v[8:11], v[36:39]
	v_mfma_f32_16x16x32_bf16 v[56:59], v[84:87], v[8:11], v[56:59]
	v_lshlrev_b32_e32 v84, 10, v200
	v_and_or_b32 v205, v84, s19, v219
	v_add_u32_e32 v206, 0x80000, v205
	s_waitcnt lgkmcnt(1)
	v_mfma_f32_16x16x32_bf16 v[48:51], v[48:51], v[4:7], v[68:71]
	s_nop 2
	ds_read_b128 v[68:71], v210 offset:45696
	ds_read_b128 v[72:75], v210 offset:45760
	v_add_u32_e32 v207, 0x100000, v205
	v_add_u32_e32 v208, 0x180000, v205
	v_mfma_f32_16x16x32_bf16 v[36:39], v[152:155], v[4:7], v[36:39]
	v_mfma_f32_16x16x32_bf16 v[60:63], v[88:91], v[8:11], v[60:63]
	s_waitcnt lgkmcnt(1)
	v_mfma_f32_16x16x32_bf16 v[56:59], v[68:71], v[4:7], v[56:59]
	ds_read_b128 v[68:71], v210 offset:54144
	ds_read_b128 v[76:79], v210 offset:54208
	v_mfma_f32_16x16x32_bf16 v[36:39], v[160:163], v[0:3], v[36:39]
	s_waitcnt lgkmcnt(1)
	v_mfma_f32_16x16x32_bf16 v[60:63], v[68:71], v[4:7], v[60:63]
	ds_read_b128 v[68:71], v209 offset:37248
	ds_read_b128 v[80:83], v209 offset:37312
	global_load_dwordx4 v[160:163], v193, s[8:9]
	global_load_dwordx4 v[164:167], v194, s[8:9]
	global_load_dwordx4 v[168:171], v195, s[8:9]
	global_load_dwordx4 v[172:175], v196, s[8:9]
	v_mfma_f32_16x16x32_bf16 v[64:67], v[92:95], v[8:11], v[64:67]
	s_waitcnt vmcnt(7)
	ds_write_b128 v211, v[12:15]
	s_waitcnt vmcnt(6)
	ds_write_b128 v212, v[16:19]
	s_waitcnt vmcnt(5)
	ds_write_b128 v224, v[20:23]
	s_waitcnt vmcnt(4)
	ds_write_b128 v225, v[24:27]
	s_waitcnt lgkmcnt(0)
	s_barrier
; #define LAS __attribute__((address_space(3)))
; #define GAS __attribute__((address_space(1)))
; __device__ __forceinline__ f32x4 mfma16(bf16x8 a, bf16x8 b, f32x4 c) { return __builtin_amdgcn_mfma_f32_16x16x32_bf16(a, b, c, 0, 0, 0); }
; __device__ __forceinline__ void xattn_unit(const Args& a, LAS unsigned char* lds, int b, int h, int qb, int tid, int wave, int lane) {
;     ...
;     auto gload = [&](int j) {
;         if (j < 4) { const GAS char* p_ = kxb + (size_t)j * (64 * DM * 2);
; #pragma unroll
;             for (int i = 0; i < 4; ++i) rr[j & 1][i] = *(const GAS u32x4*)(p_ + (size_t)(vok + (unsigned)(i * 16 * DM * 2)));
;         } else { const GAS char* p_ = vxb + (size_t)(j - 4) * 128;
; #pragma unroll
;             for (int i = 0; i < 4; ++i) rr[j & 1][i] = *(const GAS u32x4*)(p_ + (size_t)(vov + (unsigned)(i * 64 * MEMR * 2)));
;         }
;     };
;     ...
;     for (int j = 0; j < 8; ++j) {
;         if (j < 6) gload(j + 2);
;         const LAS bf16* base = (const LAS bf16*)(lds + (j & 1) * STG);
;         if (j < 4) {
; #pragma unroll
;             for (int rt = 0; rt < 4; ++rt)
; #pragma unroll
;                 for (int kk = 0; kk < 8; ++kk) S[4 * j + rt] = mfma16(*(const LAS bf16x8*)(base + (16 * rt + fr) * KS + 32 * kk + 8 * fq), qf[kk], S[4 * j + rt]);
	v_mfma_f32_16x16x32_bf16 v[64:67], v[68:71], v[4:7], v[64:67]
	global_load_dwordx4 v[12:15], v205, s[6:7]
	global_load_dwordx4 v[16:19], v206, s[6:7]
	global_load_dwordx4 v[20:23], v207, s[6:7]
	global_load_dwordx4 v[24:27], v208, s[6:7]
	v_mfma_f32_16x16x32_bf16 v[52:55], v[52:55], v[0:3], v[48:51]
	v_mfma_f32_16x16x32_bf16 v[56:59], v[72:75], v[0:3], v[56:59]
	v_mfma_f32_16x16x32_bf16 v[60:63], v[76:79], v[0:3], v[60:63]
	v_mfma_f32_16x16x32_bf16 v[48:51], v[80:83], v[0:3], v[64:67]
	ds_read_b128 v[76:79], v210
	ds_read_b128 v[84:87], v210 offset:64
	ds_read_b128 v[220:223], v210 offset:128
	ds_read_b128 v[132:135], v210 offset:192
	ds_read_b128 v[124:127], v210 offset:256
	ds_read_b128 v[116:119], v210 offset:320
	ds_read_b128 v[72:75], v210 offset:384
	ds_read_b128 v[64:67], v210 offset:448
	ds_read_b128 v[88:91], v210 offset:8448
	ds_read_b128 v[176:179], v210 offset:8512
	ds_read_b128 v[228:231], v210 offset:8576
	ds_read_b128 v[140:143], v210 offset:8640
	ds_read_b128 v[128:131], v210 offset:8704
	ds_read_b128 v[108:111], v210 offset:8768
	ds_read_b128 v[80:83], v210 offset:8832
	ds_read_b128 v[68:71], v210 offset:8896
	ds_read_b128 v[92:95], v210 offset:16896
	ds_read_b128 v[180:183], v210 offset:16960
	ds_read_b128 v[232:235], v210 offset:17024
	ds_read_b128 v[148:151], v210 offset:17088
	ds_read_b128 v[96:99], v209
	s_waitcnt lgkmcnt(14)
	v_mfma_f32_16x16x32_bf16 v[184:187], v[76:79], v[156:159], 0
	s_waitcnt lgkmcnt(12)
	v_mfma_f32_16x16x32_bf16 v[188:191], v[88:91], v[156:159], 0
	ds_read_b128 v[136:139], v210 offset:17152
	ds_read_b128 v[100:103], v210 offset:17216
	ds_read_b128 v[88:91], v210 offset:17280
	ds_read_b128 v[76:79], v210 offset:17344
	ds_read_b128 v[196:199], v209 offset:64
	ds_read_b128 v[236:239], v209 offset:128
	s_waitcnt lgkmcnt(6)
	v_mfma_f32_16x16x32_bf16 v[240:243], v[96:99], v[156:159], 0
	ds_read_b128 v[152:155], v209 offset:192
	ds_read_b128 v[144:147], v209 offset:256
	ds_read_b128 v[96:99], v209 offset:320
	v_mfma_f32_16x16x32_bf16 v[192:195], v[92:95], v[156:159], 0
	v_mfma_f32_16x16x32_bf16 v[244:247], v[84:87], v[120:123], v[184:187]
	ds_read_b128 v[92:95], v209 offset:384
	ds_read_b128 v[84:87], v209 offset:448
	s_waitcnt vmcnt(7)
	ds_write_b128 v211, v[160:163] offset:36864
	s_waitcnt vmcnt(6)
	ds_write_b128 v212, v[164:167] offset:36864
	s_waitcnt vmcnt(5)
	ds_write_b128 v224, v[168:171] offset:36864
	s_waitcnt vmcnt(4)
	ds_write_b128 v225, v[172:175] offset:36864
	s_waitcnt lgkmcnt(0)
	s_barrier
	v_mfma_f32_16x16x32_bf16 v[172:175], v[196:199], v[120:123], v[240:243]
	ds_read_b128 v[164:167], v210 offset:36864
	s_nop 1
	ds_read_b128 v[240:243], v210 offset:36928
	v_cndmask_b32_e32 v211, v253, v227, vcc
	v_lshlrev_b32_e32 v211, 2, v211
	s_waitcnt lgkmcnt(1)
	v_mfma_f32_16x16x32_bf16 v[248:251], v[164:167], v[156:159], 0
	ds_read_b128 v[164:167], v210 offset:45312
	ds_read_b128 v[184:187], v210 offset:45376
	v_cmp_lt_i32_e32 vcc, v204, v226
	v_mfma_f32_16x16x32_bf16 v[160:163], v[176:179], v[120:123], v[188:191]
	s_nop 0
	v_cndmask_b32_e32 v212, v253, v204, vcc
	v_lshlrev_b32_e32 v212, 2, v212
	v_mfma_f32_16x16x32_bf16 v[168:171], v[180:183], v[120:123], v[192:195]
	s_waitcnt lgkmcnt(1)
	v_mfma_f32_16x16x32_bf16 v[188:191], v[164:167], v[156:159], 0
	ds_read_b128 v[164:167], v210 offset:53760
	ds_read_b128 v[192:195], v210 offset:53824
	s_waitcnt lgkmcnt(1)
	v_mfma_f32_16x16x32_bf16 v[196:199], v[164:167], v[156:159], 0
	ds_read_b128 v[164:167], v209 offset:36864
	ds_read_b128 v[176:179], v209 offset:36928
	s_waitcnt lgkmcnt(1)
	v_mfma_f32_16x16x32_bf16 v[180:183], v[164:167], v[156:159], 0
	v_mfma_f32_16x16x32_bf16 v[164:167], v[220:223], v[112:115], v[244:247]
	v_lshrrev_b32_e32 v220, 1, v200
	v_lshrrev_b32_e32 v221, 3, v200
	v_and_b32_e32 v200, 24, v220
	v_mfma_f32_16x16x32_bf16 v[160:163], v[228:231], v[112:115], v[160:163]
	v_or_b32_e32 v222, 0x70, v214
	v_or_b32_e32 v223, 0xf0, v214
	v_mul_lo_u32 v220, v221, s22
	v_mfma_f32_16x16x32_bf16 v[156:159], v[232:235], v[112:115], v[168:171]
	v_mfma_f32_16x16x32_bf16 v[168:171], v[236:239], v[112:115], v[172:175]
	v_mfma_f32_16x16x32_bf16 v[184:187], v[184:187], v[120:123], v[188:191]
	v_mfma_f32_16x16x32_bf16 v[188:191], v[192:195], v[120:123], v[196:199]
	v_lshrrev_b32_e32 v192, 3, v217
	v_lshrrev_b32_e32 v193, 3, v218
	v_mfma_f32_16x16x32_bf16 v[172:175], v[240:243], v[120:123], v[248:251]
	s_waitcnt lgkmcnt(0)
	v_mfma_f32_16x16x32_bf16 v[120:123], v[176:179], v[120:123], v[180:183]
	v_mul_lo_u32 v178, v193, s22
	v_or_b32_e32 v177, 0xb0, v214
	v_add3_u32 v176, 0, v220, v219
	v_mfma_f32_16x16x32_bf16 v[132:135], v[132:135], v[104:107], v[164:167]
	s_nop 2
	v_mul_lo_u32 v164, v216, s22
	v_mul_lo_u32 v165, v192, s22
	v_mfma_f32_16x16x32_bf16 v[140:143], v[140:143], v[104:107], v[160:163]
	s_nop 2
	v_add3_u32 v160, 0, v164, v219
	v_add3_u32 v161, 0, v165, v219
	v_mfma_f32_16x16x32_bf16 v[164:167], v[148:151], v[104:107], v[156:159]
	v_add3_u32 v148, 0, v178, v219
	v_add_u32_e32 v162, 0, v200
	v_mad_u32_u24 v151, v215, s22, v162
	v_mfma_f32_16x16x32_bf16 v[168:171], v[152:155], v[104:107], v[168:171]
	ds_read_b128 v[152:155], v210 offset:36992
	ds_read_b128 v[178:181], v210 offset:37056
	v_mad_u32_u24 v156, v213, s22, v162
	v_mad_u32_u24 v150, v177, s22, v162
	s_waitcnt lgkmcnt(1)
	v_mfma_f32_16x16x32_bf16 v[172:175], v[152:155], v[112:115], v[172:175]
	ds_read_b128 v[152:155], v210 offset:45440
	ds_read_b128 v[192:195], v210 offset:45504
	v_mad_u32_u24 v149, v223, s22, v162
	v_add_u32_e32 v158, 0x2000, v156
	s_waitcnt lgkmcnt(1)
; #define LAS __attribute__((address_space(3)))
; __device__ __forceinline__ f32x4 mfma16(bf16x8 a, bf16x8 b, f32x4 c) { return __builtin_amdgcn_mfma_f32_16x16x32_bf16(a, b, c, 0, 0, 0); }
; __device__ __forceinline__ void xattn_unit(const Args& a, LAS unsigned char* lds, int b, int h, int qb, int tid, int wave, int lane) {
;     ...
;                 for (int kk = 0; kk < 8; ++kk) S[4 * j + rt] = mfma16(*(const LAS bf16x8*)(base + (16 * rt + fr) * KS + 32 * kk + 8 * fq), qf[kk], S[4 * j + rt]);
;             if (j == 3) {
;                 float mx = -3.0e38f;
; #pragma unroll
;                 for (int i = 0; i < 16; ++i) mx = fmaxf(mx, fmaxf(fmaxf(S[i][0], S[i][1]), fmaxf(S[i][2], S[i][3])));
;                 mx = fmaxf(mx, __shfl_xor(mx, 16)); mx = fmaxf(mx, __shfl_xor(mx, 32));
	v_mfma_f32_16x16x32_bf16 v[182:185], v[152:155], v[112:115], v[184:187]
	ds_read_b128 v[152:155], v210 offset:53888
	ds_read_b128 v[196:199], v210 offset:53952
	v_add_u32_e32 v159, 0x2800, v156
	v_add_u32_e32 v157, 0x3000, v156
	s_waitcnt lgkmcnt(1)
	v_mfma_f32_16x16x32_bf16 v[186:189], v[152:155], v[112:115], v[188:191]
	ds_read_b128 v[152:155], v209 offset:36992
	ds_read_b128 v[214:217], v209 offset:37056
	v_add_u32_e32 v163, 0x800, v156
	s_waitcnt lgkmcnt(1)
	v_mfma_f32_16x16x32_bf16 v[218:221], v[152:155], v[112:115], v[120:123]
	v_mad_u32_u24 v152, v222, s22, v162
	v_add_u32_e32 v162, 0x1000, v156
	v_add_u32_e32 v154, 0x4800, v156
	v_mfma_f32_16x16x32_bf16 v[228:231], v[124:127], v[28:31], v[132:135]
	v_add_u32_e32 v155, 0x5000, v156
	v_add_u32_e32 v153, 0x5800, v156
	v_mfma_f32_16x16x32_bf16 v[132:135], v[136:139], v[28:31], v[164:167]
	v_add_u32_e32 v139, 0x6800, v156
	v_lshl_add_u64 v[136:137], s[4:5], 0, v[202:203]
	v_add_u32_e32 v138, 0x9000, v156
	v_mfma_f32_16x16x32_bf16 v[112:115], v[144:147], v[28:31], v[168:171]
	v_add_u32_e32 v146, 0x7000, v156
	v_add_u32_e32 v144, 0x7800, v156
	v_add_u32_e32 v145, 0x9800, v156
	v_mfma_f32_16x16x32_bf16 v[140:143], v[128:131], v[28:31], v[140:143]
	v_add_u32_e32 v147, 0xa000, v156
	v_add_u32_e32 v164, 0x9000, v151
	v_add_u32_e32 v165, 0xb000, v156
	v_mfma_f32_16x16x32_bf16 v[120:123], v[178:181], v[104:107], v[172:175]
	v_add_u32_e32 v166, 0xb800, v156
	v_add_u32_e32 v167, 0xc000, v156
	v_add_u32_e32 v168, 0x9000, v152
	v_mfma_f32_16x16x32_bf16 v[100:103], v[100:103], v[8:11], v[132:135]
	v_add_u32_e32 v169, 0xd800, v156
	v_add_u32_e32 v170, 0xe000, v156
	v_add_u32_e32 v171, 0xe800, v156
	v_mfma_f32_16x16x32_bf16 v[96:99], v[96:99], v[8:11], v[112:115]
	s_nop 2
	ds_read_b128 v[112:115], v210 offset:37120
	ds_read_b128 v[132:135], v210 offset:37184
	v_add_u32_e32 v172, 0x9000, v150
	v_add_u32_e32 v173, 0xf800, v156
	v_mfma_f32_16x16x32_bf16 v[124:127], v[192:195], v[104:107], v[182:185]
	v_add_u32_e32 v177, 0x7000, v138
	v_add_u32_e32 v175, 0x7800, v138
	v_add_u32_e32 v174, 0x9000, v149
	v_mfma_f32_16x16x32_bf16 v[108:111], v[108:111], v[8:11], v[140:143]
	v_lshl_add_u64 v[136:137], v[136:137], 0, s[0:1]
	v_lshl_add_u64 v[136:137], v[136:137], 0, v[200:201]
	s_waitcnt lgkmcnt(1)
	v_mfma_f32_16x16x32_bf16 v[112:115], v[112:115], v[28:31], v[120:123]
	s_nop 2
	ds_read_b128 v[120:123], v210 offset:45568
	ds_read_b128 v[140:143], v210 offset:45632
	v_mfma_f32_16x16x32_bf16 v[128:131], v[196:199], v[104:107], v[186:189]
	s_waitcnt lgkmcnt(1)
	v_mfma_f32_16x16x32_bf16 v[120:123], v[120:123], v[28:31], v[124:127]
	s_nop 2
	ds_read_b128 v[124:127], v210 offset:54016
	ds_read_b128 v[178:181], v210 offset:54080
	v_mfma_f32_16x16x32_bf16 v[104:107], v[214:217], v[104:107], v[218:221]
	s_waitcnt lgkmcnt(1)
	v_mfma_f32_16x16x32_bf16 v[124:127], v[124:127], v[28:31], v[128:131]
	s_nop 2
	ds_read_b128 v[128:131], v209 offset:37120
	ds_read_b128 v[182:185], v209 offset:37184
	v_mfma_f32_16x16x32_bf16 v[116:119], v[116:119], v[8:11], v[228:231]
	s_waitcnt lgkmcnt(1)
	v_mfma_f32_16x16x32_bf16 v[28:31], v[128:131], v[28:31], v[104:107]
	s_nop 2
	v_max_f32_e32 v104, v47, v47
	v_max_f32_e32 v105, v46, v46
	v_max_f32_e32 v106, v43, v43
	v_max_f32_e32 v107, v42, v42
	v_mfma_f32_16x16x32_bf16 v[72:75], v[72:75], v[4:7], v[116:119]
	v_max_f32_e32 v104, v105, v104
	s_nop 1
	v_max_f32_e32 v116, v39, v39
	v_max_f32_e32 v117, v38, v38
	v_mfma_f32_16x16x32_bf16 v[80:83], v[80:83], v[4:7], v[108:111]
	s_nop 2
	v_max_f32_e32 v108, v35, v35
	v_max_f32_e32 v109, v34, v34
	v_mfma_f32_16x16x32_bf16 v[88:91], v[88:91], v[4:7], v[100:103]
	s_nop 2
	v_max_f32_e32 v100, v107, v106
	v_max_f32_e32 v101, v117, v116
	v_max_f32_e32 v102, v109, v108
	v_max3_f32 v103, v44, v45, v104
	v_max3_f32 v100, v40, v41, v100
	v_mfma_f32_16x16x32_bf16 v[92:95], v[92:95], v[4:7], v[96:99]
	v_max3_f32 v101, v36, v37, v101
	v_max3_f32 v102, v32, v33, v102
	v_max3_f32 v100, v103, s21, v100
	v_mfma_f32_16x16x32_bf16 v[96:99], v[132:135], v[8:11], v[112:115]
	v_max_f32_e32 v108, v55, v55
	v_max_f32_e32 v109, v54, v54
	v_max_f32_e32 v116, v62, v62
	v_max_f32_e32 v113, v59, v59
	v_max_f32_e32 v114, v58, v58
	v_max3_f32 v112, v100, v101, v102
	v_mfma_f32_16x16x32_bf16 v[100:103], v[140:143], v[8:11], v[120:123]
	v_max_f32_e32 v115, v63, v63
	v_mfma_f32_16x16x32_bf16 v[104:107], v[178:181], v[8:11], v[124:127]
	s_waitcnt lgkmcnt(0)
	v_mfma_f32_16x16x32_bf16 v[8:11], v[182:185], v[8:11], v[28:31]
	s_nop 2
	v_max_f32_e32 v28, v51, v51
	v_max_f32_e32 v29, v50, v50
	v_max_f32_e32 v30, v109, v108
	v_max_f32_e32 v31, v114, v113
	v_mfma_f32_16x16x32_bf16 v[108:111], v[64:67], v[0:3], v[72:75]
	v_max_f32_e32 v64, v116, v115
	v_max_f32_e32 v28, v29, v28
	v_max3_f32 v29, v52, v53, v30
	v_max3_f32 v30, v56, v57, v31
	v_max3_f32 v31, v60, v61, v64
	v_max3_f32 v28, v48, v49, v28
	v_max3_f32 v29, v112, v29, v30
	v_max3_f32 v116, v29, v31, v28
	ds_read_b128 v[28:31], v210 offset:37248
	ds_read_b128 v[72:75], v210 offset:37312
	v_mfma_f32_16x16x32_bf16 v[76:79], v[76:79], v[0:3], v[88:91]
	v_max_f32_e32 v117, v111, v111
	v_max_f32_e32 v118, v110, v110
	v_mfma_f32_16x16x32_bf16 v[84:87], v[84:87], v[0:3], v[92:95]
	s_waitcnt lgkmcnt(1)
	v_mfma_f32_16x16x32_bf16 v[88:91], v[28:31], v[4:7], v[96:99]
	ds_read_b128 v[28:31], v210 offset:45696
	ds_read_b128 v[92:95], v210 offset:45760
	s_waitcnt lgkmcnt(1)
	v_mfma_f32_16x16x32_bf16 v[96:99], v[28:31], v[4:7], v[100:103]
	ds_read_b128 v[28:31], v210 offset:54144
	s_nop 1
	ds_read_b128 v[100:103], v210 offset:54208
	s_waitcnt lgkmcnt(1)
	v_mfma_f32_16x16x32_bf16 v[104:107], v[28:31], v[4:7], v[104:107]
	ds_read_b128 v[28:31], v209 offset:37248
	ds_read_b128 v[112:115], v209 offset:37312
	v_mfma_f32_16x16x32_bf16 v[80:83], v[68:71], v[0:3], v[80:83]
	s_waitcnt lgkmcnt(1)
	v_mfma_f32_16x16x32_bf16 v[4:7], v[28:31], v[4:7], v[8:11]
	global_load_dwordx4 v[68:71], v205, s[6:7] offset:128
	global_load_dwordx4 v[28:31], v206, s[6:7] offset:128
	global_load_dwordx4 v[64:67], v207, s[6:7] offset:128
	v_mfma_f32_16x16x32_bf16 v[8:11], v[72:75], v[0:3], v[88:91]
	global_load_dwordx4 v[72:75], v208, s[6:7] offset:128
	s_waitcnt vmcnt(7)
	ds_write_b128 v176, v[12:15]
	s_waitcnt vmcnt(6)
	ds_write_b128 v160, v[16:19]
	s_waitcnt vmcnt(5)
	ds_write_b128 v161, v[20:23]
	s_waitcnt vmcnt(4)
	ds_write_b128 v148, v[24:27]
	s_waitcnt lgkmcnt(0)
	v_mfma_f32_16x16x32_bf16 v[88:91], v[92:95], v[0:3], v[96:99]
	s_barrier
; #define LAS __attribute__((address_space(3)))
; __device__ __forceinline__ f32x4 mfma16(bf16x8 a, bf16x8 b, f32x4 c) { return __builtin_amdgcn_mfma_f32_16x16x32_bf16(a, b, c, 0, 0, 0); }
; __device__ __forceinline__ bf16x8 pack8(f32x4 a, f32x4 b) { u32x4 w; w.x = pk2(a[0], a[1]); w.y = pk2(a[2], a[3]); w.z = pk2(b[0], b[1]); w.w = pk2(b[2], b[3]); return __builtin_bit_cast(bf16x8, w); }
; __device__ __forceinline__ void xattn_unit(const Args& a, LAS unsigned char* lds, int b, int h, int qb, int tid, int wave, int lane) {
;     ...
;             if (j == 3) {
;                 float mx = -3.0e38f;
; #pragma unroll
;                 for (int i = 0; i < 16; ++i) mx = fmaxf(mx, fmaxf(fmaxf(S[i][0], S[i][1]), fmaxf(S[i][2], S[i][3])));
;                 mx = fmaxf(mx, __shfl_xor(mx, 16)); mx = fmaxf(mx, __shfl_xor(mx, 32));
; #pragma unroll
;                 for (int i = 0; i < 16; ++i)
; #pragma unroll
;                     for (int k = 0; k < 4; ++k) { S[i][k] = __builtin_amdgcn_exp2f(S[i][k] - mx); l += S[i][k]; }
;                 l += __shfl_xor(l, 16); l += __shfl_xor(l, 32);
; #pragma unroll
;                 for (int c2 = 0; c2 < 8; ++c2) pf[c2] = pack8(S[2 * c2], S[2 * c2 + 1]);
;             }
;         } else {
;             const int mt = j - 4;
; #pragma unroll
;             for (int dt = 0; dt < 16; ++dt) {
;                 const LAS bf16* vr = base + (16 * dt + fr) * VS + 4 * fq;
;                 O[dt] = mfma16(cat8(*(const LAS u32x2*)vr, *(const LAS u32x2*)(vr + 16)), pf[2 * mt], O[dt]);
	ds_read2_b64 v[12:15], v156 offset1:4
	ds_read2_b64 v[16:19], v163 offset0:32 offset1:36
	v_max_f32_e32 v96, v83, v83
	v_max_f32_e32 v97, v82, v82
	v_max_f32_e32 v98, v79, v79
	v_mfma_f32_16x16x32_bf16 v[92:95], v[100:103], v[0:3], v[104:107]
	v_max_f32_e32 v99, v78, v78
	v_max_f32_e32 v100, v87, v87
	v_max_f32_e32 v101, v86, v86
	v_mfma_f32_16x16x32_bf16 v[0:3], v[112:115], v[0:3], v[4:7]
	ds_read2_b64 v[20:23], v162 offset0:64 offset1:68
	ds_read2_b64 v[24:27], v151 offset1:4
	ds_read2_b64 v[112:115], v156 offset0:8 offset1:12
	v_max_f32_e32 v4, v118, v117
	v_max_f32_e32 v5, v97, v96
	v_max_f32_e32 v6, v99, v98
	v_max_f32_e32 v7, v101, v100
	v_max3_f32 v4, v108, v109, v4
	v_max3_f32 v5, v80, v81, v5
	v_max3_f32 v6, v76, v77, v6
	v_max3_f32 v7, v84, v85, v7
	v_max3_f32 v4, v116, v4, v5
	v_max3_f32 v4, v4, v6, v7
	v_max_f32_e32 v5, v11, v11
	v_max_f32_e32 v6, v10, v10
	v_max_f32_e32 v7, v91, v91
	v_max_f32_e32 v96, v90, v90
	v_max_f32_e32 v97, v95, v95
	v_max_f32_e32 v98, v94, v94
	v_max_f32_e32 v99, v3, v3
	v_max_f32_e32 v100, v2, v2
	v_max_f32_e32 v5, v6, v5
	v_max_f32_e32 v6, v96, v7
	v_max_f32_e32 v7, v98, v97
	v_max_f32_e32 v96, v100, v99
	v_max3_f32 v5, v8, v9, v5
	v_max3_f32 v6, v88, v89, v6
	v_max3_f32 v7, v92, v93, v7
	v_max3_f32 v96, v0, v1, v96
	v_max3_f32 v4, v4, v5, v6
	v_max3_f32 v4, v4, v7, v96
	ds_bpermute_b32 v5, v211, v4
	s_waitcnt lgkmcnt(0)
	v_max_f32_e32 v5, v5, v5
	v_max_f32_e32 v4, v4, v5
	ds_bpermute_b32 v5, v212, v4
	s_waitcnt lgkmcnt(0)
	v_max_f32_e32 v5, v5, v5
	v_max_f32_e32 v4, v4, v5
	v_sub_f32_e32 v5, v44, v4
	v_sub_f32_e32 v6, v45, v4
	v_sub_f32_e32 v7, v46, v4
	v_sub_f32_e32 v44, v47, v4
	v_sub_f32_e32 v40, v40, v4
	v_sub_f32_e32 v41, v41, v4
	v_sub_f32_e32 v42, v42, v4
	v_sub_f32_e32 v43, v43, v4
	v_sub_f32_e32 v36, v36, v4
	v_sub_f32_e32 v37, v37, v4
	v_sub_f32_e32 v38, v38, v4
	v_sub_f32_e32 v39, v39, v4
	v_sub_f32_e32 v32, v32, v4
	v_sub_f32_e32 v33, v33, v4
	v_sub_f32_e32 v34, v34, v4
	v_sub_f32_e32 v35, v35, v4
	v_sub_f32_e32 v45, v52, v4
	v_sub_f32_e32 v46, v53, v4
	v_sub_f32_e32 v47, v54, v4
	v_sub_f32_e32 v52, v55, v4
	v_sub_f32_e32 v53, v56, v4
	v_sub_f32_e32 v54, v57, v4
	v_sub_f32_e32 v55, v58, v4
	v_sub_f32_e32 v56, v59, v4
	v_sub_f32_e32 v57, v60, v4
	v_sub_f32_e32 v58, v61, v4
	v_sub_f32_e32 v59, v62, v4
	v_sub_f32_e32 v60, v63, v4
	v_sub_f32_e32 v48, v48, v4
	v_sub_f32_e32 v49, v49, v4
	v_sub_f32_e32 v50, v50, v4
	v_sub_f32_e32 v51, v51, v4
	v_sub_f32_e32 v61, v108, v4
	v_sub_f32_e32 v62, v109, v4
	v_sub_f32_e32 v63, v110, v4
	v_sub_f32_e32 v96, v111, v4
	v_sub_f32_e32 v80, v80, v4
	v_sub_f32_e32 v81, v81, v4
	v_sub_f32_e32 v82, v82, v4
	v_sub_f32_e32 v83, v83, v4
	v_sub_f32_e32 v76, v76, v4
	v_sub_f32_e32 v77, v77, v4
	v_sub_f32_e32 v78, v78, v4
	v_sub_f32_e32 v79, v79, v4
	v_sub_f32_e32 v84, v84, v4
	v_sub_f32_e32 v85, v85, v4
	v_sub_f32_e32 v86, v86, v4
	v_sub_f32_e32 v87, v87, v4
	v_sub_f32_e32 v8, v8, v4
	v_sub_f32_e32 v9, v9, v4
	v_sub_f32_e32 v10, v10, v4
	v_sub_f32_e32 v11, v11, v4
	v_sub_f32_e32 v88, v88, v4
	v_sub_f32_e32 v89, v89, v4
	v_sub_f32_e32 v90, v90, v4
	v_sub_f32_e32 v91, v91, v4
	v_sub_f32_e32 v92, v92, v4
	v_sub_f32_e32 v93, v93, v4
	v_sub_f32_e32 v94, v94, v4
	v_sub_f32_e32 v95, v95, v4
	v_sub_f32_e32 v0, v0, v4
	v_sub_f32_e32 v1, v1, v4
	v_sub_f32_e32 v2, v2, v4
	v_sub_f32_e32 v3, v3, v4
	v_exp_f32_e32 v4, v5
	v_exp_f32_e32 v97, v6
	v_exp_f32_e32 v98, v7
	v_exp_f32_e32 v99, v44
	v_exp_f32_e32 v100, v40
	v_exp_f32_e32 v189, v52
	v_add_f32_e32 v52, 0, v4
	v_exp_f32_e32 v101, v41
	v_add_f32_e32 v52, v97, v52
	v_exp_f32_e32 v102, v42
	v_add_f32_e32 v52, v98, v52
	v_exp_f32_e32 v103, v43
	v_add_f32_e32 v52, v99, v52
	v_exp_f32_e32 v104, v36
	v_add_f32_e32 v52, v100, v52
	v_exp_f32_e32 v105, v37
	v_add_f32_e32 v52, v101, v52
	v_exp_f32_e32 v106, v38
	v_exp_f32_e32 v120, v39
	v_add_f32_e32 v52, v102, v52
	v_add_f32_e32 v52, v103, v52
	v_add_f32_e32 v52, v104, v52
	v_add_f32_e32 v52, v105, v52
	v_exp_f32_e32 v190, v53
	v_exp_f32_e32 v191, v54
	v_exp_f32_e32 v192, v55
	v_exp_f32_e32 v193, v56
	v_exp_f32_e32 v194, v57
	v_exp_f32_e32 v195, v58
	v_exp_f32_e32 v196, v59
	v_exp_f32_e32 v197, v60
	v_exp_f32_e32 v203, v61
	v_exp_f32_e32 v209, v62
	v_exp_f32_e32 v210, v63
	v_exp_f32_e32 v213, v96
	v_exp_f32_e32 v214, v80
	v_exp_f32_e32 v215, v81
	v_exp_f32_e32 v216, v82
	v_exp_f32_e32 v217, v83
	v_exp_f32_e32 v218, v76
	v_exp_f32_e32 v219, v77
	v_exp_f32_e32 v220, v78
	v_exp_f32_e32 v221, v79
	v_exp_f32_e32 v222, v84
	v_exp_f32_e32 v223, v85
	v_exp_f32_e32 v224, v86
	v_exp_f32_e32 v225, v87
	v_exp_f32_e32 v232, v88
	v_exp_f32_e32 v233, v89
	v_exp_f32_e32 v234, v90
	v_exp_f32_e32 v235, v91
	v_exp_f32_e32 v236, v92
	v_exp_f32_e32 v237, v93
	v_exp_f32_e32 v238, v94
	v_exp_f32_e32 v239, v95
	v_cvt_pk_bf16_f32 v36, v4, v97
	v_cvt_pk_bf16_f32 v37, v98, v99
	v_cvt_pk_bf16_f32 v38, v100, v101
	v_cvt_pk_bf16_f32 v39, v102, v103
	v_cvt_pk_bf16_f32 v40, v104, v105
	v_cvt_pk_bf16_f32 v41, v106, v120
	v_add_f32_e32 v121, v106, v52
	ds_read2_b64 v[52:55], v158 offset0:128 offset1:132
	ds_read2_b64 v[56:59], v159 offset0:160 offset1:164
	ds_read2_b64 v[60:63], v157 offset0:192 offset1:196
	ds_read2_b64 v[76:79], v152 offset1:4
	ds_read2_b64 v[80:83], v154 offset1:4
	ds_read2_b64 v[84:87], v155 offset0:32 offset1:36
	ds_read2_b64 v[88:91], v153 offset0:64 offset1:68
	ds_read2_b64 v[92:95], v150 offset1:4
	ds_read2_b64 v[96:99], v139 offset0:128 offset1:132
	ds_read2_b64 v[100:103], v146 offset0:160 offset1:164
	ds_read2_b64 v[104:107], v144 offset0:192 offset1:196
	ds_read2_b64 v[108:111], v149 offset1:4
	v_exp_f32_e32 v182, v32
	v_exp_f32_e32 v183, v33
	v_exp_f32_e32 v184, v34
	v_exp_f32_e32 v185, v35
	v_mfma_f32_16x16x32_bf16 v[12:15], v[12:15], v[36:39], 0
	v_cvt_pk_bf16_f32 v42, v182, v183
	v_add_f32_e32 v244, v120, v121
	v_cvt_pk_bf16_f32 v43, v184, v185
	v_mfma_f32_16x16x32_bf16 v[16:19], v[16:19], v[36:39], 0
	v_exp_f32_e32 v186, v45
	v_exp_f32_e32 v187, v46
	v_exp_f32_e32 v188, v47
	v_mfma_f32_16x16x32_bf16 v[20:23], v[20:23], v[36:39], 0
	v_cvt_pk_bf16_f32 v46, v190, v191
	v_cvt_pk_bf16_f32 v44, v186, v187
	v_cvt_pk_bf16_f32 v45, v188, v189
	v_mfma_f32_16x16x32_bf16 v[24:27], v[24:27], v[36:39], 0
	v_cvt_pk_bf16_f32 v47, v192, v193
	v_exp_f32_e32 v198, v48
	v_exp_f32_e32 v199, v49
	s_waitcnt lgkmcnt(11)
; #define LAS __attribute__((address_space(3)))
; __device__ __forceinline__ f32x4 mfma16(bf16x8 a, bf16x8 b, f32x4 c) { return __builtin_amdgcn_mfma_f32_16x16x32_bf16(a, b, c, 0, 0, 0); }
; __device__ __forceinline__ bf16x8 pack8(f32x4 a, f32x4 b) { u32x4 w; w.x = pk2(a[0], a[1]); w.y = pk2(a[2], a[3]); w.z = pk2(b[0], b[1]); w.w = pk2(b[2], b[3]); return __builtin_bit_cast(bf16x8, w); }
; __device__ __forceinline__ void xattn_unit(const Args& a, LAS unsigned char* lds, int b, int h, int qb, int tid, int wave, int lane) {
;     ...
;                 for (int i = 0; i < 16; ++i)
; #pragma unroll
;                     for (int k = 0; k < 4; ++k) { S[i][k] = __builtin_amdgcn_exp2f(S[i][k] - mx); l += S[i][k]; }
;                 l += __shfl_xor(l, 16); l += __shfl_xor(l, 32);
; #pragma unroll
;                 for (int c2 = 0; c2 < 8; ++c2) pf[c2] = pack8(S[2 * c2], S[2 * c2 + 1]);
;             }
;         } else {
;             const int mt = j - 4;
; #pragma unroll
;             for (int dt = 0; dt < 16; ++dt) {
;                 const LAS bf16* vr = base + (16 * dt + fr) * VS + 4 * fq;
;                 O[dt] = mfma16(cat8(*(const LAS u32x2*)vr, *(const LAS u32x2*)(vr + 16)), pf[2 * mt], O[dt]);
;                 O[dt] = mfma16(cat8(*(const LAS u32x2*)(vr + 32), *(const LAS u32x2*)(vr + 48)), pf[2 * mt + 1], O[dt]);
;             }
;         }
;         if (j < 7) lstore(j + 1);
;         __syncthreads();
	v_mfma_f32_16x16x32_bf16 v[52:55], v[52:55], v[36:39], 0
	v_exp_f32_e32 v200, v50
	v_exp_f32_e32 v202, v51
	v_cvt_pk_bf16_f32 v48, v194, v195
	s_waitcnt lgkmcnt(10)
	v_mfma_f32_16x16x32_bf16 v[56:59], v[56:59], v[36:39], 0
	v_cvt_pk_bf16_f32 v49, v196, v197
	v_cvt_pk_bf16_f32 v50, v198, v199
	v_cvt_pk_bf16_f32 v51, v200, v202
	s_waitcnt lgkmcnt(9)
	v_mfma_f32_16x16x32_bf16 v[60:63], v[60:63], v[36:39], 0
	v_add_f32_e32 v182, v182, v244
	v_exp_f32_e32 v228, v8
	v_exp_f32_e32 v229, v9
	s_waitcnt lgkmcnt(8)
	v_mfma_f32_16x16x32_bf16 v[76:79], v[76:79], v[36:39], 0
	v_exp_f32_e32 v230, v10
	v_exp_f32_e32 v231, v11
	v_exp_f32_e32 v240, v0
	s_waitcnt lgkmcnt(7)
	v_mfma_f32_16x16x32_bf16 v[80:83], v[80:83], v[36:39], 0
	v_exp_f32_e32 v241, v1
	v_exp_f32_e32 v242, v2
	v_exp_f32_e32 v243, v3
	s_waitcnt lgkmcnt(6)
	v_mfma_f32_16x16x32_bf16 v[84:87], v[84:87], v[36:39], 0
	v_cvt_pk_bf16_f32 v32, v203, v209
	v_cvt_pk_bf16_f32 v33, v210, v213
	v_cvt_pk_bf16_f32 v34, v214, v215
	s_waitcnt lgkmcnt(5)
	v_mfma_f32_16x16x32_bf16 v[88:91], v[88:91], v[36:39], 0
	v_cvt_pk_bf16_f32 v35, v216, v217
	v_cvt_pk_bf16_f32 v8, v218, v219
	v_cvt_pk_bf16_f32 v9, v220, v221
	s_waitcnt lgkmcnt(4)
	v_mfma_f32_16x16x32_bf16 v[92:95], v[92:95], v[36:39], 0
	v_cvt_pk_bf16_f32 v10, v222, v223
	v_cvt_pk_bf16_f32 v11, v224, v225
	v_cvt_pk_bf16_f32 v4, v228, v229
	s_waitcnt lgkmcnt(3)
	v_mfma_f32_16x16x32_bf16 v[96:99], v[96:99], v[36:39], 0
	v_cvt_pk_bf16_f32 v5, v230, v231
	v_cvt_pk_bf16_f32 v6, v232, v233
	v_cvt_pk_bf16_f32 v7, v234, v235
	s_waitcnt lgkmcnt(2)
	v_mfma_f32_16x16x32_bf16 v[100:103], v[100:103], v[36:39], 0
	v_cvt_pk_bf16_f32 v0, v236, v237
	v_cvt_pk_bf16_f32 v1, v238, v239
	v_cvt_pk_bf16_f32 v2, v240, v241
	s_waitcnt lgkmcnt(1)
	v_mfma_f32_16x16x32_bf16 v[104:107], v[104:107], v[36:39], 0
	v_cvt_pk_bf16_f32 v3, v242, v243
	s_waitcnt lgkmcnt(0)
	v_mfma_f32_16x16x32_bf16 v[36:39], v[108:111], v[36:39], 0
	ds_read2_b64 v[108:111], v163 offset0:40 offset1:44
	v_mfma_f32_16x16x32_bf16 v[12:15], v[112:115], v[40:43], v[12:15]
	ds_read2_b64 v[112:115], v162 offset0:72 offset1:76
	s_waitcnt lgkmcnt(1)
	v_mfma_f32_16x16x32_bf16 v[16:19], v[108:111], v[40:43], v[16:19]
	ds_read2_b64 v[108:111], v151 offset0:8 offset1:12
	s_waitcnt lgkmcnt(1)
	v_mfma_f32_16x16x32_bf16 v[20:23], v[112:115], v[40:43], v[20:23]
	ds_read2_b64 v[112:115], v158 offset0:136 offset1:140
	s_waitcnt lgkmcnt(1)
	v_mfma_f32_16x16x32_bf16 v[24:27], v[108:111], v[40:43], v[24:27]
	ds_read2_b64 v[108:111], v159 offset0:168 offset1:172
	s_waitcnt lgkmcnt(1)
	v_mfma_f32_16x16x32_bf16 v[52:55], v[112:115], v[40:43], v[52:55]
	ds_read2_b64 v[112:115], v157 offset0:200 offset1:204
	s_waitcnt lgkmcnt(1)
	v_mfma_f32_16x16x32_bf16 v[56:59], v[108:111], v[40:43], v[56:59]
	ds_read2_b64 v[108:111], v152 offset0:8 offset1:12
	s_waitcnt lgkmcnt(1)
	v_mfma_f32_16x16x32_bf16 v[60:63], v[112:115], v[40:43], v[60:63]
	ds_read2_b64 v[112:115], v154 offset0:8 offset1:12
	ds_read2_b64 v[116:119], v155 offset0:40 offset1:44
	ds_read2_b64 v[120:123], v153 offset0:72 offset1:76
	s_waitcnt lgkmcnt(3)
	v_mfma_f32_16x16x32_bf16 v[76:79], v[108:111], v[40:43], v[76:79]
	global_load_dwordx4 v[108:111], v205, s[6:7] offset:256
	s_waitcnt lgkmcnt(2)
	v_mfma_f32_16x16x32_bf16 v[80:83], v[112:115], v[40:43], v[80:83]
	global_load_dwordx4 v[112:115], v206, s[6:7] offset:256
	global_load_dwordx4 v[124:127], v207, s[6:7] offset:256
	ds_read2_b64 v[128:131], v150 offset0:8 offset1:12
	s_waitcnt lgkmcnt(2)
	v_mfma_f32_16x16x32_bf16 v[84:87], v[116:119], v[40:43], v[84:87]
	global_load_dwordx4 v[116:119], v208, s[6:7] offset:256
	ds_read2_b64 v[132:135], v139 offset0:136 offset1:140
	ds_read2_b64 v[140:143], v146 offset0:168 offset1:172
	s_waitcnt lgkmcnt(3)
	v_mfma_f32_16x16x32_bf16 v[88:91], v[120:123], v[40:43], v[88:91]
	ds_read2_b64 v[120:123], v144 offset0:200 offset1:204
	ds_read2_b64 v[178:181], v149 offset0:8 offset1:12
	s_waitcnt vmcnt(7)
	ds_write_b128 v176, v[68:71] offset:36864
	s_waitcnt vmcnt(6)
	ds_write_b128 v160, v[28:31] offset:36864
	s_waitcnt vmcnt(5)
	ds_write_b128 v161, v[64:67] offset:36864
	s_waitcnt vmcnt(4)
	ds_write_b128 v148, v[72:75] offset:36864
	s_waitcnt lgkmcnt(0)
	s_barrier
	ds_read2_b64 v[72:75], v138 offset1:4
	v_mfma_f32_16x16x32_bf16 v[92:95], v[128:131], v[40:43], v[92:95]
	v_add_f32_e32 v128, v183, v182
	v_add_f32_e32 v128, v184, v128
	v_mfma_f32_16x16x32_bf16 v[68:71], v[132:135], v[40:43], v[96:99]
	v_mfma_f32_16x16x32_bf16 v[28:31], v[140:143], v[40:43], v[100:103]
	v_mfma_f32_16x16x32_bf16 v[64:67], v[120:123], v[40:43], v[104:107]
	v_mfma_f32_16x16x32_bf16 v[36:39], v[178:181], v[40:43], v[36:39]
	ds_read2_b64 v[40:43], v145 offset0:32 offset1:36
	v_add_f32_e32 v178, v185, v128
	v_add_f32_e32 v178, v186, v178
	s_waitcnt lgkmcnt(1)
	v_mfma_f32_16x16x32_bf16 v[12:15], v[72:75], v[44:47], v[12:15]
	ds_read2_b64 v[72:75], v147 offset0:64 offset1:68
	v_add_f32_e32 v178, v187, v178
	s_waitcnt lgkmcnt(1)
	v_mfma_f32_16x16x32_bf16 v[16:19], v[40:43], v[44:47], v[16:19]
	ds_read2_b64 v[40:43], v164 offset1:4
	s_waitcnt lgkmcnt(1)
	v_mfma_f32_16x16x32_bf16 v[20:23], v[72:75], v[44:47], v[20:23]
	ds_read2_b64 v[72:75], v165 offset0:128 offset1:132
	s_waitcnt lgkmcnt(1)
	v_mfma_f32_16x16x32_bf16 v[24:27], v[40:43], v[44:47], v[24:27]
	ds_read2_b64 v[40:43], v166 offset0:160 offset1:164
	s_waitcnt lgkmcnt(1)
	v_mfma_f32_16x16x32_bf16 v[52:55], v[72:75], v[44:47], v[52:55]
	ds_read2_b64 v[72:75], v167 offset0:192 offset1:196
	s_waitcnt lgkmcnt(1)
	v_mfma_f32_16x16x32_bf16 v[40:43], v[40:43], v[44:47], v[56:59]
	s_nop 2
	ds_read2_b64 v[56:59], v168 offset1:4
	s_waitcnt lgkmcnt(1)
; #define LAS __attribute__((address_space(3)))
; __device__ __forceinline__ f32x4 mfma16(bf16x8 a, bf16x8 b, f32x4 c) { return __builtin_amdgcn_mfma_f32_16x16x32_bf16(a, b, c, 0, 0, 0); }
; __device__ __forceinline__ void xattn_unit(const Args& a, LAS unsigned char* lds, int b, int h, int qb, int tid, int wave, int lane) {
;     ...
;                 l += __shfl_xor(l, 16); l += __shfl_xor(l, 32);
;     ...
;         } else {
;             const int mt = j - 4;
; #pragma unroll
;             for (int dt = 0; dt < 16; ++dt) {
;                 const LAS bf16* vr = base + (16 * dt + fr) * VS + 4 * fq;
;                 O[dt] = mfma16(cat8(*(const LAS u32x2*)vr, *(const LAS u32x2*)(vr + 16)), pf[2 * mt], O[dt]);
;                 O[dt] = mfma16(cat8(*(const LAS u32x2*)(vr + 32), *(const LAS u32x2*)(vr + 48)), pf[2 * mt + 1], O[dt]);
;             }
;         }
;         if (j < 7) lstore(j + 1);
;         __syncthreads();
	v_mfma_f32_16x16x32_bf16 v[60:63], v[72:75], v[44:47], v[60:63]
	ds_read2_b64 v[72:75], v169 offset1:4
	s_waitcnt lgkmcnt(1)
	v_mfma_f32_16x16x32_bf16 v[56:59], v[56:59], v[44:47], v[76:79]
	s_nop 2
	ds_read2_b64 v[76:79], v170 offset0:32 offset1:36
	s_waitcnt lgkmcnt(1)
	v_mfma_f32_16x16x32_bf16 v[72:75], v[72:75], v[44:47], v[80:83]
	s_nop 2
	ds_read2_b64 v[80:83], v171 offset0:64 offset1:68
	s_waitcnt lgkmcnt(1)
	v_mfma_f32_16x16x32_bf16 v[76:79], v[76:79], v[44:47], v[84:87]
	s_nop 2
	ds_read2_b64 v[84:87], v172 offset1:4
	s_waitcnt lgkmcnt(1)
	v_mfma_f32_16x16x32_bf16 v[80:83], v[80:83], v[44:47], v[88:91]
	s_nop 2
	ds_read2_b64 v[88:91], v173 offset0:128 offset1:132
	s_waitcnt lgkmcnt(1)
	v_mfma_f32_16x16x32_bf16 v[84:87], v[84:87], v[44:47], v[92:95]
	s_nop 2
	ds_read2_b64 v[92:95], v177 offset0:160 offset1:164
	s_waitcnt lgkmcnt(1)
	v_mfma_f32_16x16x32_bf16 v[68:71], v[88:91], v[44:47], v[68:71]
	ds_read2_b64 v[88:91], v175 offset0:192 offset1:196
	s_waitcnt lgkmcnt(1)
	v_mfma_f32_16x16x32_bf16 v[28:31], v[92:95], v[44:47], v[28:31]
	ds_read2_b64 v[92:95], v174 offset1:4
	s_waitcnt lgkmcnt(1)
	v_mfma_f32_16x16x32_bf16 v[64:67], v[88:91], v[44:47], v[64:67]
	ds_read2_b64 v[88:91], v138 offset0:8 offset1:12
	s_waitcnt lgkmcnt(1)
	v_mfma_f32_16x16x32_bf16 v[36:39], v[92:95], v[44:47], v[36:39]
	ds_read2_b64 v[44:47], v145 offset0:40 offset1:44
	s_waitcnt lgkmcnt(1)
	v_mfma_f32_16x16x32_bf16 v[12:15], v[88:91], v[48:51], v[12:15]
	ds_read2_b64 v[88:91], v147 offset0:72 offset1:76
	s_waitcnt lgkmcnt(1)
	v_mfma_f32_16x16x32_bf16 v[16:19], v[44:47], v[48:51], v[16:19]
	ds_read2_b64 v[44:47], v164 offset0:8 offset1:12
	s_waitcnt lgkmcnt(1)
	v_mfma_f32_16x16x32_bf16 v[20:23], v[88:91], v[48:51], v[20:23]
	ds_read2_b64 v[88:91], v165 offset0:136 offset1:140
	s_waitcnt lgkmcnt(1)
	v_mfma_f32_16x16x32_bf16 v[24:27], v[44:47], v[48:51], v[24:27]
	ds_read2_b64 v[44:47], v166 offset0:168 offset1:172
	s_waitcnt lgkmcnt(1)
	v_mfma_f32_16x16x32_bf16 v[52:55], v[88:91], v[48:51], v[52:55]
	ds_read2_b64 v[88:91], v167 offset0:200 offset1:204
	ds_read2_b64 v[92:95], v168 offset0:8 offset1:12
	ds_read2_b64 v[96:99], v169 offset0:8 offset1:12
	s_waitcnt lgkmcnt(3)
	v_mfma_f32_16x16x32_bf16 v[40:43], v[44:47], v[48:51], v[40:43]
	global_load_dwordx4 v[44:47], v205, s[6:7] offset:384
	s_waitcnt lgkmcnt(2)
	v_mfma_f32_16x16x32_bf16 v[60:63], v[88:91], v[48:51], v[60:63]
	global_load_dwordx4 v[88:91], v206, s[6:7] offset:384
	global_load_dwordx4 v[100:103], v207, s[6:7] offset:384
	ds_read2_b64 v[104:107], v170 offset0:40 offset1:44
	s_waitcnt lgkmcnt(2)
	v_mfma_f32_16x16x32_bf16 v[56:59], v[92:95], v[48:51], v[56:59]
	global_load_dwordx4 v[92:95], v208, s[6:7] offset:384
	ds_read2_b64 v[120:123], v171 offset0:72 offset1:76
	ds_read2_b64 v[128:131], v172 offset0:8 offset1:12
	s_waitcnt lgkmcnt(1)
	v_mfma_f32_16x16x32_bf16 v[80:83], v[120:123], v[48:51], v[80:83]
	v_add_f32_e32 v120, v188, v178
	v_add_f32_e32 v120, v189, v120
	v_add_f32_e32 v120, v190, v120
	v_mfma_f32_16x16x32_bf16 v[72:75], v[96:99], v[48:51], v[72:75]
	ds_read2_b64 v[96:99], v173 offset0:136 offset1:140
	ds_read2_b64 v[132:135], v177 offset0:168 offset1:172
	ds_read2_b64 v[140:143], v175 offset0:200 offset1:204
	v_add_f32_e32 v120, v191, v120
	v_add_f32_e32 v120, v192, v120
	v_add_f32_e32 v120, v193, v120
	v_mfma_f32_16x16x32_bf16 v[76:79], v[104:107], v[48:51], v[76:79]
	ds_read2_b64 v[104:107], v174 offset0:8 offset1:12
	s_waitcnt vmcnt(7)
	ds_write_b128 v176, v[108:111]
	s_waitcnt vmcnt(6)
	ds_write_b128 v160, v[112:115]
	s_waitcnt vmcnt(5)
	ds_write_b128 v161, v[124:127]
	s_waitcnt vmcnt(4)
	ds_write_b128 v148, v[116:119]
	s_waitcnt lgkmcnt(0)
	v_mfma_f32_16x16x32_bf16 v[68:71], v[96:99], v[48:51], v[68:71]
	v_add_f32_e32 v96, v194, v120
	v_add_f32_e32 v96, v195, v96
	v_add_f32_e32 v96, v196, v96
	v_add_f32_e32 v96, v197, v96
	v_add_f32_e32 v96, v198, v96
	v_add_f32_e32 v96, v199, v96
	v_add_f32_e32 v96, v200, v96
	v_add_f32_e32 v96, v202, v96
	v_add_f32_e32 v96, v203, v96
	v_mfma_f32_16x16x32_bf16 v[84:87], v[128:131], v[48:51], v[84:87]
	s_barrier
	v_mfma_f32_16x16x32_bf16 v[28:31], v[132:135], v[48:51], v[28:31]
	v_mfma_f32_16x16x32_bf16 v[64:67], v[140:143], v[48:51], v[64:67]
	v_mfma_f32_16x16x32_bf16 v[36:39], v[104:107], v[48:51], v[36:39]
	v_add_f32_e32 v48, v209, v96
	v_add_f32_e32 v48, v210, v48
	v_add_f32_e32 v48, v213, v48
	v_add_f32_e32 v48, v214, v48
	v_add_f32_e32 v48, v215, v48
	v_add_f32_e32 v48, v216, v48
	v_add_f32_e32 v48, v217, v48
	v_add_f32_e32 v48, v218, v48
	v_add_f32_e32 v48, v219, v48
	v_add_f32_e32 v48, v220, v48
	v_add_f32_e32 v48, v221, v48
	v_add_f32_e32 v48, v222, v48
	v_add_f32_e32 v48, v223, v48
	v_add_f32_e32 v48, v224, v48
	v_add_f32_e32 v48, v225, v48
	v_add_f32_e32 v48, v228, v48
	v_add_f32_e32 v48, v229, v48
	v_add_f32_e32 v48, v230, v48
	v_add_f32_e32 v48, v231, v48
	v_add_f32_e32 v48, v232, v48
	v_add_f32_e32 v48, v233, v48
	v_add_f32_e32 v48, v234, v48
	v_add_f32_e32 v48, v235, v48
	v_add_f32_e32 v48, v236, v48
	v_add_f32_e32 v48, v237, v48
	v_add_f32_e32 v48, v238, v48
	v_add_f32_e32 v48, v239, v48
	v_add_f32_e32 v48, v240, v48
	v_add_f32_e32 v48, v241, v48
	v_add_f32_e32 v48, v242, v48
	v_add_f32_e32 v48, v243, v48
	s_nop 0
	s_waitcnt lgkmcnt(0)
	v_mov_b32_e32 v49, v48
	s_nop 1
	v_permlane16_swap_b32_e32 v48, v49
	v_add_f32_e32 v48, v48, v49
	s_nop 0
	s_waitcnt lgkmcnt(0)
; #define LAS __attribute__((address_space(3)))
; __device__ __forceinline__ f32x4 mfma16(bf16x8 a, bf16x8 b, f32x4 c) { return __builtin_amdgcn_mfma_f32_16x16x32_bf16(a, b, c, 0, 0, 0); }
; __device__ __forceinline__ void xattn_unit(const Args& a, LAS unsigned char* lds, int b, int h, int qb, int tid, int wave, int lane) {
;     ...
;                 l += __shfl_xor(l, 16); l += __shfl_xor(l, 32);
;     ...
;             const int mt = j - 4;
; #pragma unroll
;             for (int dt = 0; dt < 16; ++dt) {
;                 const LAS bf16* vr = base + (16 * dt + fr) * VS + 4 * fq;
;                 O[dt] = mfma16(cat8(*(const LAS u32x2*)vr, *(const LAS u32x2*)(vr + 16)), pf[2 * mt], O[dt]);
;                 O[dt] = mfma16(cat8(*(const LAS u32x2*)(vr + 32), *(const LAS u32x2*)(vr + 48)), pf[2 * mt + 1], O[dt]);
;             }
;         }
;         if (j < 7) lstore(j + 1);
;         __syncthreads();
;     }
;     const float il = 1.f / l;
	v_mov_b32_e32 v49, v48
	s_nop 1
	v_permlane32_swap_b32_e32 v48, v49
	v_add_f32_e32 v48, v48, v49
	v_div_scale_f32 v49, s[6:7], v48, v48, 1.0
	v_rcp_f32_e32 v51, v49
	v_div_scale_f32 v50, vcc, 1.0, v48, 1.0
	v_fma_f32 v96, -v49, v51, 1.0
	v_fmac_f32_e32 v51, v96, v51
	v_mul_f32_e32 v96, v50, v51
	v_fma_f32 v97, -v49, v96, v50
	v_fmac_f32_e32 v96, v97, v51
	v_fma_f32 v49, -v49, v96, v50
	v_div_fmas_f32 v49, v49, v51, v96
	v_div_fixup_f32 v120, v49, v48, 1.0
	ds_read2_b64 v[48:51], v156 offset1:4
	ds_read2_b64 v[96:99], v163 offset0:32 offset1:36
	s_waitcnt lgkmcnt(1)
	v_mfma_f32_16x16x32_bf16 v[12:15], v[48:51], v[32:35], v[12:15]
	ds_read2_b64 v[48:51], v162 offset0:64 offset1:68
	s_waitcnt lgkmcnt(1)
	v_mfma_f32_16x16x32_bf16 v[16:19], v[96:99], v[32:35], v[16:19]
	ds_read2_b64 v[96:99], v151 offset1:4
	s_waitcnt lgkmcnt(1)
	v_mfma_f32_16x16x32_bf16 v[20:23], v[48:51], v[32:35], v[20:23]
	ds_read2_b64 v[48:51], v158 offset0:128 offset1:132
	s_waitcnt lgkmcnt(1)
	v_mfma_f32_16x16x32_bf16 v[24:27], v[96:99], v[32:35], v[24:27]
	ds_read2_b64 v[96:99], v159 offset0:160 offset1:164
	s_waitcnt lgkmcnt(1)
	v_mfma_f32_16x16x32_bf16 v[48:51], v[48:51], v[32:35], v[52:55]
	s_nop 2
	ds_read2_b64 v[52:55], v157 offset0:192 offset1:196
	s_waitcnt lgkmcnt(1)
	v_mfma_f32_16x16x32_bf16 v[40:43], v[96:99], v[32:35], v[40:43]
	ds_read2_b64 v[96:99], v152 offset1:4
	s_waitcnt lgkmcnt(1)
	v_mfma_f32_16x16x32_bf16 v[52:55], v[52:55], v[32:35], v[60:63]
	s_nop 2
	ds_read2_b64 v[60:63], v154 offset1:4
	s_waitcnt lgkmcnt(1)
	v_mfma_f32_16x16x32_bf16 v[56:59], v[96:99], v[32:35], v[56:59]
	ds_read2_b64 v[96:99], v155 offset0:32 offset1:36
	s_waitcnt lgkmcnt(1)
	v_mfma_f32_16x16x32_bf16 v[60:63], v[60:63], v[32:35], v[72:75]
	s_nop 2
	ds_read2_b64 v[72:75], v153 offset0:64 offset1:68
	s_waitcnt lgkmcnt(1)
	v_mfma_f32_16x16x32_bf16 v[76:79], v[96:99], v[32:35], v[76:79]
	ds_read2_b64 v[96:99], v150 offset1:4
	s_waitcnt lgkmcnt(1)
	v_mfma_f32_16x16x32_bf16 v[72:75], v[72:75], v[32:35], v[80:83]
	s_nop 2
	ds_read2_b64 v[80:83], v139 offset0:128 offset1:132
	s_waitcnt lgkmcnt(1)
	v_mfma_f32_16x16x32_bf16 v[84:87], v[96:99], v[32:35], v[84:87]
	ds_read2_b64 v[96:99], v146 offset0:160 offset1:164
	s_waitcnt lgkmcnt(1)
	v_mfma_f32_16x16x32_bf16 v[68:71], v[80:83], v[32:35], v[68:71]
	ds_read2_b64 v[80:83], v144 offset0:192 offset1:196
	s_waitcnt lgkmcnt(1)
	v_mfma_f32_16x16x32_bf16 v[28:31], v[96:99], v[32:35], v[28:31]
	ds_read2_b64 v[96:99], v149 offset1:4
	s_waitcnt lgkmcnt(1)
	v_mfma_f32_16x16x32_bf16 v[64:67], v[80:83], v[32:35], v[64:67]
	ds_read2_b64 v[80:83], v156 offset0:8 offset1:12
	s_waitcnt lgkmcnt(1)
	v_mfma_f32_16x16x32_bf16 v[32:35], v[96:99], v[32:35], v[36:39]
	s_nop 2
	ds_read2_b64 v[36:39], v163 offset0:40 offset1:44
	s_waitcnt lgkmcnt(1)
	v_mfma_f32_16x16x32_bf16 v[12:15], v[80:83], v[8:11], v[12:15]
	ds_read2_b64 v[80:83], v162 offset0:72 offset1:76
	s_waitcnt lgkmcnt(1)
	v_mfma_f32_16x16x32_bf16 v[16:19], v[36:39], v[8:11], v[16:19]
	ds_read2_b64 v[36:39], v151 offset0:8 offset1:12
	s_waitcnt lgkmcnt(1)
	v_mfma_f32_16x16x32_bf16 v[20:23], v[80:83], v[8:11], v[20:23]
	ds_read2_b64 v[80:83], v158 offset0:136 offset1:140
	s_waitcnt lgkmcnt(1)
	v_mfma_f32_16x16x32_bf16 v[24:27], v[36:39], v[8:11], v[24:27]
	ds_read2_b64 v[36:39], v159 offset0:168 offset1:172
	s_waitcnt lgkmcnt(1)
	v_mfma_f32_16x16x32_bf16 v[48:51], v[80:83], v[8:11], v[48:51]
	ds_read2_b64 v[80:83], v157 offset0:200 offset1:204
	s_waitcnt lgkmcnt(1)
	v_mfma_f32_16x16x32_bf16 v[36:39], v[36:39], v[8:11], v[40:43]
	s_nop 2
	ds_read2_b64 v[40:43], v152 offset0:8 offset1:12
	s_waitcnt lgkmcnt(1)
	v_mfma_f32_16x16x32_bf16 v[52:55], v[80:83], v[8:11], v[52:55]
	ds_read2_b64 v[80:83], v154 offset0:8 offset1:12
	s_waitcnt lgkmcnt(1)
	v_mfma_f32_16x16x32_bf16 v[40:43], v[40:43], v[8:11], v[56:59]
	s_nop 2
	ds_read2_b64 v[56:59], v155 offset0:40 offset1:44
	s_waitcnt lgkmcnt(1)
	v_mfma_f32_16x16x32_bf16 v[60:63], v[80:83], v[8:11], v[60:63]
	ds_read2_b64 v[80:83], v153 offset0:72 offset1:76
	s_waitcnt lgkmcnt(1)
	v_mfma_f32_16x16x32_bf16 v[56:59], v[56:59], v[8:11], v[76:79]
	s_nop 2
	ds_read2_b64 v[76:79], v150 offset0:8 offset1:12
	s_waitcnt lgkmcnt(1)
	v_mfma_f32_16x16x32_bf16 v[72:75], v[80:83], v[8:11], v[72:75]
	ds_read2_b64 v[80:83], v139 offset0:136 offset1:140
	ds_read2_b64 v[96:99], v146 offset0:168 offset1:172
	s_waitcnt lgkmcnt(2)
	v_mfma_f32_16x16x32_bf16 v[76:79], v[76:79], v[8:11], v[84:87]
	s_nop 2
	ds_read2_b64 v[84:87], v144 offset0:200 offset1:204
	ds_read2_b64 v[104:107], v149 offset0:8 offset1:12
	s_waitcnt vmcnt(3)
	ds_write_b128 v176, v[44:47] offset:36864
	s_waitcnt vmcnt(2)
	ds_write_b128 v160, v[88:91] offset:36864
	s_waitcnt vmcnt(1)
	ds_write_b128 v161, v[100:103] offset:36864
	s_waitcnt vmcnt(0)
	ds_write_b128 v148, v[92:95] offset:36864
	s_waitcnt lgkmcnt(7)
	v_mfma_f32_16x16x32_bf16 v[44:47], v[80:83], v[8:11], v[68:71]
	s_waitcnt lgkmcnt(0)
	s_barrier
; #define LAS __attribute__((address_space(3)))
; __device__ __forceinline__ unsigned pk2(float lo, float hi) { f32x2_t v = {lo, hi}; bf16x2_t b = __builtin_convertvector(v, bf16x2_t); return __builtin_bit_cast(unsigned, b); }
; __device__ __forceinline__ f32x4 mfma16(bf16x8 a, bf16x8 b, f32x4 c) { return __builtin_amdgcn_mfma_f32_16x16x32_bf16(a, b, c, 0, 0, 0); }
; __device__ __forceinline__ void xattn_unit(const Args& a, LAS unsigned char* lds, int b, int h, int qb, int tid, int wave, int lane) {
;     ...
;             const int mt = j - 4;
; #pragma unroll
;             for (int dt = 0; dt < 16; ++dt) {
;                 const LAS bf16* vr = base + (16 * dt + fr) * VS + 4 * fq;
;                 O[dt] = mfma16(cat8(*(const LAS u32x2*)vr, *(const LAS u32x2*)(vr + 16)), pf[2 * mt], O[dt]);
;                 O[dt] = mfma16(cat8(*(const LAS u32x2*)(vr + 32), *(const LAS u32x2*)(vr + 48)), pf[2 * mt + 1], O[dt]);
;             }
;         }
;         if (j < 7) lstore(j + 1);
;         __syncthreads();
;     }
;     const float il = 1.f / l;
; #pragma unroll
;     for (int dt = 0; dt < 16; ++dt) { u32x2 w; w.x = pk2(O[dt][0] * il, O[dt][1] * il); w.y = pk2(O[dt][2] * il, O[dt][3] * il);
	v_mfma_f32_16x16x32_bf16 v[28:31], v[96:99], v[8:11], v[28:31]
	ds_read2_b64 v[68:71], v138 offset1:4
	v_mfma_f32_16x16x32_bf16 v[64:67], v[84:87], v[8:11], v[64:67]
	v_mfma_f32_16x16x32_bf16 v[8:11], v[104:107], v[8:11], v[32:35]
	s_nop 2
	ds_read2_b64 v[32:35], v145 offset0:32 offset1:36
	s_waitcnt lgkmcnt(1)
	v_mfma_f32_16x16x32_bf16 v[12:15], v[68:71], v[4:7], v[12:15]
	ds_read2_b64 v[68:71], v147 offset0:64 offset1:68
	s_waitcnt lgkmcnt(1)
	v_mfma_f32_16x16x32_bf16 v[16:19], v[32:35], v[4:7], v[16:19]
	ds_read2_b64 v[32:35], v164 offset1:4
	s_waitcnt lgkmcnt(1)
	v_mfma_f32_16x16x32_bf16 v[20:23], v[68:71], v[4:7], v[20:23]
	ds_read2_b64 v[68:71], v165 offset0:128 offset1:132
	s_waitcnt lgkmcnt(1)
	v_mfma_f32_16x16x32_bf16 v[24:27], v[32:35], v[4:7], v[24:27]
	ds_read2_b64 v[32:35], v166 offset0:160 offset1:164
	s_waitcnt lgkmcnt(1)
	v_mfma_f32_16x16x32_bf16 v[48:51], v[68:71], v[4:7], v[48:51]
	ds_read2_b64 v[68:71], v167 offset0:192 offset1:196
	s_waitcnt lgkmcnt(1)
	v_mfma_f32_16x16x32_bf16 v[32:35], v[32:35], v[4:7], v[36:39]
	s_nop 2
	ds_read2_b64 v[36:39], v168 offset1:4
	s_waitcnt lgkmcnt(1)
	v_mfma_f32_16x16x32_bf16 v[52:55], v[68:71], v[4:7], v[52:55]
	ds_read2_b64 v[68:71], v169 offset1:4
	s_waitcnt lgkmcnt(1)
	v_mfma_f32_16x16x32_bf16 v[36:39], v[36:39], v[4:7], v[40:43]
	s_nop 2
	ds_read2_b64 v[40:43], v170 offset0:32 offset1:36
	s_waitcnt lgkmcnt(1)
	v_mfma_f32_16x16x32_bf16 v[60:63], v[68:71], v[4:7], v[60:63]
	ds_read2_b64 v[68:71], v171 offset0:64 offset1:68
	s_waitcnt lgkmcnt(1)
	v_mfma_f32_16x16x32_bf16 v[40:43], v[40:43], v[4:7], v[56:59]
	s_nop 2
	ds_read2_b64 v[56:59], v172 offset1:4
	s_waitcnt lgkmcnt(1)
	v_mfma_f32_16x16x32_bf16 v[68:71], v[68:71], v[4:7], v[72:75]
	s_nop 2
	ds_read2_b64 v[72:75], v173 offset0:128 offset1:132
	s_waitcnt lgkmcnt(1)
	v_mfma_f32_16x16x32_bf16 v[56:59], v[56:59], v[4:7], v[76:79]
	s_nop 2
	ds_read2_b64 v[76:79], v177 offset0:160 offset1:164
	s_waitcnt lgkmcnt(1)
	v_mfma_f32_16x16x32_bf16 v[44:47], v[72:75], v[4:7], v[44:47]
	ds_read2_b64 v[72:75], v175 offset0:192 offset1:196
	s_waitcnt lgkmcnt(1)
	v_mfma_f32_16x16x32_bf16 v[28:31], v[76:79], v[4:7], v[28:31]
	ds_read2_b64 v[76:79], v174 offset1:4
	s_waitcnt lgkmcnt(1)
	v_mfma_f32_16x16x32_bf16 v[64:67], v[72:75], v[4:7], v[64:67]
	ds_read2_b64 v[72:75], v138 offset0:8 offset1:12
	s_waitcnt lgkmcnt(1)
	v_mfma_f32_16x16x32_bf16 v[4:7], v[76:79], v[4:7], v[8:11]
	s_nop 2
	ds_read2_b64 v[8:11], v145 offset0:40 offset1:44
	s_waitcnt lgkmcnt(1)
	v_mfma_f32_16x16x32_bf16 v[12:15], v[72:75], v[0:3], v[12:15]
	ds_read2_b64 v[72:75], v147 offset0:72 offset1:76
	s_waitcnt lgkmcnt(1)
	v_mfma_f32_16x16x32_bf16 v[8:11], v[8:11], v[0:3], v[16:19]
	s_nop 2
	ds_read2_b64 v[16:19], v164 offset0:8 offset1:12
	s_waitcnt lgkmcnt(1)
	v_mfma_f32_16x16x32_bf16 v[20:23], v[72:75], v[0:3], v[20:23]
	ds_read2_b64 v[72:75], v165 offset0:136 offset1:140
	s_nop 0
	v_pk_mul_f32 v[8:9], v[120:121], v[8:9] op_sel_hi:[0,1]
	v_pk_mul_f32 v[10:11], v[120:121], v[10:11] op_sel_hi:[0,1]
	s_waitcnt lgkmcnt(1)
	v_mfma_f32_16x16x32_bf16 v[16:19], v[16:19], v[0:3], v[24:27]
	s_nop 2
	ds_read2_b64 v[24:27], v166 offset0:168 offset1:172
	s_waitcnt lgkmcnt(1)
	v_mfma_f32_16x16x32_bf16 v[48:51], v[72:75], v[0:3], v[48:51]
	ds_read2_b64 v[72:75], v167 offset0:200 offset1:204
	s_nop 0
	v_pk_mul_f32 v[16:17], v[120:121], v[16:17] op_sel_hi:[0,1]
	v_pk_mul_f32 v[18:19], v[120:121], v[18:19] op_sel_hi:[0,1]
	s_waitcnt lgkmcnt(1)
	v_mfma_f32_16x16x32_bf16 v[24:27], v[24:27], v[0:3], v[32:35]
	s_nop 2
	ds_read2_b64 v[32:35], v168 offset0:8 offset1:12
	s_waitcnt lgkmcnt(1)
	v_mfma_f32_16x16x32_bf16 v[52:55], v[72:75], v[0:3], v[52:55]
	ds_read2_b64 v[72:75], v169 offset0:8 offset1:12
	s_nop 0
	v_pk_mul_f32 v[24:25], v[120:121], v[24:25] op_sel_hi:[0,1]
	v_pk_mul_f32 v[26:27], v[120:121], v[26:27] op_sel_hi:[0,1]
	s_waitcnt lgkmcnt(1)
	v_mfma_f32_16x16x32_bf16 v[32:35], v[32:35], v[0:3], v[36:39]
	s_nop 2
	ds_read2_b64 v[36:39], v170 offset0:40 offset1:44
	s_waitcnt lgkmcnt(1)
	v_mfma_f32_16x16x32_bf16 v[60:63], v[72:75], v[0:3], v[60:63]
	ds_read2_b64 v[72:75], v171 offset0:72 offset1:76
	s_nop 0
	v_pk_mul_f32 v[32:33], v[120:121], v[32:33] op_sel_hi:[0,1]
	v_pk_mul_f32 v[34:35], v[120:121], v[34:35] op_sel_hi:[0,1]
	s_waitcnt lgkmcnt(1)
	v_mfma_f32_16x16x32_bf16 v[36:39], v[36:39], v[0:3], v[40:43]
	s_nop 2
	ds_read2_b64 v[40:43], v172 offset0:8 offset1:12
	s_waitcnt lgkmcnt(1)
	v_mfma_f32_16x16x32_bf16 v[68:71], v[72:75], v[0:3], v[68:71]
	ds_read2_b64 v[72:75], v173 offset0:136 offset1:140
	s_nop 0
	v_pk_mul_f32 v[36:37], v[120:121], v[36:37] op_sel_hi:[0,1]
	v_pk_mul_f32 v[38:39], v[120:121], v[38:39] op_sel_hi:[0,1]
	s_waitcnt lgkmcnt(1)
	v_mfma_f32_16x16x32_bf16 v[40:43], v[40:43], v[0:3], v[56:59]
	s_nop 2
	ds_read2_b64 v[56:59], v177 offset0:168 offset1:172
	s_waitcnt lgkmcnt(1)
	v_mfma_f32_16x16x32_bf16 v[44:47], v[72:75], v[0:3], v[44:47]
	ds_read2_b64 v[72:75], v175 offset0:200 offset1:204
	s_nop 0
	v_pk_mul_f32 v[40:41], v[120:121], v[40:41] op_sel_hi:[0,1]
	v_pk_mul_f32 v[42:43], v[120:121], v[42:43] op_sel_hi:[0,1]
	s_waitcnt lgkmcnt(1)
	v_mfma_f32_16x16x32_bf16 v[28:31], v[56:59], v[0:3], v[28:31]
	ds_read2_b64 v[56:59], v174 offset0:8 offset1:12
	s_nop 0
	v_pk_mul_f32 v[44:45], v[120:121], v[44:45] op_sel_hi:[0,1]
	v_pk_mul_f32 v[46:47], v[120:121], v[46:47] op_sel_hi:[0,1]
	s_waitcnt lgkmcnt(1)
	v_mfma_f32_16x16x32_bf16 v[64:67], v[72:75], v[0:3], v[64:67]
	s_nop 1
	v_mul_f32_e64 v28, v120, v28
	v_mul_f32_e64 v29, v120, v29
	v_pk_mul_f32 v[30:31], v[120:121], v[30:31] op_sel_hi:[0,1]
	s_waitcnt lgkmcnt(0)
	v_mfma_f32_16x16x32_bf16 v[0:3], v[56:59], v[0:3], v[4:7]
	v_mul_f32_e64 v56, v120, v68
	v_mul_f32_e64 v57, v120, v69
	s_nop 0
	v_pk_mul_f32 v[4:5], v[120:121], v[12:13] op_sel_hi:[0,1]
	v_pk_mul_f32 v[6:7], v[120:121], v[14:15] op_sel_hi:[0,1]
	v_pk_mul_f32 v[12:13], v[120:121], v[20:21] op_sel_hi:[0,1]
	v_pk_mul_f32 v[14:15], v[120:121], v[22:23] op_sel_hi:[0,1]
	v_pk_mul_f32 v[20:21], v[120:121], v[48:49] op_sel_hi:[0,1]
	v_pk_mul_f32 v[22:23], v[120:121], v[50:51] op_sel_hi:[0,1]
	v_pk_mul_f32 v[48:49], v[120:121], v[52:53] op_sel_hi:[0,1]
	v_pk_mul_f32 v[50:51], v[120:121], v[54:55] op_sel_hi:[0,1]
	v_pk_mul_f32 v[52:53], v[120:121], v[60:61] op_sel_hi:[0,1]
	v_pk_mul_f32 v[54:55], v[120:121], v[62:63] op_sel_hi:[0,1]
	v_pk_mul_f32 v[58:59], v[120:121], v[70:71] op_sel_hi:[0,1]
	v_pk_mul_f32 v[60:61], v[120:121], v[64:65] op_sel_hi:[0,1]
	v_pk_mul_f32 v[62:63], v[120:121], v[66:67] op_sel_hi:[0,1]
	v_pk_mul_f32 v[0:1], v[120:121], v[0:1] op_sel_hi:[0,1]
	v_pk_mul_f32 v[2:3], v[120:121], v[2:3] op_sel_hi:[0,1]
	v_cvt_pk_bf16_f32 v4, v4, v5
	v_cvt_pk_bf16_f32 v5, v6, v7
	s_barrier
; #define GAS __attribute__((address_space(1)))
; __device__ __forceinline__ unsigned pk2(float lo, float hi) { f32x2_t v = {lo, hi}; bf16x2_t b = __builtin_convertvector(v, bf16x2_t); return __builtin_bit_cast(unsigned, b); }
; __device__ __forceinline__ void xattn_unit(const Args& a, LAS unsigned char* lds, int b, int h, int qb, int tid, int wave, int lane) {
;     ...
;     const float il = 1.f / l;
; #pragma unroll
;     for (int dt = 0; dt < 16; ++dt) { u32x2 w; w.x = pk2(O[dt][0] * il, O[dt][1] * il); w.y = pk2(O[dt][2] * il, O[dt][3] * il);
;         *(GAS u32x2*)(XO + qrow * DM + h * 256 + 16 * dt + 4 * fq) = w; }
	v_cvt_pk_bf16_f32 v6, v8, v9
	v_cvt_pk_bf16_f32 v7, v10, v11
	v_cvt_pk_bf16_f32 v8, v12, v13
	v_cvt_pk_bf16_f32 v9, v14, v15
	v_cvt_pk_bf16_f32 v10, v16, v17
	v_cvt_pk_bf16_f32 v11, v18, v19
	v_cvt_pk_bf16_f32 v12, v20, v21
	v_cvt_pk_bf16_f32 v13, v22, v23
	v_cvt_pk_bf16_f32 v14, v24, v25
	v_cvt_pk_bf16_f32 v15, v26, v27
	v_cvt_pk_bf16_f32 v16, v48, v49
	v_cvt_pk_bf16_f32 v17, v50, v51
	v_cvt_pk_bf16_f32 v18, v32, v33
	v_cvt_pk_bf16_f32 v19, v34, v35
	v_cvt_pk_bf16_f32 v20, v52, v53
	v_cvt_pk_bf16_f32 v21, v54, v55
	v_cvt_pk_bf16_f32 v22, v36, v37
	v_cvt_pk_bf16_f32 v23, v38, v39
	v_cvt_pk_bf16_f32 v24, v56, v57
	v_cvt_pk_bf16_f32 v25, v58, v59
	v_cvt_pk_bf16_f32 v26, v40, v41
	v_cvt_pk_bf16_f32 v27, v42, v43
	v_cvt_pk_bf16_f32 v36, v44, v45
	v_cvt_pk_bf16_f32 v37, v46, v47
	v_cvt_pk_bf16_f32 v38, v28, v29
	v_cvt_pk_bf16_f32 v39, v30, v31
	v_cvt_pk_bf16_f32 v40, v60, v61
	v_cvt_pk_bf16_f32 v41, v62, v63
	v_cvt_pk_bf16_f32 v42, v0, v1
	v_cvt_pk_bf16_f32 v43, v2, v3
	v_bfe_u32 v44, v252, 4, 1
	v_mul_u32_u24_e32 v44, 24, v44
	v_mov_b32_e32 v45, 0
	v_lshl_add_u64 v[44:45], v[136:137], 0, v[44:45]
	v_permlane16_swap_b32_e32 v4, v6
	v_permlane16_swap_b32_e32 v5, v7
	v_permlane16_swap_b32_e32 v8, v10
	v_permlane16_swap_b32_e32 v9, v11
	v_permlane16_swap_b32_e32 v12, v14
	v_permlane16_swap_b32_e32 v13, v15
	v_permlane16_swap_b32_e32 v16, v18
	v_permlane16_swap_b32_e32 v17, v19
	v_permlane16_swap_b32_e32 v20, v22
	v_permlane16_swap_b32_e32 v21, v23
	v_permlane16_swap_b32_e32 v24, v26
	v_permlane16_swap_b32_e32 v25, v27
	v_permlane16_swap_b32_e32 v36, v38
	v_permlane16_swap_b32_e32 v37, v39
	v_permlane16_swap_b32_e32 v40, v42
	v_permlane16_swap_b32_e32 v41, v43
	global_store_dwordx4 v[44:45], v[4:7], off
	global_store_dwordx4 v[44:45], v[8:11], off offset:64
	global_store_dwordx4 v[44:45], v[12:15], off offset:128
	global_store_dwordx4 v[44:45], v[16:19], off offset:192
	global_store_dwordx4 v[44:45], v[20:23], off offset:256
	global_store_dwordx4 v[44:45], v[24:27], off offset:320
	global_store_dwordx4 v[44:45], v[36:39], off offset:384
	global_store_dwordx4 v[44:45], v[40:43], off offset:448
	s_cbranch_scc0 .LBB0_1518

; #define GAS __attribute__((address_space(1)))
; #define LDPTR(i) ({ volatile LAS unsigned* p_ = (volatile LAS unsigned*)(lds + 131072 + 8 * (i)); const unsigned lo_ = __builtin_amdgcn_readfirstlane(p_[0]), hi_ = __builtin_amdgcn_readfirstlane(p_[1]); (const GAS float*)(((unsigned long long)hi_ << 32) | lo_); })
; __global__ void __launch_bounds__(512, 2) mk_fwd(Args a) {
;     ...
;     {
;         int tid13 = threadIdx.x; asm volatile("" : "+v"(tid13)); const int lane = tid13 & 63;
;         const GAS float* parts = (const GAS float*)(ws + WS_PARTD); const GAS float* fingp = LDPTR(6);
;         const GAS bf16* hbp = (const GAS bf16*)(ws + WS_HB);
;         f32x4 gg[4];
; #pragma unroll
;         for (int j = 0; j < 4; ++j) gg[j] = ((const GAS f32x4*)fingp)[lane + 64 * j];
;         for (int m0 = 2 * (vb * 8 + wave); m0 < NT; m0 += 2 * G * 8) {
;             u32x2 hw[2][4]; float sp[2];
; #pragma unroll
;             for (int rr = 0; rr < 2; ++rr) { const int m = m0 + rr; sp[rr] = lane < 16 ? parts[(size_t)m * 16 + lane] : 0.f; const GAS u32x2* hr = (const GAS u32x2*)(hbp + (size_t)m * DM) + lane;
; #pragma unroll
;                 for (int j = 0; j < 4; ++j) hw[rr][j] = __builtin_nontemporal_load(&hr[64 * j]); }
; #pragma unroll
;             for (int rr = 0; rr < 2; ++rr) { const int m = m0 + rr; const float s = wave_sum(sp[rr]); const float rs = rsqrtf(s * (1.f / 1024.f) + EPS);
;                 GAS f32x4* o = (GAS f32x4*)(a.out + (size_t)m * DM) + lane;
; #pragma unroll
;                 for (int j = 0; j < 4; ++j) { const u32x2 w = hw[rr][j]; const f32x4 v = {bflo(w.x), bfhi(w.x), bflo(w.y), bfhi(w.y)}; __builtin_nontemporal_store(v * rs * gg[j], &o[64 * j]); } }
;         }
;     }
.Lp13_loop:
	s_waitcnt vmcnt(8)
	v_mov_b32_e32 v124, v24
	v_mov_b32_e32 v125, v25
	v_mov_b32_e32 v126, v26
	v_mov_b32_e32 v127, v27
	v_mov_b32_e32 v128, v28
	v_mov_b32_e32 v129, v29
	v_mov_b32_e32 v130, v30
	v_mov_b32_e32 v131, v31
	v_mov_b32_e32 v132, v32
	v_mov_b32_e32 v133, v33
	v_mov_b32_e32 v148, v48
	v_mov_b32_e32 v149, v49
	v_mov_b32_e32 v150, v50
	v_mov_b32_e32 v151, v51
	v_mov_b32_e32 v152, v52
	v_mov_b32_e32 v153, v53
	v_mov_b32_e32 v154, v54
	v_mov_b32_e32 v155, v55
	v_lshl_add_u64 v[18:19], v[18:19], 0, s[10:11]
	v_lshl_add_u64 v[20:21], v[20:21], 0, s[12:13]
	v_mov_b32_e32 v33, 0
	s_and_saveexec_b64 s[0:1], vcc
	global_load_dword v33, v[18:19], off offset:-64
	s_or_b64 exec, exec, s[0:1]
	global_load_dwordx2 v[30:31], v[20:21], off offset:-2048 nt
	global_load_dwordx2 v[28:29], v[20:21], off offset:-1536 nt
	global_load_dwordx2 v[26:27], v[20:21], off offset:-1024 nt
	global_load_dwordx2 v[24:25], v[20:21], off offset:-512 nt
	v_mov_b32_e32 v32, 0
	s_and_saveexec_b64 s[0:1], vcc
	global_load_dword v32, v[18:19], off
	s_or_b64 exec, exec, s[0:1]
	global_load_dwordx2 v[48:49], v[20:21], off nt
	global_load_dwordx2 v[50:51], v[20:21], off offset:512 nt
	global_load_dwordx2 v[52:53], v[20:21], off offset:1024 nt
	global_load_dwordx2 v[54:55], v[20:21], off offset:1536 nt
	s_nop 0
	s_nop 0
	v_lshlrev_b32_e32 v56, 16, v124
	v_and_b32_e32 v57, 0xffff0000, v124
	v_lshlrev_b32_e32 v42, 16, v130
	v_and_b32_e32 v43, 0xffff0000, v130
	s_waitcnt lgkmcnt(0)
	s_nop 1
	v_mov_b32_dpp v41, v133 quad_perm:[1,0,3,2] row_mask:0xf bank_mask:0xf
	v_mov_b32_dpp v40, v132 quad_perm:[1,0,3,2] row_mask:0xf bank_mask:0xf
	v_pk_add_f32 v[132:133], v[132:133], v[40:41]
	s_nop 0
	s_nop 0
	v_lshlrev_b32_e32 v130, 16, v131
	v_and_b32_e32 v131, 0xffff0000, v131
	v_lshlrev_b32_e32 v44, 16, v128
	v_and_b32_e32 v45, 0xffff0000, v128
	s_waitcnt lgkmcnt(0)
	s_nop 1
	v_mov_b32_dpp v41, v133 quad_perm:[2,3,0,1] row_mask:0xf bank_mask:0xf
	v_mov_b32_dpp v40, v132 quad_perm:[2,3,0,1] row_mask:0xf bank_mask:0xf
	v_pk_add_f32 v[132:133], v[132:133], v[40:41]
	s_nop 0
	s_nop 0
	v_lshlrev_b32_e32 v128, 16, v129
	v_and_b32_e32 v129, 0xffff0000, v129
	v_lshlrev_b32_e32 v46, 16, v126
	v_and_b32_e32 v47, 0xffff0000, v126
	s_waitcnt lgkmcnt(0)
	s_nop 1
	v_mov_b32_dpp v41, v133 row_half_mirror row_mask:0xf bank_mask:0xf
	v_mov_b32_dpp v40, v132 row_half_mirror row_mask:0xf bank_mask:0xf
	v_pk_add_f32 v[132:133], v[132:133], v[40:41]
	s_nop 0
	s_nop 0
	v_lshlrev_b32_e32 v126, 16, v127
	v_and_b32_e32 v127, 0xffff0000, v127
	s_add_i32 s4, s4, s6
	s_waitcnt lgkmcnt(0)
	s_nop 1
	v_mov_b32_dpp v41, v133 row_ror:8 row_mask:0xf bank_mask:0xf
	v_mov_b32_dpp v40, v132 row_ror:8 row_mask:0xf bank_mask:0xf
	v_pk_add_f32 v[132:133], v[132:133], v[40:41]
	s_nop 0
	s_nop 0
	s_cmpk_gt_i32 s4, 0x7fff
	s_waitcnt lgkmcnt(0)
	v_mov_b32_e32 v41, v133
	v_mov_b32_e32 v40, v132
	s_nop 1
	v_permlane16_swap_b32_e32 v133, v41
	v_permlane16_swap_b32_e32 v132, v40
	v_pk_add_f32 v[132:133], v[132:133], v[40:41]
	s_nop 0
	s_nop 0
	s_waitcnt lgkmcnt(0)
	v_mov_b32_e32 v41, v133
	v_mov_b32_e32 v40, v132
	s_nop 1
	v_permlane32_swap_b32_e32 v133, v41
	v_permlane32_swap_b32_e32 v132, v40
	v_pk_add_f32 v[132:133], v[132:133], v[40:41]
	s_nop 0
	v_pk_fma_f32 v[132:133], v[132:133], s[14:15], v[22:23] op_sel_hi:[1,0,0]
	s_nop 0
	v_mul_f32_e32 v124, 0x4b800000, v133
	v_cmp_gt_f32_e64 s[0:1], s5, v133
	v_mul_f32_e32 v39, 0x4b800000, v132
	v_cmp_gt_f32_e64 s[2:3], s5, v132
	v_cndmask_b32_e64 v124, v133, v124, s[0:1]
	v_rsq_f32_e32 v133, v124
	v_cndmask_b32_e64 v132, v132, v39, s[2:3]
	v_rsq_f32_e32 v39, v132
	v_lshlrev_b32_e32 v124, 16, v125
	v_mul_f32_e32 v132, 0x45800000, v133
	v_cndmask_b32_e64 v132, v133, v132, s[0:1]
	v_mul_f32_e32 v40, 0x45800000, v39
	v_and_b32_e32 v125, 0xffff0000, v125
	v_cndmask_b32_e64 v58, v39, v40, s[2:3]
	v_pk_mul_f32 v[40:41], v[132:133], v[42:43] op_sel_hi:[0,1]
	v_pk_mul_f32 v[130:131], v[132:133], v[130:131] op_sel_hi:[0,1]
	v_pk_mul_f32 v[42:43], v[132:133], v[44:45] op_sel_hi:[0,1]
	v_pk_mul_f32 v[128:129], v[132:133], v[128:129] op_sel_hi:[0,1]
	v_pk_mul_f32 v[44:45], v[132:133], v[46:47] op_sel_hi:[0,1]
	v_pk_mul_f32 v[46:47], v[132:133], v[126:127] op_sel_hi:[0,1]
	v_pk_mul_f32 v[56:57], v[132:133], v[56:57] op_sel_hi:[0,1]
	v_pk_mul_f32 v[132:133], v[132:133], v[124:125] op_sel_hi:[0,1]
	v_pk_mul_f32 v[126:127], v[2:3], v[130:131]
	v_pk_mul_f32 v[124:125], v[0:1], v[40:41]
	v_pk_mul_f32 v[130:131], v[6:7], v[128:129]
	v_pk_mul_f32 v[128:129], v[4:5], v[42:43]
	v_pk_mul_f32 v[42:43], v[10:11], v[46:47]
	v_pk_mul_f32 v[40:41], v[8:9], v[44:45]
	v_pk_mul_f32 v[46:47], v[14:15], v[132:133]
	v_pk_mul_f32 v[44:45], v[12:13], v[56:57]
	global_store_dwordx4 v[16:17], v[124:127], off offset:-4096 nt
	global_store_dwordx4 v[16:17], v[128:131], off offset:-3072 nt
	global_store_dwordx4 v[16:17], v[40:43], off offset:-2048 nt
	global_store_dwordx4 v[16:17], v[44:47], off offset:-1024 nt
	v_lshlrev_b32_e32 v124, 16, v148
	v_and_b32_e32 v125, 0xffff0000, v148
	v_lshlrev_b32_e32 v126, 16, v149
	v_and_b32_e32 v127, 0xffff0000, v149
	v_pk_mul_f32 v[124:125], v[58:59], v[124:125] op_sel_hi:[0,1]
	v_pk_mul_f32 v[126:127], v[58:59], v[126:127] op_sel_hi:[0,1]
	v_lshlrev_b32_e32 v128, 16, v150
	v_and_b32_e32 v129, 0xffff0000, v150
	v_lshlrev_b32_e32 v130, 16, v151
	v_and_b32_e32 v131, 0xffff0000, v151
	v_pk_mul_f32 v[126:127], v[2:3], v[126:127]
	v_pk_mul_f32 v[124:125], v[0:1], v[124:125]
	global_store_dwordx4 v[16:17], v[124:127], off nt
	s_nop 1
	v_pk_mul_f32 v[124:125], v[58:59], v[128:129] op_sel_hi:[0,1]
	v_pk_mul_f32 v[126:127], v[58:59], v[130:131] op_sel_hi:[0,1]
	v_pk_mul_f32 v[126:127], v[6:7], v[126:127]
	v_pk_mul_f32 v[124:125], v[4:5], v[124:125]
	global_store_dwordx4 v[16:17], v[124:127], off offset:1024 nt
	s_nop 1
	v_lshlrev_b32_e32 v124, 16, v152
	v_and_b32_e32 v125, 0xffff0000, v152
	v_lshlrev_b32_e32 v126, 16, v153
	v_and_b32_e32 v127, 0xffff0000, v153
	v_pk_mul_f32 v[124:125], v[58:59], v[124:125] op_sel_hi:[0,1]
	v_pk_mul_f32 v[126:127], v[58:59], v[126:127] op_sel_hi:[0,1]
	v_pk_mul_f32 v[126:127], v[10:11], v[126:127]
	v_pk_mul_f32 v[124:125], v[8:9], v[124:125]
	global_store_dwordx4 v[16:17], v[124:127], off offset:2048 nt
	s_nop 1
	v_lshlrev_b32_e32 v124, 16, v154
	v_and_b32_e32 v125, 0xffff0000, v154
	v_lshlrev_b32_e32 v126, 16, v155
	v_and_b32_e32 v127, 0xffff0000, v155
	v_pk_mul_f32 v[124:125], v[58:59], v[124:125] op_sel_hi:[0,1]
	v_pk_mul_f32 v[126:127], v[58:59], v[126:127] op_sel_hi:[0,1]
	v_pk_mul_f32 v[126:127], v[14:15], v[126:127]
	v_pk_mul_f32 v[124:125], v[12:13], v[124:125]
	global_store_dwordx4 v[16:17], v[124:127], off offset:3072 nt
	v_lshl_add_u64 v[16:17], v[16:17], 0, s[8:9]
	s_cbranch_scc0 .Lp13_loop
